# Wo GEMM skips all-zero K-tiles; GEMM loops: drop redundant lgkmcnt waits and mid-block setprio toggles; end-of-MFMA-block barrier moved 4 MFMAs earlier with prio 2 tail
# speedup vs baseline: 1.0071x; 1.0071x over previous
.LBB0_252:
	s_add_u32 s22, s20, 0xfffc0080
	s_addc_u32 s23, s21, -1
	s_add_i32 s64, 0, 0x10000
	s_cmp_eq_u32 s68, 12
	s_cselect_b32 s25, s13, s23
	s_cselect_b32 s24, s19, s22
	s_cselect_b32 s23, s11, s63
	s_cselect_b32 s22, s61, s62
	s_add_i32 s69, 0, 0x14000
	v_add_u32_e32 v140, s64, v167
	v_add_u32_e32 v164, s69, v167
	ds_read_b128 v[48:51], v140
	ds_read_b128 v[56:59], v140 offset:1024
	ds_read_b128 v[136:139], v140 offset:2048
	ds_read_b128 v[140:143], v140 offset:3072
	ds_read_b128 v[156:159], v164
	ds_read_b128 v[160:163], v164 offset:1024
	ds_read_b128 v[182:185], v164 offset:2048
	ds_read_b128 v[186:189], v164 offset:3072
	v_lshl_add_u64 v[164:165], s[20:21], 0, v[154:155]
	s_add_i32 m0, s49, 0xc000
	ds_read_b128 v[190:193], v172
	ds_read_b128 v[194:197], v172 offset:1024
	ds_read_b128 v[198:201], v172 offset:2048
	ds_read_b128 v[202:205], v172 offset:3072
	ds_read_b128 v[206:209], v172 offset:4096
	ds_read_b128 v[210:213], v172 offset:5120
	ds_read_b128 v[228:231], v172 offset:6144
	ds_read_b128 v[232:235], v172 offset:7168
	global_load_lds_dwordx4 v[164:165], off
	v_lshl_add_u64 v[164:165], s[20:21], 0, v[152:153]
	s_add_i32 m0, s49, 0xe000
	s_nop 0
	global_load_lds_dwordx4 v[164:165], off
	s_waitcnt vmcnt(8)
	s_waitcnt lgkmcnt(0)
	s_barrier
	s_setprio 1
	v_mfma_f32_16x16x32_bf16 v[132:135], v[48:51], v[190:193], v[132:135]
	v_mfma_f32_16x16x32_bf16 v[124:127], v[136:139], v[190:193], v[124:127]
	v_mfma_f32_16x16x32_bf16 v[116:119], v[48:51], v[198:201], v[116:119]
	v_mfma_f32_16x16x32_bf16 v[112:115], v[136:139], v[198:201], v[112:115]
	v_mfma_f32_16x16x32_bf16 v[100:103], v[48:51], v[206:209], v[100:103]
	v_mfma_f32_16x16x32_bf16 v[96:99], v[136:139], v[206:209], v[96:99]
	v_mfma_f32_16x16x32_bf16 v[84:87], v[48:51], v[228:231], v[84:87]
	v_mfma_f32_16x16x32_bf16 v[80:83], v[136:139], v[228:231], v[80:83]
	v_mfma_f32_16x16x32_bf16 v[132:135], v[56:59], v[194:197], v[132:135]
	v_mfma_f32_16x16x32_bf16 v[124:127], v[140:143], v[194:197], v[124:127]
	v_mfma_f32_16x16x32_bf16 v[116:119], v[56:59], v[202:205], v[116:119]
	v_mfma_f32_16x16x32_bf16 v[112:115], v[140:143], v[202:205], v[112:115]
	v_mfma_f32_16x16x32_bf16 v[100:103], v[56:59], v[210:213], v[100:103]
	v_mfma_f32_16x16x32_bf16 v[96:99], v[140:143], v[210:213], v[96:99]
	v_mfma_f32_16x16x32_bf16 v[84:87], v[56:59], v[232:235], v[84:87]
	v_mfma_f32_16x16x32_bf16 v[80:83], v[140:143], v[232:235], v[80:83]
	v_mfma_f32_16x16x32_bf16 v[128:131], v[156:159], v[190:193], v[128:131]
	v_mfma_f32_16x16x32_bf16 v[120:123], v[182:185], v[190:193], v[120:123]
	v_mfma_f32_16x16x32_bf16 v[108:111], v[156:159], v[198:201], v[108:111]
	v_mfma_f32_16x16x32_bf16 v[104:107], v[182:185], v[198:201], v[104:107]
	v_mfma_f32_16x16x32_bf16 v[92:95], v[156:159], v[206:209], v[92:95]
	v_mfma_f32_16x16x32_bf16 v[88:91], v[182:185], v[206:209], v[88:91]
	v_mfma_f32_16x16x32_bf16 v[76:79], v[156:159], v[228:231], v[76:79]
	v_mfma_f32_16x16x32_bf16 v[72:75], v[182:185], v[228:231], v[72:75]
	v_mfma_f32_16x16x32_bf16 v[128:131], v[160:163], v[194:197], v[128:131]
	v_mfma_f32_16x16x32_bf16 v[120:123], v[186:189], v[194:197], v[120:123]
	v_mfma_f32_16x16x32_bf16 v[108:111], v[160:163], v[202:205], v[108:111]
	v_mfma_f32_16x16x32_bf16 v[104:107], v[186:189], v[202:205], v[104:107]
	s_setprio 2
	s_barrier
	v_mfma_f32_16x16x32_bf16 v[92:95], v[160:163], v[210:213], v[92:95]
	v_mfma_f32_16x16x32_bf16 v[88:91], v[186:189], v[210:213], v[88:91]
	v_mfma_f32_16x16x32_bf16 v[76:79], v[160:163], v[232:235], v[76:79]
	v_mfma_f32_16x16x32_bf16 v[72:75], v[186:189], v[232:235], v[72:75]
	s_setprio 0
	s_add_i32 s64, s64, s41
	v_lshl_add_u64 v[164:165], s[22:23], 0, v[148:149]
	s_mov_b32 m0, s64
	ds_read_b128 v[190:193], v172 offset:16384
	ds_read_b128 v[194:197], v172 offset:17408
	ds_read_b128 v[198:201], v172 offset:18432
	ds_read_b128 v[202:205], v172 offset:19456
	ds_read_b128 v[206:209], v172 offset:20480
	ds_read_b128 v[210:213], v172 offset:21504
	ds_read_b128 v[228:231], v172 offset:22528
	ds_read_b128 v[232:235], v172 offset:23552
	global_load_lds_dwordx4 v[164:165], off
	s_add_i32 m0, s64, 0x2000
	s_add_u32 s64, s22, 0x40000
	v_lshl_add_u64 v[220:221], s[22:23], 0, v[144:145]
	s_addc_u32 s65, s23, 0
	s_add_i32 s69, s69, s41
	global_load_lds_dwordx4 v[220:221], off
	v_lshl_add_u64 v[222:223], s[64:65], 0, v[148:149]
	s_mov_b32 m0, s69
	v_lshl_add_u64 v[226:227], s[24:25], 0, v[146:147]
	global_load_lds_dwordx4 v[222:223], off
	v_lshl_add_u64 v[222:223], s[64:65], 0, v[144:145]
	s_add_i32 m0, s69, 0x2000
	s_nop 0
	global_load_lds_dwordx4 v[222:223], off
	v_lshl_add_u64 v[222:223], s[24:25], 0, v[150:151]
	s_mov_b32 m0, s49
	s_nop 0
	global_load_lds_dwordx4 v[222:223], off
	s_mov_b32 m0, s50
	s_nop 0
	global_load_lds_dwordx4 v[226:227], off
	s_waitcnt vmcnt(8)
	s_waitcnt lgkmcnt(0)
	s_barrier
	s_setprio 1
	v_mfma_f32_16x16x32_bf16 v[68:71], v[48:51], v[190:193], v[68:71]
	v_mfma_f32_16x16x32_bf16 v[64:67], v[136:139], v[190:193], v[64:67]
	v_mfma_f32_16x16x32_bf16 v[44:47], v[48:51], v[198:201], v[44:47]
	v_mfma_f32_16x16x32_bf16 v[40:43], v[136:139], v[198:201], v[40:43]
	v_mfma_f32_16x16x32_bf16 v[28:31], v[48:51], v[206:209], v[28:31]
	v_mfma_f32_16x16x32_bf16 v[24:27], v[136:139], v[206:209], v[24:27]
	v_mfma_f32_16x16x32_bf16 v[12:15], v[48:51], v[228:231], v[12:15]
	v_mfma_f32_16x16x32_bf16 v[8:11], v[136:139], v[228:231], v[8:11]
	v_mfma_f32_16x16x32_bf16 v[68:71], v[56:59], v[194:197], v[68:71]
	v_mfma_f32_16x16x32_bf16 v[64:67], v[140:143], v[194:197], v[64:67]
	v_mfma_f32_16x16x32_bf16 v[44:47], v[56:59], v[202:205], v[44:47]
	v_mfma_f32_16x16x32_bf16 v[40:43], v[140:143], v[202:205], v[40:43]
	v_mfma_f32_16x16x32_bf16 v[28:31], v[56:59], v[210:213], v[28:31]
	v_mfma_f32_16x16x32_bf16 v[24:27], v[140:143], v[210:213], v[24:27]
	v_mfma_f32_16x16x32_bf16 v[12:15], v[56:59], v[232:235], v[12:15]
	v_mfma_f32_16x16x32_bf16 v[8:11], v[140:143], v[232:235], v[8:11]
	v_mfma_f32_16x16x32_bf16 v[52:55], v[182:185], v[190:193], v[52:55]
	v_mfma_f32_16x16x32_bf16 v[36:39], v[156:159], v[198:201], v[36:39]
	v_mfma_f32_16x16x32_bf16 v[32:35], v[182:185], v[198:201], v[32:35]
	v_mfma_f32_16x16x32_bf16 v[20:23], v[156:159], v[206:209], v[20:23]
	v_mfma_f32_16x16x32_bf16 v[16:19], v[182:185], v[206:209], v[16:19]
	v_mfma_f32_16x16x32_bf16 v[4:7], v[156:159], v[228:231], v[4:7]
	v_mfma_f32_16x16x32_bf16 v[0:3], v[182:185], v[228:231], v[0:3]
	v_mfma_f32_16x16x32_bf16 v[48:51], v[156:159], v[190:193], v[60:63]
	v_mfma_f32_16x16x32_bf16 v[52:55], v[186:189], v[194:197], v[52:55]
	v_mfma_f32_16x16x32_bf16 v[36:39], v[160:163], v[202:205], v[36:39]
	v_mfma_f32_16x16x32_bf16 v[32:35], v[186:189], v[202:205], v[32:35]
	v_mfma_f32_16x16x32_bf16 v[20:23], v[160:163], v[210:213], v[20:23]
	s_setprio 2
	s_barrier
	v_mfma_f32_16x16x32_bf16 v[16:19], v[186:189], v[210:213], v[16:19]
	v_mfma_f32_16x16x32_bf16 v[4:7], v[160:163], v[232:235], v[4:7]
	v_mfma_f32_16x16x32_bf16 v[0:3], v[186:189], v[232:235], v[0:3]
	v_mfma_f32_16x16x32_bf16 v[48:51], v[160:163], v[194:197], v[48:51]
	s_setprio 0
	s_add_i32 s64, 0, 0x18000
	s_add_i32 s65, 0, 0x1c000
	v_add_u32_e32 v140, s64, v167
	v_add_u32_e32 v173, s65, v167
	ds_read_b128 v[56:59], v140
	ds_read_b128 v[60:63], v140 offset:1024
	ds_read_b128 v[136:139], v140 offset:2048
	ds_read_b128 v[140:143], v140 offset:3072
	ds_read_b128 v[156:159], v173
	ds_read_b128 v[160:163], v173 offset:1024
	ds_read_b128 v[182:185], v173 offset:2048
	ds_read_b128 v[186:189], v173 offset:3072
	s_add_u32 s24, s24, 0x40000
	s_addc_u32 s25, s25, 0
	s_mov_b32 m0, s51
	v_lshl_add_u64 v[236:237], s[24:25], 0, v[150:151]
	ds_read_b128 v[190:193], v172 offset:32768
	ds_read_b128 v[194:197], v172 offset:33792
	ds_read_b128 v[198:201], v172 offset:34816
	ds_read_b128 v[202:205], v172 offset:35840
	ds_read_b128 v[206:209], v172 offset:36864
	ds_read_b128 v[210:213], v172 offset:37888
	ds_read_b128 v[228:231], v172 offset:38912
	ds_read_b128 v[232:235], v172 offset:39936
	global_load_lds_dwordx4 v[236:237], off
	v_lshl_add_u64 v[236:237], s[24:25], 0, v[146:147]
	s_mov_b32 m0, s52
	s_nop 0
	global_load_lds_dwordx4 v[236:237], off
	s_waitcnt vmcnt(8)
	s_waitcnt lgkmcnt(0)
	s_barrier
	s_setprio 1
	v_mfma_f32_16x16x32_bf16 v[132:135], v[56:59], v[190:193], v[132:135]
	v_mfma_f32_16x16x32_bf16 v[124:127], v[136:139], v[190:193], v[124:127]
	v_mfma_f32_16x16x32_bf16 v[116:119], v[56:59], v[198:201], v[116:119]
	v_mfma_f32_16x16x32_bf16 v[112:115], v[136:139], v[198:201], v[112:115]
	v_mfma_f32_16x16x32_bf16 v[100:103], v[56:59], v[206:209], v[100:103]
	v_mfma_f32_16x16x32_bf16 v[96:99], v[136:139], v[206:209], v[96:99]
	v_mfma_f32_16x16x32_bf16 v[84:87], v[56:59], v[228:231], v[84:87]
	v_mfma_f32_16x16x32_bf16 v[80:83], v[136:139], v[228:231], v[80:83]
	v_mfma_f32_16x16x32_bf16 v[132:135], v[60:63], v[194:197], v[132:135]
	v_mfma_f32_16x16x32_bf16 v[124:127], v[140:143], v[194:197], v[124:127]
	v_mfma_f32_16x16x32_bf16 v[116:119], v[60:63], v[202:205], v[116:119]
	v_mfma_f32_16x16x32_bf16 v[112:115], v[140:143], v[202:205], v[112:115]
	v_mfma_f32_16x16x32_bf16 v[100:103], v[60:63], v[210:213], v[100:103]
	v_mfma_f32_16x16x32_bf16 v[96:99], v[140:143], v[210:213], v[96:99]
	v_mfma_f32_16x16x32_bf16 v[84:87], v[60:63], v[232:235], v[84:87]
	v_mfma_f32_16x16x32_bf16 v[80:83], v[140:143], v[232:235], v[80:83]
	v_mfma_f32_16x16x32_bf16 v[128:131], v[156:159], v[190:193], v[128:131]
	v_mfma_f32_16x16x32_bf16 v[120:123], v[182:185], v[190:193], v[120:123]
	v_mfma_f32_16x16x32_bf16 v[108:111], v[156:159], v[198:201], v[108:111]
	v_mfma_f32_16x16x32_bf16 v[104:107], v[182:185], v[198:201], v[104:107]
	v_mfma_f32_16x16x32_bf16 v[92:95], v[156:159], v[206:209], v[92:95]
	v_mfma_f32_16x16x32_bf16 v[88:91], v[182:185], v[206:209], v[88:91]
	v_mfma_f32_16x16x32_bf16 v[76:79], v[156:159], v[228:231], v[76:79]
	v_mfma_f32_16x16x32_bf16 v[72:75], v[182:185], v[228:231], v[72:75]
	v_mfma_f32_16x16x32_bf16 v[128:131], v[160:163], v[194:197], v[128:131]
	v_mfma_f32_16x16x32_bf16 v[120:123], v[186:189], v[194:197], v[120:123]
	v_mfma_f32_16x16x32_bf16 v[108:111], v[160:163], v[202:205], v[108:111]
	v_mfma_f32_16x16x32_bf16 v[104:107], v[186:189], v[202:205], v[104:107]
	s_setprio 2
	s_barrier
	v_mfma_f32_16x16x32_bf16 v[92:95], v[160:163], v[210:213], v[92:95]
	v_mfma_f32_16x16x32_bf16 v[88:91], v[186:189], v[210:213], v[88:91]
	v_mfma_f32_16x16x32_bf16 v[76:79], v[160:163], v[232:235], v[76:79]
	v_mfma_f32_16x16x32_bf16 v[72:75], v[186:189], v[232:235], v[72:75]
	s_setprio 0
	s_add_i32 s24, s64, s41
	v_lshl_add_u64 v[164:165], v[164:165], 0, s[34:35]
	s_mov_b32 m0, s24
	ds_read_b128 v[190:193], v172 offset:49152
	ds_read_b128 v[194:197], v172 offset:50176
	ds_read_b128 v[198:201], v172 offset:51200
	ds_read_b128 v[202:205], v172 offset:52224
	ds_read_b128 v[206:209], v172 offset:53248
	ds_read_b128 v[210:213], v172 offset:54272
	ds_read_b128 v[228:231], v172 offset:55296
	ds_read_b128 v[232:235], v172 offset:56320
	global_load_lds_dwordx4 v[164:165], off
	s_add_i32 m0, s24, 0x2000
	s_add_u32 s22, s22, 0x40080
	v_lshl_add_u64 v[164:165], v[220:221], 0, s[34:35]
	s_addc_u32 s23, s23, 0
	s_add_i32 s24, s65, s41
	global_load_lds_dwordx4 v[164:165], off
	v_lshl_add_u64 v[164:165], s[22:23], 0, v[148:149]
	s_mov_b32 m0, s24
	s_nop 0
	global_load_lds_dwordx4 v[164:165], off
	v_lshl_add_u64 v[164:165], s[22:23], 0, v[144:145]
	s_add_i32 m0, s24, 0x2000
	s_nop 0
	global_load_lds_dwordx4 v[164:165], off
	v_lshl_add_u64 v[164:165], v[222:223], 0, s[34:35]
	s_mov_b32 m0, s55
	s_nop 0
	global_load_lds_dwordx4 v[164:165], off
	v_lshl_add_u64 v[164:165], v[226:227], 0, s[34:35]
	s_mov_b32 m0, s56
	s_nop 0
	global_load_lds_dwordx4 v[164:165], off
	s_waitcnt vmcnt(8)
	s_waitcnt lgkmcnt(0)
	s_barrier
	s_setprio 1
	v_mfma_f32_16x16x32_bf16 v[68:71], v[56:59], v[190:193], v[68:71]
	v_mfma_f32_16x16x32_bf16 v[64:67], v[136:139], v[190:193], v[64:67]
	v_mfma_f32_16x16x32_bf16 v[44:47], v[56:59], v[198:201], v[44:47]
	v_mfma_f32_16x16x32_bf16 v[40:43], v[136:139], v[198:201], v[40:43]
	v_mfma_f32_16x16x32_bf16 v[28:31], v[56:59], v[206:209], v[28:31]
	v_mfma_f32_16x16x32_bf16 v[24:27], v[136:139], v[206:209], v[24:27]
	v_mfma_f32_16x16x32_bf16 v[12:15], v[56:59], v[228:231], v[12:15]
	v_mfma_f32_16x16x32_bf16 v[8:11], v[136:139], v[228:231], v[8:11]
	v_mfma_f32_16x16x32_bf16 v[68:71], v[60:63], v[194:197], v[68:71]
	v_mfma_f32_16x16x32_bf16 v[64:67], v[140:143], v[194:197], v[64:67]
	v_mfma_f32_16x16x32_bf16 v[44:47], v[60:63], v[202:205], v[44:47]
	v_mfma_f32_16x16x32_bf16 v[40:43], v[140:143], v[202:205], v[40:43]
	v_mfma_f32_16x16x32_bf16 v[28:31], v[60:63], v[210:213], v[28:31]
	v_mfma_f32_16x16x32_bf16 v[24:27], v[140:143], v[210:213], v[24:27]
	v_mfma_f32_16x16x32_bf16 v[12:15], v[60:63], v[232:235], v[12:15]
	v_mfma_f32_16x16x32_bf16 v[8:11], v[140:143], v[232:235], v[8:11]
	v_mfma_f32_16x16x32_bf16 v[48:51], v[156:159], v[190:193], v[48:51]
	v_mfma_f32_16x16x32_bf16 v[60:63], v[160:163], v[194:197], v[48:51]
	v_mfma_f32_16x16x32_bf16 v[48:51], v[182:185], v[190:193], v[52:55]
	v_mfma_f32_16x16x32_bf16 v[36:39], v[156:159], v[198:201], v[36:39]
	v_mfma_f32_16x16x32_bf16 v[32:35], v[182:185], v[198:201], v[32:35]
	v_mfma_f32_16x16x32_bf16 v[20:23], v[156:159], v[206:209], v[20:23]
	v_mfma_f32_16x16x32_bf16 v[16:19], v[182:185], v[206:209], v[16:19]
	v_mfma_f32_16x16x32_bf16 v[4:7], v[156:159], v[228:231], v[4:7]
	v_mfma_f32_16x16x32_bf16 v[0:3], v[182:185], v[228:231], v[0:3]
	v_mfma_f32_16x16x32_bf16 v[52:55], v[186:189], v[194:197], v[48:51]
	v_mfma_f32_16x16x32_bf16 v[36:39], v[160:163], v[202:205], v[36:39]
	v_mfma_f32_16x16x32_bf16 v[32:35], v[186:189], v[202:205], v[32:35]
	s_setprio 2
	s_barrier
	v_mfma_f32_16x16x32_bf16 v[20:23], v[160:163], v[210:213], v[20:23]
	v_mfma_f32_16x16x32_bf16 v[16:19], v[186:189], v[210:213], v[16:19]
	v_mfma_f32_16x16x32_bf16 v[4:7], v[160:163], v[232:235], v[4:7]
	v_mfma_f32_16x16x32_bf16 v[0:3], v[186:189], v[232:235], v[0:3]
	s_setprio 0
	s_add_i32 s68, s68, 2
	s_add_u32 s62, s62, 0x100
	s_addc_u32 s63, s63, 0
	s_add_u32 s20, s20, 0x100
	s_addc_u32 s21, s21, 0
	s_cmp_gt_u32 s68, 13
	s_cbranch_scc0 .LBB0_252
	s_and_b64 vcc, exec, s[8:9]
	s_cbranch_vccz .LBB0_255
	s_barrier

.LBB0_319:
	s_add_u32 s24, s22, 0xfffc0080
	s_addc_u32 s25, s23, -1
	s_add_i32 s64, 0, 0x10000
	s_cmp_eq_u32 s63, 12
	s_cselect_b32 s27, s9, s25
	s_cselect_b32 s26, s15, s24
	s_cselect_b32 s25, s13, s62
	s_cselect_b32 s24, s21, s44
	s_add_i32 s68, 0, 0x14000
	v_add_u32_e32 v112, s64, v159
	v_add_u32_e32 v165, s68, v159
	ds_read_b128 v[96:99], v112
	ds_read_b128 v[100:103], v112 offset:1024
	ds_read_b128 v[108:111], v112 offset:2048
	ds_read_b128 v[112:115], v112 offset:3072
	ds_read_b128 v[154:157], v165
	ds_read_b128 v[166:169], v165 offset:1024
	ds_read_b128 v[170:173], v165 offset:2048
	ds_read_b128 v[182:185], v165 offset:3072
	v_lshl_add_u64 v[220:221], s[22:23], 0, v[152:153]
	s_add_i32 m0, s50, 0xc000
	ds_read_b128 v[186:189], v164
	ds_read_b128 v[190:193], v164 offset:1024
	ds_read_b128 v[194:197], v164 offset:2048
	ds_read_b128 v[198:201], v164 offset:3072
	ds_read_b128 v[202:205], v164 offset:4096
	ds_read_b128 v[206:209], v164 offset:5120
	ds_read_b128 v[210:213], v164 offset:6144
	ds_read_b128 v[228:231], v164 offset:7168
	global_load_lds_dwordx4 v[220:221], off
	v_lshl_add_u64 v[220:221], s[22:23], 0, v[150:151]
	s_add_i32 m0, s50, 0xe000
	s_nop 0
	global_load_lds_dwordx4 v[220:221], off
	s_waitcnt vmcnt(8)
	s_waitcnt lgkmcnt(0)
	s_barrier
	s_setprio 1
	v_mfma_f32_16x16x32_bf16 v[140:143], v[96:99], v[186:189], v[140:143]
	v_mfma_f32_16x16x32_bf16 v[136:139], v[108:111], v[186:189], v[136:139]
	v_mfma_f32_16x16x32_bf16 v[124:127], v[96:99], v[194:197], v[124:127]
	v_mfma_f32_16x16x32_bf16 v[120:123], v[108:111], v[194:197], v[120:123]
	v_mfma_f32_16x16x32_bf16 v[92:95], v[96:99], v[202:205], v[92:95]
	v_mfma_f32_16x16x32_bf16 v[88:91], v[108:111], v[202:205], v[88:91]
	v_mfma_f32_16x16x32_bf16 v[76:79], v[96:99], v[210:213], v[76:79]
	v_mfma_f32_16x16x32_bf16 v[72:75], v[108:111], v[210:213], v[72:75]
	v_mfma_f32_16x16x32_bf16 v[140:143], v[100:103], v[190:193], v[140:143]
	v_mfma_f32_16x16x32_bf16 v[136:139], v[112:115], v[190:193], v[136:139]
	v_mfma_f32_16x16x32_bf16 v[124:127], v[100:103], v[198:201], v[124:127]
	v_mfma_f32_16x16x32_bf16 v[120:123], v[112:115], v[198:201], v[120:123]
	v_mfma_f32_16x16x32_bf16 v[92:95], v[100:103], v[206:209], v[92:95]
	v_mfma_f32_16x16x32_bf16 v[88:91], v[112:115], v[206:209], v[88:91]
	v_mfma_f32_16x16x32_bf16 v[76:79], v[100:103], v[228:231], v[76:79]
	v_mfma_f32_16x16x32_bf16 v[72:75], v[112:115], v[228:231], v[72:75]
	v_mfma_f32_16x16x32_bf16 v[132:135], v[154:157], v[186:189], v[132:135]
	v_mfma_f32_16x16x32_bf16 v[128:131], v[170:173], v[186:189], v[128:131]
	v_mfma_f32_16x16x32_bf16 v[116:119], v[154:157], v[194:197], v[116:119]
	v_mfma_f32_16x16x32_bf16 v[104:107], v[170:173], v[194:197], v[104:107]
	v_mfma_f32_16x16x32_bf16 v[84:87], v[154:157], v[202:205], v[84:87]
	v_mfma_f32_16x16x32_bf16 v[80:83], v[170:173], v[202:205], v[80:83]
	v_mfma_f32_16x16x32_bf16 v[68:71], v[154:157], v[210:213], v[68:71]
	v_mfma_f32_16x16x32_bf16 v[64:67], v[170:173], v[210:213], v[64:67]
	v_mfma_f32_16x16x32_bf16 v[132:135], v[166:169], v[190:193], v[132:135]
	v_mfma_f32_16x16x32_bf16 v[128:131], v[182:185], v[190:193], v[128:131]
	v_mfma_f32_16x16x32_bf16 v[116:119], v[166:169], v[198:201], v[116:119]
	v_mfma_f32_16x16x32_bf16 v[104:107], v[182:185], v[198:201], v[104:107]
	s_setprio 2
	s_barrier
	v_mfma_f32_16x16x32_bf16 v[84:87], v[166:169], v[206:209], v[84:87]
	v_mfma_f32_16x16x32_bf16 v[80:83], v[182:185], v[206:209], v[80:83]
	v_mfma_f32_16x16x32_bf16 v[68:71], v[166:169], v[228:231], v[68:71]
	v_mfma_f32_16x16x32_bf16 v[64:67], v[182:185], v[228:231], v[64:67]
	s_setprio 0
	s_add_i32 s64, s64, s43
	v_lshl_add_u64 v[220:221], s[24:25], 0, v[176:177]
	s_mov_b32 m0, s64
	ds_read_b128 v[186:189], v164 offset:16384
	ds_read_b128 v[190:193], v164 offset:17408
	ds_read_b128 v[194:197], v164 offset:18432
	ds_read_b128 v[198:201], v164 offset:19456
	ds_read_b128 v[202:205], v164 offset:20480
	ds_read_b128 v[206:209], v164 offset:21504
	ds_read_b128 v[210:213], v164 offset:22528
	ds_read_b128 v[228:231], v164 offset:23552
	global_load_lds_dwordx4 v[220:221], off
	s_add_i32 m0, s64, 0x2000
	s_add_u32 s64, s24, 0x40000
	v_lshl_add_u64 v[222:223], s[24:25], 0, v[148:149]
	s_addc_u32 s65, s25, 0
	s_add_i32 s68, s68, s43
	global_load_lds_dwordx4 v[222:223], off
	v_lshl_add_u64 v[226:227], s[64:65], 0, v[176:177]
	s_mov_b32 m0, s68
	v_lshl_add_u64 v[232:233], s[26:27], 0, v[146:147]
	global_load_lds_dwordx4 v[226:227], off
	v_lshl_add_u64 v[226:227], s[64:65], 0, v[148:149]
	s_add_i32 m0, s68, 0x2000
	s_nop 0
	global_load_lds_dwordx4 v[226:227], off
	v_lshl_add_u64 v[226:227], s[26:27], 0, v[144:145]
	s_mov_b32 m0, s50
	s_nop 0
	global_load_lds_dwordx4 v[226:227], off
	s_mov_b32 m0, s51
	s_nop 0
	global_load_lds_dwordx4 v[232:233], off
	s_waitcnt vmcnt(8)
	s_waitcnt lgkmcnt(0)
	s_barrier
	s_setprio 1
	v_mfma_f32_16x16x32_bf16 v[60:63], v[96:99], v[186:189], v[60:63]
	v_mfma_f32_16x16x32_bf16 v[56:59], v[108:111], v[186:189], v[56:59]
	v_mfma_f32_16x16x32_bf16 v[44:47], v[96:99], v[194:197], v[44:47]
	v_mfma_f32_16x16x32_bf16 v[40:43], v[108:111], v[194:197], v[40:43]
	v_mfma_f32_16x16x32_bf16 v[28:31], v[96:99], v[202:205], v[28:31]
	v_mfma_f32_16x16x32_bf16 v[24:27], v[108:111], v[202:205], v[24:27]
	v_mfma_f32_16x16x32_bf16 v[12:15], v[96:99], v[210:213], v[12:15]
	v_mfma_f32_16x16x32_bf16 v[8:11], v[108:111], v[210:213], v[8:11]
	v_mfma_f32_16x16x32_bf16 v[60:63], v[100:103], v[190:193], v[60:63]
	v_mfma_f32_16x16x32_bf16 v[56:59], v[112:115], v[190:193], v[56:59]
	v_mfma_f32_16x16x32_bf16 v[44:47], v[100:103], v[198:201], v[44:47]
	v_mfma_f32_16x16x32_bf16 v[40:43], v[112:115], v[198:201], v[40:43]
	v_mfma_f32_16x16x32_bf16 v[28:31], v[100:103], v[206:209], v[28:31]
	v_mfma_f32_16x16x32_bf16 v[24:27], v[112:115], v[206:209], v[24:27]
	v_mfma_f32_16x16x32_bf16 v[12:15], v[100:103], v[228:231], v[12:15]
	v_mfma_f32_16x16x32_bf16 v[8:11], v[112:115], v[228:231], v[8:11]
	v_mfma_f32_16x16x32_bf16 v[52:55], v[154:157], v[186:189], v[52:55]
	v_mfma_f32_16x16x32_bf16 v[48:51], v[170:173], v[186:189], v[48:51]
	v_mfma_f32_16x16x32_bf16 v[36:39], v[154:157], v[194:197], v[36:39]
	v_mfma_f32_16x16x32_bf16 v[32:35], v[170:173], v[194:197], v[32:35]
	v_mfma_f32_16x16x32_bf16 v[20:23], v[154:157], v[202:205], v[20:23]
	v_mfma_f32_16x16x32_bf16 v[16:19], v[170:173], v[202:205], v[16:19]
	v_mfma_f32_16x16x32_bf16 v[4:7], v[154:157], v[210:213], v[4:7]
	v_mfma_f32_16x16x32_bf16 v[0:3], v[170:173], v[210:213], v[0:3]
	v_mfma_f32_16x16x32_bf16 v[52:55], v[166:169], v[190:193], v[52:55]
	v_mfma_f32_16x16x32_bf16 v[48:51], v[182:185], v[190:193], v[48:51]
	v_mfma_f32_16x16x32_bf16 v[36:39], v[166:169], v[198:201], v[36:39]
	v_mfma_f32_16x16x32_bf16 v[32:35], v[182:185], v[198:201], v[32:35]
	s_setprio 2
	s_barrier
	v_mfma_f32_16x16x32_bf16 v[20:23], v[166:169], v[206:209], v[20:23]
	v_mfma_f32_16x16x32_bf16 v[16:19], v[182:185], v[206:209], v[16:19]
	v_mfma_f32_16x16x32_bf16 v[4:7], v[166:169], v[228:231], v[4:7]
	v_mfma_f32_16x16x32_bf16 v[0:3], v[182:185], v[228:231], v[0:3]
	s_setprio 0
	s_add_i32 s64, 0, 0x18000
	s_add_i32 s65, 0, 0x1c000
	v_add_u32_e32 v112, s64, v159
	v_add_u32_e32 v165, s65, v159
	ds_read_b128 v[96:99], v112
	ds_read_b128 v[100:103], v112 offset:1024
	ds_read_b128 v[108:111], v112 offset:2048
	ds_read_b128 v[112:115], v112 offset:3072
	ds_read_b128 v[154:157], v165
	ds_read_b128 v[166:169], v165 offset:1024
	ds_read_b128 v[170:173], v165 offset:2048
	ds_read_b128 v[182:185], v165 offset:3072
	s_add_u32 s26, s26, 0x40000
	s_addc_u32 s27, s27, 0
	s_mov_b32 m0, s52
	v_lshl_add_u64 v[234:235], s[26:27], 0, v[144:145]
	ds_read_b128 v[186:189], v164 offset:32768
	ds_read_b128 v[190:193], v164 offset:33792
	ds_read_b128 v[194:197], v164 offset:34816
	ds_read_b128 v[198:201], v164 offset:35840
	ds_read_b128 v[202:205], v164 offset:36864
	ds_read_b128 v[206:209], v164 offset:37888
	ds_read_b128 v[210:213], v164 offset:38912
	ds_read_b128 v[228:231], v164 offset:39936
	global_load_lds_dwordx4 v[234:235], off
	v_lshl_add_u64 v[234:235], s[26:27], 0, v[146:147]
	s_mov_b32 m0, s53
	s_nop 0
	global_load_lds_dwordx4 v[234:235], off
	s_waitcnt vmcnt(8)
	s_waitcnt lgkmcnt(0)
	s_barrier
	s_setprio 1
	v_mfma_f32_16x16x32_bf16 v[140:143], v[96:99], v[186:189], v[140:143]
	v_mfma_f32_16x16x32_bf16 v[136:139], v[108:111], v[186:189], v[136:139]
	v_mfma_f32_16x16x32_bf16 v[124:127], v[96:99], v[194:197], v[124:127]
	v_mfma_f32_16x16x32_bf16 v[120:123], v[108:111], v[194:197], v[120:123]
	v_mfma_f32_16x16x32_bf16 v[92:95], v[96:99], v[202:205], v[92:95]
	v_mfma_f32_16x16x32_bf16 v[88:91], v[108:111], v[202:205], v[88:91]
	v_mfma_f32_16x16x32_bf16 v[76:79], v[96:99], v[210:213], v[76:79]
	v_mfma_f32_16x16x32_bf16 v[72:75], v[108:111], v[210:213], v[72:75]
	v_mfma_f32_16x16x32_bf16 v[140:143], v[100:103], v[190:193], v[140:143]
	v_mfma_f32_16x16x32_bf16 v[136:139], v[112:115], v[190:193], v[136:139]
	v_mfma_f32_16x16x32_bf16 v[124:127], v[100:103], v[198:201], v[124:127]
	v_mfma_f32_16x16x32_bf16 v[120:123], v[112:115], v[198:201], v[120:123]
	v_mfma_f32_16x16x32_bf16 v[92:95], v[100:103], v[206:209], v[92:95]
	v_mfma_f32_16x16x32_bf16 v[88:91], v[112:115], v[206:209], v[88:91]
	v_mfma_f32_16x16x32_bf16 v[76:79], v[100:103], v[228:231], v[76:79]
	v_mfma_f32_16x16x32_bf16 v[72:75], v[112:115], v[228:231], v[72:75]
	v_mfma_f32_16x16x32_bf16 v[132:135], v[154:157], v[186:189], v[132:135]
	v_mfma_f32_16x16x32_bf16 v[128:131], v[170:173], v[186:189], v[128:131]
	v_mfma_f32_16x16x32_bf16 v[116:119], v[154:157], v[194:197], v[116:119]
	v_mfma_f32_16x16x32_bf16 v[104:107], v[170:173], v[194:197], v[104:107]
	v_mfma_f32_16x16x32_bf16 v[84:87], v[154:157], v[202:205], v[84:87]
	v_mfma_f32_16x16x32_bf16 v[80:83], v[170:173], v[202:205], v[80:83]
	v_mfma_f32_16x16x32_bf16 v[68:71], v[154:157], v[210:213], v[68:71]
	v_mfma_f32_16x16x32_bf16 v[64:67], v[170:173], v[210:213], v[64:67]
	v_mfma_f32_16x16x32_bf16 v[132:135], v[166:169], v[190:193], v[132:135]
	v_mfma_f32_16x16x32_bf16 v[128:131], v[182:185], v[190:193], v[128:131]
	v_mfma_f32_16x16x32_bf16 v[116:119], v[166:169], v[198:201], v[116:119]
	v_mfma_f32_16x16x32_bf16 v[104:107], v[182:185], v[198:201], v[104:107]
	s_setprio 2
	s_barrier
	v_mfma_f32_16x16x32_bf16 v[84:87], v[166:169], v[206:209], v[84:87]
	v_mfma_f32_16x16x32_bf16 v[80:83], v[182:185], v[206:209], v[80:83]
	v_mfma_f32_16x16x32_bf16 v[68:71], v[166:169], v[228:231], v[68:71]
	v_mfma_f32_16x16x32_bf16 v[64:67], v[182:185], v[228:231], v[64:67]
	s_setprio 0
	s_add_i32 s26, s64, s43
	v_lshl_add_u64 v[220:221], v[220:221], 0, s[34:35]
	s_mov_b32 m0, s26
	ds_read_b128 v[186:189], v164 offset:49152
	ds_read_b128 v[190:193], v164 offset:50176
	ds_read_b128 v[194:197], v164 offset:51200
	ds_read_b128 v[198:201], v164 offset:52224
	ds_read_b128 v[202:205], v164 offset:53248
	ds_read_b128 v[206:209], v164 offset:54272
	ds_read_b128 v[210:213], v164 offset:55296
	ds_read_b128 v[228:231], v164 offset:56320
	global_load_lds_dwordx4 v[220:221], off
	s_add_i32 m0, s26, 0x2000
	s_add_u32 s24, s24, 0x40080
	v_lshl_add_u64 v[220:221], v[222:223], 0, s[34:35]
	s_addc_u32 s25, s25, 0
	s_add_i32 s26, s65, s43
	global_load_lds_dwordx4 v[220:221], off
	v_lshl_add_u64 v[220:221], s[24:25], 0, v[176:177]
	s_mov_b32 m0, s26
	s_nop 0
	global_load_lds_dwordx4 v[220:221], off
	v_lshl_add_u64 v[220:221], s[24:25], 0, v[148:149]
	s_add_i32 m0, s26, 0x2000
	s_nop 0
	global_load_lds_dwordx4 v[220:221], off
	v_lshl_add_u64 v[220:221], v[226:227], 0, s[34:35]
	s_mov_b32 m0, s57
	s_nop 0
	global_load_lds_dwordx4 v[220:221], off
	v_lshl_add_u64 v[220:221], v[232:233], 0, s[34:35]
	s_mov_b32 m0, s58
	s_nop 0
	global_load_lds_dwordx4 v[220:221], off
	s_waitcnt vmcnt(8)
	s_waitcnt lgkmcnt(0)
	s_barrier
	s_setprio 1
	v_mfma_f32_16x16x32_bf16 v[60:63], v[96:99], v[186:189], v[60:63]
	v_mfma_f32_16x16x32_bf16 v[56:59], v[108:111], v[186:189], v[56:59]
	v_mfma_f32_16x16x32_bf16 v[44:47], v[96:99], v[194:197], v[44:47]
	v_mfma_f32_16x16x32_bf16 v[40:43], v[108:111], v[194:197], v[40:43]
	v_mfma_f32_16x16x32_bf16 v[28:31], v[96:99], v[202:205], v[28:31]
	v_mfma_f32_16x16x32_bf16 v[24:27], v[108:111], v[202:205], v[24:27]
	v_mfma_f32_16x16x32_bf16 v[12:15], v[96:99], v[210:213], v[12:15]
	v_mfma_f32_16x16x32_bf16 v[8:11], v[108:111], v[210:213], v[8:11]
	v_mfma_f32_16x16x32_bf16 v[60:63], v[100:103], v[190:193], v[60:63]
	v_mfma_f32_16x16x32_bf16 v[56:59], v[112:115], v[190:193], v[56:59]
	v_mfma_f32_16x16x32_bf16 v[44:47], v[100:103], v[198:201], v[44:47]
	v_mfma_f32_16x16x32_bf16 v[40:43], v[112:115], v[198:201], v[40:43]
	v_mfma_f32_16x16x32_bf16 v[28:31], v[100:103], v[206:209], v[28:31]
	v_mfma_f32_16x16x32_bf16 v[24:27], v[112:115], v[206:209], v[24:27]
	v_mfma_f32_16x16x32_bf16 v[12:15], v[100:103], v[228:231], v[12:15]
	v_mfma_f32_16x16x32_bf16 v[8:11], v[112:115], v[228:231], v[8:11]
	v_mfma_f32_16x16x32_bf16 v[52:55], v[154:157], v[186:189], v[52:55]
	v_mfma_f32_16x16x32_bf16 v[48:51], v[170:173], v[186:189], v[48:51]
	v_mfma_f32_16x16x32_bf16 v[36:39], v[154:157], v[194:197], v[36:39]
	v_mfma_f32_16x16x32_bf16 v[32:35], v[170:173], v[194:197], v[32:35]
	v_mfma_f32_16x16x32_bf16 v[20:23], v[154:157], v[202:205], v[20:23]
	v_mfma_f32_16x16x32_bf16 v[16:19], v[170:173], v[202:205], v[16:19]
	v_mfma_f32_16x16x32_bf16 v[4:7], v[154:157], v[210:213], v[4:7]
	v_mfma_f32_16x16x32_bf16 v[0:3], v[170:173], v[210:213], v[0:3]
	v_mfma_f32_16x16x32_bf16 v[52:55], v[166:169], v[190:193], v[52:55]
	v_mfma_f32_16x16x32_bf16 v[48:51], v[182:185], v[190:193], v[48:51]
	v_mfma_f32_16x16x32_bf16 v[36:39], v[166:169], v[198:201], v[36:39]
	v_mfma_f32_16x16x32_bf16 v[32:35], v[182:185], v[198:201], v[32:35]
	s_setprio 2
	s_barrier
	v_mfma_f32_16x16x32_bf16 v[20:23], v[166:169], v[206:209], v[20:23]
	v_mfma_f32_16x16x32_bf16 v[16:19], v[182:185], v[206:209], v[16:19]
	v_mfma_f32_16x16x32_bf16 v[4:7], v[166:169], v[228:231], v[4:7]
	v_mfma_f32_16x16x32_bf16 v[0:3], v[182:185], v[228:231], v[0:3]
	s_setprio 0
	s_add_i32 s63, s63, 2
	s_add_u32 s44, s44, 0x100
	s_addc_u32 s62, s62, 0
	s_add_u32 s22, s22, 0x100
	s_addc_u32 s23, s23, 0
	s_cmp_gt_u32 s63, 13
	s_cbranch_scc0 .LBB0_319
	s_and_b64 vcc, exec, s[10:11]
	s_cbranch_vccz .LBB0_322
	s_barrier

.LBB0_412:
	s_ashr_i32 s11, s10, 31
	s_lshl_b64 s[12:13], s[10:11], 18
	s_add_u32 s12, s48, s12
	s_addc_u32 s13, s49, s13
	s_and_b64 s[14:15], s[2:3], exec
	s_cselect_b32 s27, s13, s21
	s_cselect_b32 s26, s12, s20
	s_ashr_i32 s9, s8, 31
	s_lshl_b64 s[14:15], s[8:9], 17
	s_add_u32 s14, s38, s14
	s_addc_u32 s15, s39, s15
	s_and_b64 s[24:25], s[2:3], exec
	s_cselect_b32 s25, s15, s23
	s_cselect_b32 s24, s14, s22
	s_add_i32 s11, 0, 0x10000
	s_add_i32 s17, 0, 0x14000
	v_add_u32_e32 v175, s11, v141
	v_add_u32_e32 v178, s17, v141
	ds_read_b128 v[0:3], v175
	ds_read_b128 v[4:7], v175 offset:1024
	ds_read_b128 v[8:11], v175 offset:2048
	ds_read_b128 v[12:15], v175 offset:3072
	ds_read_b128 v[16:19], v178
	ds_read_b128 v[20:23], v178 offset:1024
	ds_read_b128 v[24:27], v178 offset:2048
	ds_read_b128 v[28:31], v178 offset:3072
	s_add_u32 s58, s20, 0x20080
	s_addc_u32 s59, s21, 0
	s_add_i32 s62, s19, 0xc000
	v_lshl_add_u64 v[64:65], s[58:59], 0, v[132:133]
	s_mov_b32 m0, s62
	s_add_i32 s9, s19, 0xe000
	ds_read_b128 v[32:35], v143
	ds_read_b128 v[36:39], v143 offset:1024
	ds_read_b128 v[40:43], v143 offset:2048
	ds_read_b128 v[44:47], v143 offset:3072
	ds_read_b128 v[48:51], v143 offset:4096
	ds_read_b128 v[52:55], v143 offset:5120
	ds_read_b128 v[56:59], v143 offset:6144
	ds_read_b128 v[60:63], v143 offset:7168
	global_load_lds_dwordx4 v[64:65], off
	v_lshl_add_u64 v[64:65], s[58:59], 0, v[130:131]
	s_mov_b32 m0, s9
	s_nop 0
	global_load_lds_dwordx4 v[64:65], off
	s_waitcnt vmcnt(8)
	s_waitcnt lgkmcnt(0)
	s_barrier
	s_setprio 1
	v_mfma_f32_16x16x32_bf16 v[64:67], v[0:3], v[32:35], 0
	v_mfma_f32_16x16x32_bf16 v[68:71], v[8:11], v[32:35], 0
	v_mfma_f32_16x16x32_bf16 v[72:75], v[0:3], v[40:43], 0
	v_mfma_f32_16x16x32_bf16 v[76:79], v[8:11], v[40:43], 0
	v_mfma_f32_16x16x32_bf16 v[80:83], v[0:3], v[48:51], 0
	v_mfma_f32_16x16x32_bf16 v[84:87], v[8:11], v[48:51], 0
	v_mfma_f32_16x16x32_bf16 v[88:91], v[0:3], v[56:59], 0
	v_mfma_f32_16x16x32_bf16 v[92:95], v[8:11], v[56:59], 0
	v_mfma_f32_16x16x32_bf16 v[64:67], v[4:7], v[36:39], v[64:67]
	v_mfma_f32_16x16x32_bf16 v[68:71], v[12:15], v[36:39], v[68:71]
	v_mfma_f32_16x16x32_bf16 v[72:75], v[4:7], v[44:47], v[72:75]
	v_mfma_f32_16x16x32_bf16 v[76:79], v[12:15], v[44:47], v[76:79]
	v_mfma_f32_16x16x32_bf16 v[80:83], v[4:7], v[52:55], v[80:83]
	v_mfma_f32_16x16x32_bf16 v[84:87], v[12:15], v[52:55], v[84:87]
	v_mfma_f32_16x16x32_bf16 v[88:91], v[4:7], v[60:63], v[88:91]
	v_mfma_f32_16x16x32_bf16 v[92:95], v[12:15], v[60:63], v[92:95]
	v_mfma_f32_16x16x32_bf16 v[96:99], v[16:19], v[32:35], 0
	v_mfma_f32_16x16x32_bf16 v[32:35], v[24:27], v[32:35], 0
	v_mfma_f32_16x16x32_bf16 v[96:99], v[20:23], v[36:39], v[96:99]
	v_mfma_f32_16x16x32_bf16 v[32:35], v[28:31], v[36:39], v[32:35]
	v_mfma_f32_16x16x32_bf16 v[36:39], v[16:19], v[40:43], 0
	v_mfma_f32_16x16x32_bf16 v[40:43], v[24:27], v[40:43], 0
	v_mfma_f32_16x16x32_bf16 v[36:39], v[20:23], v[44:47], v[36:39]
	v_mfma_f32_16x16x32_bf16 v[40:43], v[28:31], v[44:47], v[40:43]
	v_mfma_f32_16x16x32_bf16 v[44:47], v[16:19], v[48:51], 0
	v_mfma_f32_16x16x32_bf16 v[48:51], v[24:27], v[48:51], 0
	v_mfma_f32_16x16x32_bf16 v[44:47], v[20:23], v[52:55], v[44:47]
	v_mfma_f32_16x16x32_bf16 v[48:51], v[28:31], v[52:55], v[48:51]
	s_setprio 2
	s_barrier
	v_mfma_f32_16x16x32_bf16 v[52:55], v[16:19], v[56:59], 0
	v_mfma_f32_16x16x32_bf16 v[56:59], v[24:27], v[56:59], 0
	v_mfma_f32_16x16x32_bf16 v[52:55], v[20:23], v[60:63], v[52:55]
	v_mfma_f32_16x16x32_bf16 v[56:59], v[28:31], v[60:63], v[56:59]
	s_setprio 0
	s_add_i32 s58, s11, s43
	v_lshl_add_u64 v[138:139], s[22:23], 0, v[176:177]
	s_mov_b64 s[68:69], 0x100
	s_add_i32 s11, s58, 0x2000
	v_lshl_add_u64 v[134:135], v[138:139], 0, s[68:69]
	s_mov_b32 m0, s58
	v_lshl_add_u64 v[172:173], s[22:23], 0, v[128:129]
	s_add_u32 s64, s22, 0x10100
	ds_read_b128 v[60:63], v143 offset:16384
	ds_read_b128 v[100:103], v143 offset:17408
	ds_read_b128 v[104:107], v143 offset:18432
	ds_read_b128 v[108:111], v143 offset:19456
	ds_read_b128 v[112:115], v143 offset:20480
	ds_read_b128 v[116:119], v143 offset:21504
	ds_read_b128 v[120:123], v143 offset:22528
	ds_read_b128 v[124:127], v143 offset:23552
	global_load_lds_dwordx4 v[134:135], off
	v_lshl_add_u64 v[134:135], v[172:173], 0, s[68:69]
	s_mov_b32 m0, s11
	s_addc_u32 s65, s23, 0
	s_add_i32 s17, s17, s43
	global_load_lds_dwordx4 v[134:135], off
	v_lshl_add_u64 v[134:135], s[64:65], 0, v[176:177]
	s_mov_b32 m0, s17
	s_add_i32 s57, s17, 0x2000
	global_load_lds_dwordx4 v[134:135], off
	v_lshl_add_u64 v[134:135], s[64:65], 0, v[128:129]
	s_mov_b32 m0, s57
	v_lshl_add_u64 v[220:221], s[20:21], 0, v[132:133]
	global_load_lds_dwordx4 v[134:135], off
	v_lshl_add_u64 v[134:135], v[220:221], 0, s[68:69]
	s_mov_b32 m0, s19
	v_lshl_add_u64 v[222:223], s[20:21], 0, v[130:131]
	global_load_lds_dwordx4 v[134:135], off
	v_lshl_add_u64 v[134:135], v[222:223], 0, s[68:69]
	s_mov_b32 m0, s51
	s_nop 0
	global_load_lds_dwordx4 v[134:135], off
	s_waitcnt vmcnt(8)
	s_waitcnt lgkmcnt(0)
	s_barrier
	s_setprio 1
	v_mfma_f32_16x16x32_bf16 v[134:137], v[0:3], v[60:63], 0
	v_mfma_f32_16x16x32_bf16 v[148:151], v[0:3], v[104:107], 0
	v_mfma_f32_16x16x32_bf16 v[156:159], v[0:3], v[112:115], 0
	v_mfma_f32_16x16x32_bf16 v[0:3], v[0:3], v[120:123], 0
	v_mfma_f32_16x16x32_bf16 v[134:137], v[4:7], v[100:103], v[134:137]
	v_mfma_f32_16x16x32_bf16 v[148:151], v[4:7], v[108:111], v[148:151]
	v_mfma_f32_16x16x32_bf16 v[156:159], v[4:7], v[116:119], v[156:159]
	v_mfma_f32_16x16x32_bf16 v[0:3], v[4:7], v[124:127], v[0:3]
	v_mfma_f32_16x16x32_bf16 v[4:7], v[8:11], v[120:123], 0
	v_mfma_f32_16x16x32_bf16 v[144:147], v[8:11], v[60:63], 0
	v_mfma_f32_16x16x32_bf16 v[152:155], v[8:11], v[104:107], 0
	v_mfma_f32_16x16x32_bf16 v[160:163], v[8:11], v[112:115], 0
	v_mfma_f32_16x16x32_bf16 v[4:7], v[12:15], v[124:127], v[4:7]
	v_mfma_f32_16x16x32_bf16 v[144:147], v[12:15], v[100:103], v[144:147]
	v_mfma_f32_16x16x32_bf16 v[152:155], v[12:15], v[108:111], v[152:155]
	v_mfma_f32_16x16x32_bf16 v[160:163], v[12:15], v[116:119], v[160:163]
	v_mfma_f32_16x16x32_bf16 v[8:11], v[16:19], v[60:63], 0
	v_mfma_f32_16x16x32_bf16 v[12:15], v[24:27], v[60:63], 0
	v_mfma_f32_16x16x32_bf16 v[8:11], v[20:23], v[100:103], v[8:11]
	v_mfma_f32_16x16x32_bf16 v[12:15], v[28:31], v[100:103], v[12:15]
	v_mfma_f32_16x16x32_bf16 v[60:63], v[16:19], v[104:107], 0
	v_mfma_f32_16x16x32_bf16 v[100:103], v[24:27], v[104:107], 0
	v_mfma_f32_16x16x32_bf16 v[104:107], v[16:19], v[112:115], 0
	v_mfma_f32_16x16x32_bf16 v[16:19], v[16:19], v[120:123], 0
	v_mfma_f32_16x16x32_bf16 v[60:63], v[20:23], v[108:111], v[60:63]
	v_mfma_f32_16x16x32_bf16 v[100:103], v[28:31], v[108:111], v[100:103]
	v_mfma_f32_16x16x32_bf16 v[104:107], v[20:23], v[116:119], v[104:107]
	v_mfma_f32_16x16x32_bf16 v[108:111], v[24:27], v[112:115], 0
	s_setprio 2
	s_barrier
	v_mfma_f32_16x16x32_bf16 v[16:19], v[20:23], v[124:127], v[16:19]
	v_mfma_f32_16x16x32_bf16 v[20:23], v[24:27], v[120:123], 0
	v_mfma_f32_16x16x32_bf16 v[108:111], v[28:31], v[116:119], v[108:111]
	v_mfma_f32_16x16x32_bf16 v[20:23], v[28:31], v[124:127], v[20:23]
	s_setprio 0
	s_add_i32 s63, 0, 0x18000
	s_add_i32 s68, 0, 0x1c000
	v_add_u32_e32 v179, s63, v141
	v_add_u32_e32 v232, s68, v141
	ds_read_b128 v[24:27], v179
	ds_read_b128 v[28:31], v179 offset:1024
	ds_read_b128 v[112:115], v179 offset:2048
	ds_read_b128 v[116:119], v179 offset:3072
	ds_read_b128 v[120:123], v232
	ds_read_b128 v[124:127], v232 offset:1024
	ds_read_b128 v[164:167], v232 offset:2048
	ds_read_b128 v[168:171], v232 offset:3072
	s_add_u32 s64, s20, 0x20100
	s_addc_u32 s65, s21, 0
	s_mov_b32 m0, s52
	v_lshl_add_u64 v[226:227], s[64:65], 0, v[132:133]
	ds_read_b128 v[182:185], v143 offset:32768
	ds_read_b128 v[186:189], v143 offset:33792
	ds_read_b128 v[190:193], v143 offset:34816
	ds_read_b128 v[194:197], v143 offset:35840
	ds_read_b128 v[198:201], v143 offset:36864
	ds_read_b128 v[202:205], v143 offset:37888
	ds_read_b128 v[206:209], v143 offset:38912
	ds_read_b128 v[210:213], v143 offset:39936
	global_load_lds_dwordx4 v[226:227], off
	v_lshl_add_u64 v[226:227], s[64:65], 0, v[130:131]
	s_mov_b32 m0, s53
	s_nop 0
	global_load_lds_dwordx4 v[226:227], off
	s_waitcnt vmcnt(8)
	s_waitcnt lgkmcnt(0)
	s_barrier
	s_setprio 1
	v_mfma_f32_16x16x32_bf16 v[64:67], v[24:27], v[182:185], v[64:67]
	v_mfma_f32_16x16x32_bf16 v[68:71], v[112:115], v[182:185], v[68:71]
	v_mfma_f32_16x16x32_bf16 v[72:75], v[24:27], v[190:193], v[72:75]
	v_mfma_f32_16x16x32_bf16 v[76:79], v[112:115], v[190:193], v[76:79]
	v_mfma_f32_16x16x32_bf16 v[80:83], v[24:27], v[198:201], v[80:83]
	v_mfma_f32_16x16x32_bf16 v[84:87], v[112:115], v[198:201], v[84:87]
	v_mfma_f32_16x16x32_bf16 v[88:91], v[24:27], v[206:209], v[88:91]
	v_mfma_f32_16x16x32_bf16 v[92:95], v[112:115], v[206:209], v[92:95]
	v_mfma_f32_16x16x32_bf16 v[64:67], v[28:31], v[186:189], v[64:67]
	v_mfma_f32_16x16x32_bf16 v[68:71], v[116:119], v[186:189], v[68:71]
	v_mfma_f32_16x16x32_bf16 v[72:75], v[28:31], v[194:197], v[72:75]
	v_mfma_f32_16x16x32_bf16 v[76:79], v[116:119], v[194:197], v[76:79]
	v_mfma_f32_16x16x32_bf16 v[80:83], v[28:31], v[202:205], v[80:83]
	v_mfma_f32_16x16x32_bf16 v[84:87], v[116:119], v[202:205], v[84:87]
	v_mfma_f32_16x16x32_bf16 v[88:91], v[28:31], v[210:213], v[88:91]
	v_mfma_f32_16x16x32_bf16 v[92:95], v[116:119], v[210:213], v[92:95]
	v_mfma_f32_16x16x32_bf16 v[96:99], v[120:123], v[182:185], v[96:99]
	v_mfma_f32_16x16x32_bf16 v[32:35], v[164:167], v[182:185], v[32:35]
	v_mfma_f32_16x16x32_bf16 v[36:39], v[120:123], v[190:193], v[36:39]
	v_mfma_f32_16x16x32_bf16 v[40:43], v[164:167], v[190:193], v[40:43]
	v_mfma_f32_16x16x32_bf16 v[44:47], v[120:123], v[198:201], v[44:47]
	v_mfma_f32_16x16x32_bf16 v[48:51], v[164:167], v[198:201], v[48:51]
	v_mfma_f32_16x16x32_bf16 v[52:55], v[120:123], v[206:209], v[52:55]
	v_mfma_f32_16x16x32_bf16 v[56:59], v[164:167], v[206:209], v[56:59]
	v_mfma_f32_16x16x32_bf16 v[96:99], v[124:127], v[186:189], v[96:99]
	v_mfma_f32_16x16x32_bf16 v[32:35], v[168:171], v[186:189], v[32:35]
	v_mfma_f32_16x16x32_bf16 v[36:39], v[124:127], v[194:197], v[36:39]
	v_mfma_f32_16x16x32_bf16 v[40:43], v[168:171], v[194:197], v[40:43]
	s_setprio 2
	s_barrier
	v_mfma_f32_16x16x32_bf16 v[44:47], v[124:127], v[202:205], v[44:47]
	v_mfma_f32_16x16x32_bf16 v[48:51], v[168:171], v[202:205], v[48:51]
	v_mfma_f32_16x16x32_bf16 v[52:55], v[124:127], v[210:213], v[52:55]
	v_mfma_f32_16x16x32_bf16 v[56:59], v[168:171], v[210:213], v[56:59]
	s_setprio 0
	s_add_i32 s63, s63, s43
	s_mov_b64 s[72:73], 0x180
	s_add_i32 s59, s63, 0x2000
	v_lshl_add_u64 v[138:139], v[138:139], 0, s[72:73]
	s_mov_b32 m0, s63
	s_add_u32 s64, s22, 0x10180
	ds_read_b128 v[182:185], v143 offset:49152
	ds_read_b128 v[186:189], v143 offset:50176
	ds_read_b128 v[190:193], v143 offset:51200
	ds_read_b128 v[194:197], v143 offset:52224
	ds_read_b128 v[198:201], v143 offset:53248
	ds_read_b128 v[202:205], v143 offset:54272
	ds_read_b128 v[206:209], v143 offset:55296
	ds_read_b128 v[210:213], v143 offset:56320
	global_load_lds_dwordx4 v[138:139], off
	v_lshl_add_u64 v[138:139], v[172:173], 0, s[72:73]
	s_mov_b32 m0, s59
	s_addc_u32 s65, s23, 0
	s_add_i32 s22, s68, s43
	global_load_lds_dwordx4 v[138:139], off
	v_lshl_add_u64 v[138:139], s[64:65], 0, v[176:177]
	s_mov_b32 m0, s22
	s_add_i32 s23, s22, 0x2000
	global_load_lds_dwordx4 v[138:139], off
	v_lshl_add_u64 v[138:139], s[64:65], 0, v[128:129]
	s_mov_b32 m0, s23
	s_nop 0
	global_load_lds_dwordx4 v[138:139], off
	v_lshl_add_u64 v[138:139], v[220:221], 0, s[72:73]
	s_mov_b32 m0, s54
	s_nop 0
	global_load_lds_dwordx4 v[138:139], off
	v_lshl_add_u64 v[138:139], v[222:223], 0, s[72:73]
	s_mov_b32 m0, s55
	s_nop 0
	global_load_lds_dwordx4 v[138:139], off
	s_waitcnt vmcnt(8)
	s_waitcnt lgkmcnt(0)
	s_barrier
	s_setprio 1
	v_mfma_f32_16x16x32_bf16 v[0:3], v[24:27], v[206:209], v[0:3]
	v_mfma_f32_16x16x32_bf16 v[4:7], v[112:115], v[206:209], v[4:7]
	v_mfma_f32_16x16x32_bf16 v[134:137], v[24:27], v[182:185], v[134:137]
	v_mfma_f32_16x16x32_bf16 v[144:147], v[112:115], v[182:185], v[144:147]
	v_mfma_f32_16x16x32_bf16 v[148:151], v[24:27], v[190:193], v[148:151]
	v_mfma_f32_16x16x32_bf16 v[152:155], v[112:115], v[190:193], v[152:155]
	v_mfma_f32_16x16x32_bf16 v[156:159], v[24:27], v[198:201], v[156:159]
	v_mfma_f32_16x16x32_bf16 v[160:163], v[112:115], v[198:201], v[160:163]
	v_mfma_f32_16x16x32_bf16 v[0:3], v[28:31], v[210:213], v[0:3]
	v_mfma_f32_16x16x32_bf16 v[4:7], v[116:119], v[210:213], v[4:7]
	v_mfma_f32_16x16x32_bf16 v[134:137], v[28:31], v[186:189], v[134:137]
	v_mfma_f32_16x16x32_bf16 v[144:147], v[116:119], v[186:189], v[144:147]
	v_mfma_f32_16x16x32_bf16 v[148:151], v[28:31], v[194:197], v[148:151]
	v_mfma_f32_16x16x32_bf16 v[152:155], v[116:119], v[194:197], v[152:155]
	v_mfma_f32_16x16x32_bf16 v[156:159], v[28:31], v[202:205], v[156:159]
	v_mfma_f32_16x16x32_bf16 v[160:163], v[116:119], v[202:205], v[160:163]
	v_mfma_f32_16x16x32_bf16 v[8:11], v[120:123], v[182:185], v[8:11]
	v_mfma_f32_16x16x32_bf16 v[12:15], v[164:167], v[182:185], v[12:15]
	v_mfma_f32_16x16x32_bf16 v[24:27], v[120:123], v[190:193], v[60:63]
	v_mfma_f32_16x16x32_bf16 v[28:31], v[164:167], v[190:193], v[100:103]
	v_mfma_f32_16x16x32_bf16 v[60:63], v[120:123], v[198:201], v[104:107]
	v_mfma_f32_16x16x32_bf16 v[100:103], v[164:167], v[198:201], v[108:111]
	v_mfma_f32_16x16x32_bf16 v[16:19], v[120:123], v[206:209], v[16:19]
	v_mfma_f32_16x16x32_bf16 v[20:23], v[164:167], v[206:209], v[20:23]
	v_mfma_f32_16x16x32_bf16 v[8:11], v[124:127], v[186:189], v[8:11]
	v_mfma_f32_16x16x32_bf16 v[12:15], v[168:171], v[186:189], v[12:15]
	v_mfma_f32_16x16x32_bf16 v[24:27], v[124:127], v[194:197], v[24:27]
	v_mfma_f32_16x16x32_bf16 v[28:31], v[168:171], v[194:197], v[28:31]
	s_setprio 2
	s_barrier
	v_mfma_f32_16x16x32_bf16 v[60:63], v[124:127], v[202:205], v[60:63]
	v_mfma_f32_16x16x32_bf16 v[100:103], v[168:171], v[202:205], v[100:103]
	v_mfma_f32_16x16x32_bf16 v[16:19], v[124:127], v[210:213], v[16:19]
	v_mfma_f32_16x16x32_bf16 v[20:23], v[168:171], v[210:213], v[20:23]
	s_setprio 0
	ds_read_b128 v[104:107], v175
	ds_read_b128 v[108:111], v175 offset:1024
	ds_read_b128 v[112:115], v175 offset:2048
	ds_read_b128 v[116:119], v175 offset:3072
	ds_read_b128 v[120:123], v178
	ds_read_b128 v[124:127], v178 offset:1024
	ds_read_b128 v[164:167], v178 offset:2048
	ds_read_b128 v[168:171], v178 offset:3072
	s_add_u32 s20, s20, 0x20180
	s_addc_u32 s21, s21, 0
	s_mov_b32 m0, s62
	v_lshl_add_u64 v[138:139], s[20:21], 0, v[132:133]
	ds_read_b128 v[182:185], v143
	ds_read_b128 v[186:189], v143 offset:1024
	ds_read_b128 v[190:193], v143 offset:2048
	ds_read_b128 v[194:197], v143 offset:3072
	ds_read_b128 v[198:201], v143 offset:4096
	ds_read_b128 v[202:205], v143 offset:5120
	ds_read_b128 v[206:209], v143 offset:6144
	ds_read_b128 v[210:213], v143 offset:7168
	global_load_lds_dwordx4 v[138:139], off
	v_lshl_add_u64 v[138:139], s[20:21], 0, v[130:131]
	s_mov_b32 m0, s9
	s_nop 0
	global_load_lds_dwordx4 v[138:139], off
	s_waitcnt vmcnt(8)
	s_waitcnt lgkmcnt(0)
	s_barrier
	s_setprio 1
	v_mfma_f32_16x16x32_bf16 v[64:67], v[104:107], v[182:185], v[64:67]
	v_mfma_f32_16x16x32_bf16 v[68:71], v[112:115], v[182:185], v[68:71]
	v_mfma_f32_16x16x32_bf16 v[72:75], v[104:107], v[190:193], v[72:75]
	v_mfma_f32_16x16x32_bf16 v[76:79], v[112:115], v[190:193], v[76:79]
	v_mfma_f32_16x16x32_bf16 v[80:83], v[104:107], v[198:201], v[80:83]
	v_mfma_f32_16x16x32_bf16 v[84:87], v[112:115], v[198:201], v[84:87]
	v_mfma_f32_16x16x32_bf16 v[88:91], v[104:107], v[206:209], v[88:91]
	v_mfma_f32_16x16x32_bf16 v[92:95], v[112:115], v[206:209], v[92:95]
	v_mfma_f32_16x16x32_bf16 v[64:67], v[108:111], v[186:189], v[64:67]
	v_mfma_f32_16x16x32_bf16 v[68:71], v[116:119], v[186:189], v[68:71]
	v_mfma_f32_16x16x32_bf16 v[72:75], v[108:111], v[194:197], v[72:75]
	v_mfma_f32_16x16x32_bf16 v[76:79], v[116:119], v[194:197], v[76:79]
	v_mfma_f32_16x16x32_bf16 v[80:83], v[108:111], v[202:205], v[80:83]
	v_mfma_f32_16x16x32_bf16 v[84:87], v[116:119], v[202:205], v[84:87]
	v_mfma_f32_16x16x32_bf16 v[88:91], v[108:111], v[210:213], v[88:91]
	v_mfma_f32_16x16x32_bf16 v[92:95], v[116:119], v[210:213], v[92:95]
	v_mfma_f32_16x16x32_bf16 v[32:35], v[164:167], v[182:185], v[32:35]
	v_mfma_f32_16x16x32_bf16 v[36:39], v[120:123], v[190:193], v[36:39]
	v_mfma_f32_16x16x32_bf16 v[40:43], v[164:167], v[190:193], v[40:43]
	v_mfma_f32_16x16x32_bf16 v[44:47], v[120:123], v[198:201], v[44:47]
	v_mfma_f32_16x16x32_bf16 v[48:51], v[164:167], v[198:201], v[48:51]
	v_mfma_f32_16x16x32_bf16 v[52:55], v[120:123], v[206:209], v[52:55]
	v_mfma_f32_16x16x32_bf16 v[56:59], v[164:167], v[206:209], v[56:59]
	v_mfma_f32_16x16x32_bf16 v[96:99], v[120:123], v[182:185], v[96:99]
	v_mfma_f32_16x16x32_bf16 v[32:35], v[168:171], v[186:189], v[32:35]
	v_mfma_f32_16x16x32_bf16 v[36:39], v[124:127], v[194:197], v[36:39]
	v_mfma_f32_16x16x32_bf16 v[40:43], v[168:171], v[194:197], v[40:43]
	v_mfma_f32_16x16x32_bf16 v[44:47], v[124:127], v[202:205], v[44:47]
	s_setprio 2
	s_barrier
	v_mfma_f32_16x16x32_bf16 v[48:51], v[168:171], v[202:205], v[48:51]
	v_mfma_f32_16x16x32_bf16 v[52:55], v[124:127], v[210:213], v[52:55]
	v_mfma_f32_16x16x32_bf16 v[56:59], v[168:171], v[210:213], v[56:59]
	v_mfma_f32_16x16x32_bf16 v[228:231], v[124:127], v[186:189], v[96:99]
	s_setprio 0
	s_mov_b32 m0, s58
	v_lshl_add_u64 v[138:139], s[24:25], 0, v[176:177]
	s_add_u32 s20, s24, 0x10000
	ds_read_b128 v[96:99], v143 offset:16384
	ds_read_b128 v[182:185], v143 offset:17408
	ds_read_b128 v[186:189], v143 offset:18432
	ds_read_b128 v[190:193], v143 offset:19456
	ds_read_b128 v[194:197], v143 offset:20480
	ds_read_b128 v[198:201], v143 offset:21504
	ds_read_b128 v[202:205], v143 offset:22528
	ds_read_b128 v[206:209], v143 offset:23552
	global_load_lds_dwordx4 v[138:139], off
	v_lshl_add_u64 v[172:173], s[24:25], 0, v[128:129]
	s_mov_b32 m0, s11
	s_addc_u32 s21, s25, 0
	global_load_lds_dwordx4 v[172:173], off
	v_lshl_add_u64 v[210:211], s[20:21], 0, v[176:177]
	s_mov_b32 m0, s17
	v_lshl_add_u64 v[226:227], s[26:27], 0, v[132:133]
	global_load_lds_dwordx4 v[210:211], off
	v_lshl_add_u64 v[210:211], s[20:21], 0, v[128:129]
	s_mov_b32 m0, s57
	v_lshl_add_u64 v[252:253], s[26:27], 0, v[130:131]
	global_load_lds_dwordx4 v[210:211], off
	s_mov_b32 m0, s19
	s_nop 0
	global_load_lds_dwordx4 v[226:227], off
	s_mov_b32 m0, s51
	s_nop 0
	global_load_lds_dwordx4 v[252:253], off
	s_waitcnt vmcnt(8)
	s_waitcnt lgkmcnt(0)
	s_barrier
	s_setprio 1
	v_mfma_f32_16x16x32_bf16 v[0:3], v[104:107], v[202:205], v[0:3]
	v_mfma_f32_16x16x32_bf16 v[4:7], v[112:115], v[202:205], v[4:7]
	v_mfma_f32_16x16x32_bf16 v[134:137], v[104:107], v[96:99], v[134:137]
	v_mfma_f32_16x16x32_bf16 v[144:147], v[112:115], v[96:99], v[144:147]
	v_mfma_f32_16x16x32_bf16 v[148:151], v[104:107], v[186:189], v[148:151]
	v_mfma_f32_16x16x32_bf16 v[152:155], v[112:115], v[186:189], v[152:155]
	v_mfma_f32_16x16x32_bf16 v[156:159], v[104:107], v[194:197], v[156:159]
	v_mfma_f32_16x16x32_bf16 v[160:163], v[112:115], v[194:197], v[160:163]
	v_mfma_f32_16x16x32_bf16 v[0:3], v[108:111], v[206:209], v[0:3]
	v_mfma_f32_16x16x32_bf16 v[4:7], v[116:119], v[206:209], v[4:7]
	v_mfma_f32_16x16x32_bf16 v[134:137], v[108:111], v[182:185], v[134:137]
	v_mfma_f32_16x16x32_bf16 v[144:147], v[116:119], v[182:185], v[144:147]
	v_mfma_f32_16x16x32_bf16 v[148:151], v[108:111], v[190:193], v[148:151]
	v_mfma_f32_16x16x32_bf16 v[152:155], v[116:119], v[190:193], v[152:155]
	v_mfma_f32_16x16x32_bf16 v[156:159], v[108:111], v[198:201], v[156:159]
	v_mfma_f32_16x16x32_bf16 v[160:163], v[116:119], v[198:201], v[160:163]
	v_mfma_f32_16x16x32_bf16 v[8:11], v[120:123], v[96:99], v[8:11]
	v_mfma_f32_16x16x32_bf16 v[12:15], v[164:167], v[96:99], v[12:15]
	v_mfma_f32_16x16x32_bf16 v[24:27], v[120:123], v[186:189], v[24:27]
	v_mfma_f32_16x16x32_bf16 v[28:31], v[164:167], v[186:189], v[28:31]
	v_mfma_f32_16x16x32_bf16 v[60:63], v[120:123], v[194:197], v[60:63]
	v_mfma_f32_16x16x32_bf16 v[16:19], v[120:123], v[202:205], v[16:19]
	v_mfma_f32_16x16x32_bf16 v[8:11], v[124:127], v[182:185], v[8:11]
	v_mfma_f32_16x16x32_bf16 v[12:15], v[168:171], v[182:185], v[12:15]
	v_mfma_f32_16x16x32_bf16 v[24:27], v[124:127], v[190:193], v[24:27]
	v_mfma_f32_16x16x32_bf16 v[28:31], v[168:171], v[190:193], v[28:31]
	v_mfma_f32_16x16x32_bf16 v[182:185], v[124:127], v[198:201], v[60:63]
	v_mfma_f32_16x16x32_bf16 v[60:63], v[164:167], v[194:197], v[100:103]
	s_setprio 2
	s_barrier
	v_mfma_f32_16x16x32_bf16 v[190:193], v[124:127], v[206:209], v[16:19]
	v_mfma_f32_16x16x32_bf16 v[16:19], v[164:167], v[202:205], v[20:23]
	v_mfma_f32_16x16x32_bf16 v[186:189], v[168:171], v[198:201], v[60:63]
	v_mfma_f32_16x16x32_bf16 v[164:167], v[168:171], v[206:209], v[16:19]
	s_setprio 0
	s_nop 1
	ds_read_b128 v[60:63], v179
	ds_read_b128 v[168:171], v179 offset:1024
	ds_read_b128 v[194:197], v179 offset:2048
	ds_read_b128 v[198:201], v179 offset:3072
	ds_read_b128 v[202:205], v232
	ds_read_b128 v[206:209], v232 offset:1024
	ds_read_b128 v[210:213], v232 offset:2048
	ds_read_b128 v[232:235], v232 offset:3072
	s_add_u32 s20, s26, 0x20000
	s_addc_u32 s21, s27, 0
	s_mov_b32 m0, s52
	v_lshl_add_u64 v[96:97], s[20:21], 0, v[132:133]
	ds_read_b128 v[16:19], v143 offset:32768
	ds_read_b128 v[20:23], v143 offset:33792
	ds_read_b128 v[108:111], v143 offset:34816
	ds_read_b128 v[236:239], v143 offset:35840
	ds_read_b128 v[240:243], v143 offset:36864
	ds_read_b128 v[244:247], v143 offset:37888
	ds_read_b128 v[248:251], v143 offset:38912
	ds_read_b128 v[220:223], v143 offset:39936
	global_load_lds_dwordx4 v[96:97], off
	v_lshl_add_u64 v[96:97], s[20:21], 0, v[130:131]
	s_mov_b32 m0, s53
	s_nop 0
	global_load_lds_dwordx4 v[96:97], off
	s_waitcnt vmcnt(8)
	s_waitcnt lgkmcnt(0)
	s_barrier
	s_setprio 1
	v_mfma_f32_16x16x32_bf16 v[64:67], v[60:63], v[16:19], v[64:67]
	v_mfma_f32_16x16x32_bf16 v[112:115], v[168:171], v[20:23], v[64:67]
	v_mfma_f32_16x16x32_bf16 v[64:67], v[194:197], v[16:19], v[68:71]
	v_mfma_f32_16x16x32_bf16 v[116:119], v[198:201], v[20:23], v[64:67]
	v_mfma_f32_16x16x32_bf16 v[64:67], v[60:63], v[108:111], v[72:75]
	v_mfma_f32_16x16x32_bf16 v[96:99], v[168:171], v[236:239], v[64:67]
	v_mfma_f32_16x16x32_bf16 v[64:67], v[194:197], v[108:111], v[76:79]
	v_mfma_f32_16x16x32_bf16 v[100:103], v[198:201], v[236:239], v[64:67]
	v_mfma_f32_16x16x32_bf16 v[64:67], v[60:63], v[240:243], v[80:83]
	v_mfma_f32_16x16x32_bf16 v[80:83], v[168:171], v[244:247], v[64:67]
	v_mfma_f32_16x16x32_bf16 v[64:67], v[194:197], v[240:243], v[84:87]
	v_mfma_f32_16x16x32_bf16 v[84:87], v[198:201], v[244:247], v[64:67]
	v_mfma_f32_16x16x32_bf16 v[64:67], v[60:63], v[248:251], v[88:91]
	v_mfma_f32_16x16x32_bf16 v[68:71], v[194:197], v[248:251], v[92:95]
	v_mfma_f32_16x16x32_bf16 v[64:67], v[168:171], v[220:223], v[64:67]
	v_mfma_f32_16x16x32_bf16 v[68:71], v[198:201], v[220:223], v[68:71]
	v_mfma_f32_16x16x32_bf16 v[72:75], v[202:205], v[16:19], v[228:231]
	v_mfma_f32_16x16x32_bf16 v[16:19], v[210:213], v[16:19], v[32:35]
	v_mfma_f32_16x16x32_bf16 v[124:127], v[232:235], v[20:23], v[16:19]
	v_mfma_f32_16x16x32_bf16 v[16:19], v[202:205], v[108:111], v[36:39]
	v_mfma_f32_16x16x32_bf16 v[104:107], v[206:209], v[236:239], v[16:19]
	v_mfma_f32_16x16x32_bf16 v[16:19], v[210:213], v[108:111], v[40:43]
	v_mfma_f32_16x16x32_bf16 v[108:111], v[232:235], v[236:239], v[16:19]
	v_mfma_f32_16x16x32_bf16 v[16:19], v[202:205], v[240:243], v[44:47]
	v_mfma_f32_16x16x32_bf16 v[88:91], v[206:209], v[244:247], v[16:19]
	v_mfma_f32_16x16x32_bf16 v[16:19], v[210:213], v[240:243], v[48:51]
	v_mfma_f32_16x16x32_bf16 v[92:95], v[232:235], v[244:247], v[16:19]
	v_mfma_f32_16x16x32_bf16 v[16:19], v[202:205], v[248:251], v[52:55]
	s_setprio 2
	s_barrier
	v_mfma_f32_16x16x32_bf16 v[120:123], v[206:209], v[20:23], v[72:75]
	v_mfma_f32_16x16x32_bf16 v[72:75], v[206:209], v[220:223], v[16:19]
	v_mfma_f32_16x16x32_bf16 v[16:19], v[210:213], v[248:251], v[56:59]
	v_mfma_f32_16x16x32_bf16 v[76:79], v[232:235], v[220:223], v[16:19]
	s_setprio 0
	s_mov_b32 m0, s63
	s_nop 3
	v_lshl_add_u64 v[16:17], v[138:139], 0, s[34:35]
	s_add_u32 s20, s24, 0x10080
	ds_read_b128 v[40:43], v143 offset:49152
	ds_read_b128 v[44:47], v143 offset:50176
	ds_read_b128 v[220:223], v143 offset:51200
	ds_read_b128 v[228:231], v143 offset:52224
	ds_read_b128 v[236:239], v143 offset:53248
	ds_read_b128 v[240:243], v143 offset:54272
	ds_read_b128 v[244:247], v143 offset:55296
	ds_read_b128 v[248:251], v143 offset:56320
	global_load_lds_dwordx4 v[16:17], off
	v_lshl_add_u64 v[16:17], v[172:173], 0, s[34:35]
	s_mov_b32 m0, s59
	s_addc_u32 s21, s25, 0
	global_load_lds_dwordx4 v[16:17], off
	v_lshl_add_u64 v[16:17], s[20:21], 0, v[176:177]
	s_mov_b32 m0, s22
	s_nop 0
	global_load_lds_dwordx4 v[16:17], off
	v_lshl_add_u64 v[16:17], s[20:21], 0, v[128:129]
	s_mov_b32 m0, s23
	s_nop 0
	global_load_lds_dwordx4 v[16:17], off
	v_lshl_add_u64 v[16:17], v[226:227], 0, s[34:35]
	s_mov_b32 m0, s54
	s_nop 0
	global_load_lds_dwordx4 v[16:17], off
	v_lshl_add_u64 v[16:17], v[252:253], 0, s[34:35]
	s_mov_b32 m0, s55
	s_nop 0
	global_load_lds_dwordx4 v[16:17], off
	s_waitcnt vmcnt(8)
	s_waitcnt lgkmcnt(0)
	s_barrier
	s_setprio 1
	v_mfma_f32_16x16x32_bf16 v[16:19], v[60:63], v[40:43], v[134:137]
	v_mfma_f32_16x16x32_bf16 v[48:51], v[168:171], v[44:47], v[16:19]
	v_mfma_f32_16x16x32_bf16 v[16:19], v[194:197], v[40:43], v[144:147]
	v_mfma_f32_16x16x32_bf16 v[52:55], v[198:201], v[44:47], v[16:19]
	v_mfma_f32_16x16x32_bf16 v[16:19], v[60:63], v[220:223], v[148:151]
	v_mfma_f32_16x16x32_bf16 v[32:35], v[168:171], v[228:231], v[16:19]
	v_mfma_f32_16x16x32_bf16 v[16:19], v[194:197], v[220:223], v[152:155]
	v_mfma_f32_16x16x32_bf16 v[36:39], v[198:201], v[228:231], v[16:19]
	v_mfma_f32_16x16x32_bf16 v[16:19], v[60:63], v[236:239], v[156:159]
	v_mfma_f32_16x16x32_bf16 v[20:23], v[194:197], v[236:239], v[160:163]
	v_mfma_f32_16x16x32_bf16 v[0:3], v[60:63], v[244:247], v[0:3]
	v_mfma_f32_16x16x32_bf16 v[4:7], v[194:197], v[244:247], v[4:7]
	v_mfma_f32_16x16x32_bf16 v[16:19], v[168:171], v[240:243], v[16:19]
	v_mfma_f32_16x16x32_bf16 v[20:23], v[198:201], v[240:243], v[20:23]
	v_mfma_f32_16x16x32_bf16 v[0:3], v[168:171], v[248:251], v[0:3]
	v_mfma_f32_16x16x32_bf16 v[4:7], v[198:201], v[248:251], v[4:7]
	v_mfma_f32_16x16x32_bf16 v[8:11], v[202:205], v[40:43], v[8:11]
	v_mfma_f32_16x16x32_bf16 v[56:59], v[206:209], v[44:47], v[8:11]
	v_mfma_f32_16x16x32_bf16 v[8:11], v[210:213], v[40:43], v[12:15]
	v_mfma_f32_16x16x32_bf16 v[60:63], v[232:235], v[44:47], v[8:11]
	v_mfma_f32_16x16x32_bf16 v[8:11], v[202:205], v[220:223], v[24:27]
	v_mfma_f32_16x16x32_bf16 v[40:43], v[206:209], v[228:231], v[8:11]
	v_mfma_f32_16x16x32_bf16 v[8:11], v[210:213], v[220:223], v[28:31]
	v_mfma_f32_16x16x32_bf16 v[44:47], v[232:235], v[228:231], v[8:11]
	v_mfma_f32_16x16x32_bf16 v[8:11], v[202:205], v[236:239], v[182:185]
	v_mfma_f32_16x16x32_bf16 v[24:27], v[206:209], v[240:243], v[8:11]
	v_mfma_f32_16x16x32_bf16 v[8:11], v[210:213], v[236:239], v[186:189]
	v_mfma_f32_16x16x32_bf16 v[28:31], v[232:235], v[240:243], v[8:11]
	s_setprio 2
	s_barrier
	v_mfma_f32_16x16x32_bf16 v[8:11], v[202:205], v[244:247], v[190:193]
	v_mfma_f32_16x16x32_bf16 v[12:15], v[210:213], v[244:247], v[164:167]
	v_mfma_f32_16x16x32_bf16 v[8:11], v[206:209], v[248:251], v[8:11]
	v_mfma_f32_16x16x32_bf16 v[12:15], v[232:235], v[248:251], v[12:15]
	s_setprio 0
	s_andn2_b64 vcc, exec, s[4:5]
	s_cbranch_vccnz .LBB0_414
	s_barrier

.LBB0_426:
	s_ashr_i32 s11, s10, 31
	s_lshl_b64 s[12:13], s[10:11], 18
	s_add_u32 s12, s25, s12
	s_addc_u32 s13, s26, s13
	s_and_b64 s[14:15], s[2:3], exec
	s_cselect_b32 s23, s13, s21
	s_cselect_b32 s22, s12, s20
	s_ashr_i32 s9, s8, 31
	s_lshl_b64 s[14:15], s[8:9], 16
	s_add_u32 s14, s27, s14
	s_addc_u32 s15, s28, s15
	s_add_u32 s56, s20, 0x20080
	s_addc_u32 s57, s21, 0
	s_add_u32 s20, s22, 0x20000
	s_addc_u32 s21, s23, 0
	s_add_i32 s9, 0, 0x10000
	s_and_b64 s[58:59], s[2:3], exec
	s_cselect_b32 s18, s14, s18
	s_cselect_b32 s19, s15, s19
	s_add_u32 s58, s18, 0x8000
	s_addc_u32 s59, s19, 0
	s_add_i32 s11, 0, 0x14000
	v_add_u32_e32 v12, s9, v139
	v_add_u32_e32 v28, s11, v139
	ds_read_b128 v[0:3], v12
	ds_read_b128 v[4:7], v12 offset:1024
	ds_read_b128 v[8:11], v12 offset:2048
	ds_read_b128 v[12:15], v12 offset:3072
	ds_read_b128 v[16:19], v28
	ds_read_b128 v[20:23], v28 offset:1024
	ds_read_b128 v[24:27], v28 offset:2048
	ds_read_b128 v[28:31], v28 offset:3072
	v_lshl_add_u64 v[64:65], s[56:57], 0, v[134:135]
	s_add_i32 m0, s43, 0xc000
	ds_read_b128 v[32:35], v140
	ds_read_b128 v[36:39], v140 offset:1024
	ds_read_b128 v[40:43], v140 offset:2048
	ds_read_b128 v[44:47], v140 offset:3072
	ds_read_b128 v[48:51], v140 offset:4096
	ds_read_b128 v[52:55], v140 offset:5120
	ds_read_b128 v[56:59], v140 offset:6144
	ds_read_b128 v[60:63], v140 offset:7168
	global_load_lds_dwordx4 v[64:65], off
	v_lshl_add_u64 v[64:65], s[56:57], 0, v[130:131]
	s_add_i32 m0, s43, 0xe000
	s_nop 0
	global_load_lds_dwordx4 v[64:65], off
	s_waitcnt vmcnt(8)
	s_waitcnt lgkmcnt(0)
	s_barrier
	s_setprio 1
	v_mfma_f32_16x16x32_bf16 v[64:67], v[0:3], v[32:35], 0
	v_mfma_f32_16x16x32_bf16 v[68:71], v[8:11], v[32:35], 0
	v_mfma_f32_16x16x32_bf16 v[72:75], v[0:3], v[40:43], 0
	v_mfma_f32_16x16x32_bf16 v[76:79], v[8:11], v[40:43], 0
	v_mfma_f32_16x16x32_bf16 v[80:83], v[0:3], v[48:51], 0
	v_mfma_f32_16x16x32_bf16 v[84:87], v[8:11], v[48:51], 0
	v_mfma_f32_16x16x32_bf16 v[88:91], v[0:3], v[56:59], 0
	v_mfma_f32_16x16x32_bf16 v[92:95], v[8:11], v[56:59], 0
	v_mfma_f32_16x16x32_bf16 v[64:67], v[4:7], v[36:39], v[64:67]
	v_mfma_f32_16x16x32_bf16 v[68:71], v[12:15], v[36:39], v[68:71]
	v_mfma_f32_16x16x32_bf16 v[72:75], v[4:7], v[44:47], v[72:75]
	v_mfma_f32_16x16x32_bf16 v[76:79], v[12:15], v[44:47], v[76:79]
	v_mfma_f32_16x16x32_bf16 v[80:83], v[4:7], v[52:55], v[80:83]
	v_mfma_f32_16x16x32_bf16 v[84:87], v[12:15], v[52:55], v[84:87]
	v_mfma_f32_16x16x32_bf16 v[88:91], v[4:7], v[60:63], v[88:91]
	v_mfma_f32_16x16x32_bf16 v[92:95], v[12:15], v[60:63], v[92:95]
	v_mfma_f32_16x16x32_bf16 v[96:99], v[16:19], v[32:35], 0
	v_mfma_f32_16x16x32_bf16 v[32:35], v[24:27], v[32:35], 0
	v_mfma_f32_16x16x32_bf16 v[104:107], v[20:23], v[36:39], v[96:99]
	v_mfma_f32_16x16x32_bf16 v[32:35], v[28:31], v[36:39], v[32:35]
	v_mfma_f32_16x16x32_bf16 v[36:39], v[16:19], v[40:43], 0
	v_mfma_f32_16x16x32_bf16 v[40:43], v[24:27], v[40:43], 0
	v_mfma_f32_16x16x32_bf16 v[36:39], v[20:23], v[44:47], v[36:39]
	v_mfma_f32_16x16x32_bf16 v[40:43], v[28:31], v[44:47], v[40:43]
	v_mfma_f32_16x16x32_bf16 v[44:47], v[16:19], v[48:51], 0
	v_mfma_f32_16x16x32_bf16 v[48:51], v[24:27], v[48:51], 0
	v_mfma_f32_16x16x32_bf16 v[44:47], v[20:23], v[52:55], v[44:47]
	v_mfma_f32_16x16x32_bf16 v[48:51], v[28:31], v[52:55], v[48:51]
	s_setprio 2
	s_barrier
	v_mfma_f32_16x16x32_bf16 v[52:55], v[16:19], v[56:59], 0
	v_mfma_f32_16x16x32_bf16 v[56:59], v[24:27], v[56:59], 0
	v_mfma_f32_16x16x32_bf16 v[52:55], v[20:23], v[60:63], v[52:55]
	v_mfma_f32_16x16x32_bf16 v[56:59], v[28:31], v[60:63], v[56:59]
	s_setprio 0
	s_add_i32 s9, s9, s29
	v_lshl_add_u64 v[136:137], s[18:19], 0, v[132:133]
	s_mov_b32 m0, s9
	ds_read_b128 v[60:63], v140 offset:16384
	ds_read_b128 v[96:99], v140 offset:17408
	ds_read_b128 v[100:103], v140 offset:18432
	ds_read_b128 v[108:111], v140 offset:19456
	ds_read_b128 v[112:115], v140 offset:20480
	ds_read_b128 v[116:119], v140 offset:21504
	ds_read_b128 v[120:123], v140 offset:22528
	ds_read_b128 v[124:127], v140 offset:23552
	global_load_lds_dwordx4 v[136:137], off
	v_lshl_add_u64 v[226:227], s[18:19], 0, v[128:129]
	s_add_i32 m0, s9, 0x2000
	s_add_i32 s9, s11, s29
	global_load_lds_dwordx4 v[226:227], off
	v_lshl_add_u64 v[142:143], s[58:59], 0, v[132:133]
	s_mov_b32 m0, s9
	v_lshl_add_u64 v[252:253], s[22:23], 0, v[134:135]
	global_load_lds_dwordx4 v[142:143], off
	v_lshl_add_u64 v[142:143], s[58:59], 0, v[128:129]
	s_add_i32 m0, s9, 0x2000
	v_lshl_add_u64 v[178:179], s[22:23], 0, v[130:131]
	global_load_lds_dwordx4 v[142:143], off
	s_mov_b32 m0, s43
	s_nop 0
	global_load_lds_dwordx4 v[252:253], off
	s_mov_b32 m0, s44
	s_nop 0
	global_load_lds_dwordx4 v[178:179], off
	s_waitcnt vmcnt(8)
	s_waitcnt lgkmcnt(0)
	s_barrier
	s_setprio 1
	v_mfma_f32_16x16x32_bf16 v[142:145], v[0:3], v[60:63], 0
	v_mfma_f32_16x16x32_bf16 v[150:153], v[0:3], v[100:103], 0
	v_mfma_f32_16x16x32_bf16 v[158:161], v[0:3], v[112:115], 0
	v_mfma_f32_16x16x32_bf16 v[0:3], v[0:3], v[120:123], 0
	v_mfma_f32_16x16x32_bf16 v[142:145], v[4:7], v[96:99], v[142:145]
	v_mfma_f32_16x16x32_bf16 v[150:153], v[4:7], v[108:111], v[150:153]
	v_mfma_f32_16x16x32_bf16 v[158:161], v[4:7], v[116:119], v[158:161]
	v_mfma_f32_16x16x32_bf16 v[0:3], v[4:7], v[124:127], v[0:3]
	v_mfma_f32_16x16x32_bf16 v[4:7], v[8:11], v[120:123], 0
	v_mfma_f32_16x16x32_bf16 v[146:149], v[8:11], v[60:63], 0
	v_mfma_f32_16x16x32_bf16 v[154:157], v[8:11], v[100:103], 0
	v_mfma_f32_16x16x32_bf16 v[162:165], v[8:11], v[112:115], 0
	v_mfma_f32_16x16x32_bf16 v[4:7], v[12:15], v[124:127], v[4:7]
	v_mfma_f32_16x16x32_bf16 v[146:149], v[12:15], v[96:99], v[146:149]
	v_mfma_f32_16x16x32_bf16 v[154:157], v[12:15], v[108:111], v[154:157]
	v_mfma_f32_16x16x32_bf16 v[162:165], v[12:15], v[116:119], v[162:165]
	v_mfma_f32_16x16x32_bf16 v[8:11], v[16:19], v[60:63], 0
	v_mfma_f32_16x16x32_bf16 v[12:15], v[24:27], v[60:63], 0
	v_mfma_f32_16x16x32_bf16 v[60:63], v[16:19], v[100:103], 0
	v_mfma_f32_16x16x32_bf16 v[166:169], v[20:23], v[108:111], v[60:63]
	v_mfma_f32_16x16x32_bf16 v[60:63], v[24:27], v[100:103], 0
	v_mfma_f32_16x16x32_bf16 v[170:173], v[28:31], v[108:111], v[60:63]
	v_mfma_f32_16x16x32_bf16 v[60:63], v[16:19], v[112:115], 0
	v_mfma_f32_16x16x32_bf16 v[16:19], v[16:19], v[120:123], 0
	v_mfma_f32_16x16x32_bf16 v[8:11], v[20:23], v[96:99], v[8:11]
	v_mfma_f32_16x16x32_bf16 v[12:15], v[28:31], v[96:99], v[12:15]
	v_mfma_f32_16x16x32_bf16 v[182:185], v[20:23], v[116:119], v[60:63]
	v_mfma_f32_16x16x32_bf16 v[60:63], v[24:27], v[112:115], 0
	s_setprio 2
	s_barrier
	v_mfma_f32_16x16x32_bf16 v[190:193], v[20:23], v[124:127], v[16:19]
	v_mfma_f32_16x16x32_bf16 v[16:19], v[24:27], v[120:123], 0
	v_mfma_f32_16x16x32_bf16 v[186:189], v[28:31], v[116:119], v[60:63]
	v_mfma_f32_16x16x32_bf16 v[194:197], v[28:31], v[124:127], v[16:19]
	s_setprio 0
	s_add_i32 s9, 0, 0x18000
	s_nop 2
	v_add_u32_e32 v16, s9, v139
	s_add_i32 s11, 0, 0x1c000
	ds_read_b128 v[24:27], v16
	ds_read_b128 v[28:31], v16 offset:1024
	ds_read_b128 v[60:63], v16 offset:2048
	ds_read_b128 v[198:201], v16 offset:3072
	v_add_u32_e32 v16, s11, v139
	ds_read_b128 v[202:205], v16
	ds_read_b128 v[206:209], v16 offset:1024
	ds_read_b128 v[210:213], v16 offset:2048
	ds_read_b128 v[220:223], v16 offset:3072
	s_mov_b32 m0, s50
	v_lshl_add_u64 v[96:97], s[20:21], 0, v[134:135]
	ds_read_b128 v[16:19], v140 offset:32768
	ds_read_b128 v[20:23], v140 offset:33792
	ds_read_b128 v[108:111], v140 offset:34816
	ds_read_b128 v[228:231], v140 offset:35840
	ds_read_b128 v[232:235], v140 offset:36864
	ds_read_b128 v[236:239], v140 offset:37888
	ds_read_b128 v[240:243], v140 offset:38912
	ds_read_b128 v[244:247], v140 offset:39936
	global_load_lds_dwordx4 v[96:97], off
	v_lshl_add_u64 v[96:97], s[20:21], 0, v[130:131]
	s_mov_b32 m0, s51
	s_nop 0
	global_load_lds_dwordx4 v[96:97], off
	s_waitcnt vmcnt(8)
	s_waitcnt lgkmcnt(0)
	s_barrier
	s_setprio 1
	v_mfma_f32_16x16x32_bf16 v[64:67], v[24:27], v[16:19], v[64:67]
	v_mfma_f32_16x16x32_bf16 v[120:123], v[28:31], v[20:23], v[64:67]
	v_mfma_f32_16x16x32_bf16 v[64:67], v[60:63], v[16:19], v[68:71]
	v_mfma_f32_16x16x32_bf16 v[124:127], v[198:201], v[20:23], v[64:67]
	v_mfma_f32_16x16x32_bf16 v[64:67], v[24:27], v[108:111], v[72:75]
	v_mfma_f32_16x16x32_bf16 v[96:99], v[28:31], v[228:231], v[64:67]
	v_mfma_f32_16x16x32_bf16 v[64:67], v[60:63], v[108:111], v[76:79]
	v_mfma_f32_16x16x32_bf16 v[100:103], v[198:201], v[228:231], v[64:67]
	v_mfma_f32_16x16x32_bf16 v[64:67], v[24:27], v[232:235], v[80:83]
	v_mfma_f32_16x16x32_bf16 v[80:83], v[28:31], v[236:239], v[64:67]
	v_mfma_f32_16x16x32_bf16 v[64:67], v[60:63], v[232:235], v[84:87]
	v_mfma_f32_16x16x32_bf16 v[84:87], v[198:201], v[236:239], v[64:67]
	v_mfma_f32_16x16x32_bf16 v[64:67], v[24:27], v[240:243], v[88:91]
	v_mfma_f32_16x16x32_bf16 v[68:71], v[60:63], v[240:243], v[92:95]
	v_mfma_f32_16x16x32_bf16 v[64:67], v[28:31], v[244:247], v[64:67]
	v_mfma_f32_16x16x32_bf16 v[68:71], v[198:201], v[244:247], v[68:71]
	v_mfma_f32_16x16x32_bf16 v[72:75], v[202:205], v[16:19], v[104:107]
	v_mfma_f32_16x16x32_bf16 v[16:19], v[210:213], v[16:19], v[32:35]
	v_mfma_f32_16x16x32_bf16 v[116:119], v[220:223], v[20:23], v[16:19]
	v_mfma_f32_16x16x32_bf16 v[16:19], v[202:205], v[108:111], v[36:39]
	v_mfma_f32_16x16x32_bf16 v[104:107], v[206:209], v[228:231], v[16:19]
	v_mfma_f32_16x16x32_bf16 v[16:19], v[210:213], v[108:111], v[40:43]
	v_mfma_f32_16x16x32_bf16 v[108:111], v[220:223], v[228:231], v[16:19]
	v_mfma_f32_16x16x32_bf16 v[16:19], v[202:205], v[232:235], v[44:47]
	v_mfma_f32_16x16x32_bf16 v[88:91], v[206:209], v[236:239], v[16:19]
	v_mfma_f32_16x16x32_bf16 v[16:19], v[210:213], v[232:235], v[48:51]
	v_mfma_f32_16x16x32_bf16 v[92:95], v[220:223], v[236:239], v[16:19]
	v_mfma_f32_16x16x32_bf16 v[16:19], v[202:205], v[240:243], v[52:55]
	s_setprio 2
	s_barrier
	v_mfma_f32_16x16x32_bf16 v[112:115], v[206:209], v[20:23], v[72:75]
	v_mfma_f32_16x16x32_bf16 v[72:75], v[206:209], v[244:247], v[16:19]
	v_mfma_f32_16x16x32_bf16 v[16:19], v[210:213], v[240:243], v[56:59]
	v_mfma_f32_16x16x32_bf16 v[76:79], v[220:223], v[244:247], v[16:19]
	s_setprio 0
	s_add_i32 s9, s9, s29
	s_nop 3
	v_lshl_add_u64 v[16:17], v[136:137], 0, s[34:35]
	s_mov_b32 m0, s9
	ds_read_b128 v[40:43], v140 offset:49152
	ds_read_b128 v[44:47], v140 offset:50176
	ds_read_b128 v[228:231], v140 offset:51200
	ds_read_b128 v[232:235], v140 offset:52224
	ds_read_b128 v[236:239], v140 offset:53248
	ds_read_b128 v[240:243], v140 offset:54272
	ds_read_b128 v[244:247], v140 offset:55296
	ds_read_b128 v[248:251], v140 offset:56320
	global_load_lds_dwordx4 v[16:17], off
	s_add_i32 m0, s9, 0x2000
	s_add_u32 s18, s18, 0x8080
	v_lshl_add_u64 v[16:17], v[226:227], 0, s[34:35]
	s_addc_u32 s19, s19, 0
	s_add_i32 s9, s11, s29
	global_load_lds_dwordx4 v[16:17], off
	v_lshl_add_u64 v[16:17], s[18:19], 0, v[132:133]
	s_mov_b32 m0, s9
	s_nop 0
	global_load_lds_dwordx4 v[16:17], off
	v_lshl_add_u64 v[16:17], s[18:19], 0, v[128:129]
	s_add_i32 m0, s9, 0x2000
	s_nop 0
	global_load_lds_dwordx4 v[16:17], off
	v_lshl_add_u64 v[16:17], v[252:253], 0, s[34:35]
	s_mov_b32 m0, s52
	s_nop 0
	global_load_lds_dwordx4 v[16:17], off
	v_lshl_add_u64 v[16:17], v[178:179], 0, s[34:35]
	s_mov_b32 m0, s53
	s_nop 0
	global_load_lds_dwordx4 v[16:17], off
	s_waitcnt vmcnt(8)
	s_waitcnt lgkmcnt(0)
	s_barrier
	s_setprio 1
	v_mfma_f32_16x16x32_bf16 v[16:19], v[24:27], v[40:43], v[142:145]
	v_mfma_f32_16x16x32_bf16 v[48:51], v[28:31], v[44:47], v[16:19]
	v_mfma_f32_16x16x32_bf16 v[16:19], v[60:63], v[40:43], v[146:149]
	v_mfma_f32_16x16x32_bf16 v[52:55], v[198:201], v[44:47], v[16:19]
	v_mfma_f32_16x16x32_bf16 v[16:19], v[24:27], v[228:231], v[150:153]
	v_mfma_f32_16x16x32_bf16 v[32:35], v[28:31], v[232:235], v[16:19]
	v_mfma_f32_16x16x32_bf16 v[16:19], v[60:63], v[228:231], v[154:157]
	v_mfma_f32_16x16x32_bf16 v[36:39], v[198:201], v[232:235], v[16:19]
	v_mfma_f32_16x16x32_bf16 v[16:19], v[24:27], v[236:239], v[158:161]
	v_mfma_f32_16x16x32_bf16 v[20:23], v[60:63], v[236:239], v[162:165]
	v_mfma_f32_16x16x32_bf16 v[0:3], v[24:27], v[244:247], v[0:3]
	v_mfma_f32_16x16x32_bf16 v[4:7], v[60:63], v[244:247], v[4:7]
	v_mfma_f32_16x16x32_bf16 v[16:19], v[28:31], v[240:243], v[16:19]
	v_mfma_f32_16x16x32_bf16 v[20:23], v[198:201], v[240:243], v[20:23]
	v_mfma_f32_16x16x32_bf16 v[0:3], v[28:31], v[248:251], v[0:3]
	v_mfma_f32_16x16x32_bf16 v[4:7], v[198:201], v[248:251], v[4:7]
	v_mfma_f32_16x16x32_bf16 v[8:11], v[202:205], v[40:43], v[8:11]
	v_mfma_f32_16x16x32_bf16 v[56:59], v[206:209], v[44:47], v[8:11]
	v_mfma_f32_16x16x32_bf16 v[8:11], v[210:213], v[40:43], v[12:15]
	v_mfma_f32_16x16x32_bf16 v[60:63], v[220:223], v[44:47], v[8:11]
	v_mfma_f32_16x16x32_bf16 v[8:11], v[202:205], v[228:231], v[166:169]
	v_mfma_f32_16x16x32_bf16 v[40:43], v[206:209], v[232:235], v[8:11]
	v_mfma_f32_16x16x32_bf16 v[8:11], v[210:213], v[228:231], v[170:173]
	v_mfma_f32_16x16x32_bf16 v[44:47], v[220:223], v[232:235], v[8:11]
	v_mfma_f32_16x16x32_bf16 v[8:11], v[202:205], v[236:239], v[182:185]
	v_mfma_f32_16x16x32_bf16 v[24:27], v[206:209], v[240:243], v[8:11]
	v_mfma_f32_16x16x32_bf16 v[8:11], v[210:213], v[236:239], v[186:189]
	v_mfma_f32_16x16x32_bf16 v[28:31], v[220:223], v[240:243], v[8:11]
	s_setprio 2
	s_barrier
	v_mfma_f32_16x16x32_bf16 v[8:11], v[202:205], v[244:247], v[190:193]
	v_mfma_f32_16x16x32_bf16 v[12:15], v[210:213], v[244:247], v[194:197]
	v_mfma_f32_16x16x32_bf16 v[8:11], v[206:209], v[248:251], v[8:11]
	v_mfma_f32_16x16x32_bf16 v[12:15], v[220:223], v[248:251], v[12:15]
	s_setprio 0
	s_andn2_b64 vcc, exec, s[4:5]
	s_cbranch_vccnz .LBB0_428
	s_barrier

.LBB0_634:
	s_add_u32 s22, s20, 0xfffc0080
	s_addc_u32 s23, s21, -1
	s_add_i32 s64, 0, 0x10000
	s_cmp_eq_u32 s63, 12
	s_cselect_b32 s25, s13, s23
	s_cselect_b32 s24, s19, s22
	s_cselect_b32 s23, s11, s62
	s_cselect_b32 s22, s60, s61
	s_add_i32 s68, 0, 0x14000
	s_waitcnt vmcnt(0) lgkmcnt(0)
	v_add_u32_e32 v140, s64, v175
	v_add_u32_e32 v170, s68, v175
	ds_read_b128 v[128:131], v140
	ds_read_b128 v[132:135], v140 offset:1024
	ds_read_b128 v[136:139], v140 offset:2048
	ds_read_b128 v[140:143], v140 offset:3072
	ds_read_b128 v[144:147], v170
	ds_read_b128 v[162:165], v170 offset:1024
	ds_read_b128 v[166:169], v170 offset:2048
	ds_read_b128 v[170:173], v170 offset:3072
	v_lshl_add_u64 v[220:221], s[20:21], 0, v[160:161]
	s_add_i32 m0, s50, 0xc000
	ds_read_b128 v[186:189], v185
	ds_read_b128 v[190:193], v185 offset:1024
	ds_read_b128 v[194:197], v185 offset:2048
	ds_read_b128 v[198:201], v185 offset:3072
	ds_read_b128 v[202:205], v185 offset:4096
	ds_read_b128 v[206:209], v185 offset:5120
	ds_read_b128 v[210:213], v185 offset:6144
	ds_read_b128 v[228:231], v185 offset:7168
	global_load_lds_dwordx4 v[220:221], off
	v_lshl_add_u64 v[220:221], s[20:21], 0, v[158:159]
	s_add_i32 m0, s50, 0xe000
	s_nop 0
	global_load_lds_dwordx4 v[220:221], off
	s_waitcnt vmcnt(8)
	s_waitcnt lgkmcnt(0)
	s_barrier
	s_setprio 1
	v_mfma_f32_16x16x32_bf16 v[124:127], v[128:131], v[186:189], v[124:127]
	v_mfma_f32_16x16x32_bf16 v[120:123], v[136:139], v[186:189], v[120:123]
	v_mfma_f32_16x16x32_bf16 v[108:111], v[128:131], v[194:197], v[108:111]
	v_mfma_f32_16x16x32_bf16 v[104:107], v[136:139], v[194:197], v[104:107]
	v_mfma_f32_16x16x32_bf16 v[92:95], v[128:131], v[202:205], v[92:95]
	v_mfma_f32_16x16x32_bf16 v[88:91], v[136:139], v[202:205], v[88:91]
	v_mfma_f32_16x16x32_bf16 v[76:79], v[128:131], v[210:213], v[76:79]
	v_mfma_f32_16x16x32_bf16 v[72:75], v[136:139], v[210:213], v[72:75]
	v_mfma_f32_16x16x32_bf16 v[124:127], v[132:135], v[190:193], v[124:127]
	v_mfma_f32_16x16x32_bf16 v[120:123], v[140:143], v[190:193], v[120:123]
	v_mfma_f32_16x16x32_bf16 v[108:111], v[132:135], v[198:201], v[108:111]
	v_mfma_f32_16x16x32_bf16 v[104:107], v[140:143], v[198:201], v[104:107]
	v_mfma_f32_16x16x32_bf16 v[92:95], v[132:135], v[206:209], v[92:95]
	v_mfma_f32_16x16x32_bf16 v[88:91], v[140:143], v[206:209], v[88:91]
	v_mfma_f32_16x16x32_bf16 v[76:79], v[132:135], v[228:231], v[76:79]
	v_mfma_f32_16x16x32_bf16 v[72:75], v[140:143], v[228:231], v[72:75]
	v_mfma_f32_16x16x32_bf16 v[116:119], v[144:147], v[186:189], v[116:119]
	v_mfma_f32_16x16x32_bf16 v[112:115], v[166:169], v[186:189], v[112:115]
	v_mfma_f32_16x16x32_bf16 v[100:103], v[144:147], v[194:197], v[100:103]
	v_mfma_f32_16x16x32_bf16 v[96:99], v[166:169], v[194:197], v[96:99]
	v_mfma_f32_16x16x32_bf16 v[84:87], v[144:147], v[202:205], v[84:87]
	v_mfma_f32_16x16x32_bf16 v[80:83], v[166:169], v[202:205], v[80:83]
	v_mfma_f32_16x16x32_bf16 v[68:71], v[144:147], v[210:213], v[68:71]
	v_mfma_f32_16x16x32_bf16 v[64:67], v[166:169], v[210:213], v[64:67]
	v_mfma_f32_16x16x32_bf16 v[116:119], v[162:165], v[190:193], v[116:119]
	v_mfma_f32_16x16x32_bf16 v[112:115], v[170:173], v[190:193], v[112:115]
	v_mfma_f32_16x16x32_bf16 v[100:103], v[162:165], v[198:201], v[100:103]
	v_mfma_f32_16x16x32_bf16 v[96:99], v[170:173], v[198:201], v[96:99]
	s_setprio 2
	s_barrier
	v_mfma_f32_16x16x32_bf16 v[84:87], v[162:165], v[206:209], v[84:87]
	v_mfma_f32_16x16x32_bf16 v[80:83], v[170:173], v[206:209], v[80:83]
	v_mfma_f32_16x16x32_bf16 v[68:71], v[162:165], v[228:231], v[68:71]
	v_mfma_f32_16x16x32_bf16 v[64:67], v[170:173], v[228:231], v[64:67]
	s_setprio 0
	s_add_i32 s64, s64, s46
	v_lshl_add_u64 v[220:221], s[22:23], 0, v[152:153]
	s_mov_b32 m0, s64
	ds_read_b128 v[186:189], v185 offset:16384
	ds_read_b128 v[190:193], v185 offset:17408
	ds_read_b128 v[194:197], v185 offset:18432
	ds_read_b128 v[198:201], v185 offset:19456
	ds_read_b128 v[202:205], v185 offset:20480
	ds_read_b128 v[206:209], v185 offset:21504
	ds_read_b128 v[210:213], v185 offset:22528
	ds_read_b128 v[228:231], v185 offset:23552
	global_load_lds_dwordx4 v[220:221], off
	s_add_i32 m0, s64, 0x2000
	s_add_u32 s64, s22, 0x40000
	v_lshl_add_u64 v[222:223], s[22:23], 0, v[148:149]
	s_addc_u32 s65, s23, 0
	s_add_i32 s68, s68, s46
	global_load_lds_dwordx4 v[222:223], off
	v_lshl_add_u64 v[226:227], s[64:65], 0, v[152:153]
	s_mov_b32 m0, s68
	v_lshl_add_u64 v[232:233], s[24:25], 0, v[150:151]
	global_load_lds_dwordx4 v[226:227], off
	v_lshl_add_u64 v[226:227], s[64:65], 0, v[148:149]
	s_add_i32 m0, s68, 0x2000
	s_nop 0
	global_load_lds_dwordx4 v[226:227], off
	v_lshl_add_u64 v[226:227], s[24:25], 0, v[154:155]
	s_mov_b32 m0, s50
	s_nop 0
	global_load_lds_dwordx4 v[226:227], off
	s_mov_b32 m0, s51
	s_nop 0
	global_load_lds_dwordx4 v[232:233], off
	s_waitcnt vmcnt(8)
	s_waitcnt lgkmcnt(0)
	s_barrier
	s_setprio 1
	v_mfma_f32_16x16x32_bf16 v[60:63], v[128:131], v[186:189], v[60:63]
	v_mfma_f32_16x16x32_bf16 v[56:59], v[136:139], v[186:189], v[56:59]
	v_mfma_f32_16x16x32_bf16 v[48:51], v[128:131], v[194:197], v[48:51]
	v_mfma_f32_16x16x32_bf16 v[40:43], v[136:139], v[194:197], v[40:43]
	v_mfma_f32_16x16x32_bf16 v[32:35], v[128:131], v[202:205], v[32:35]
	v_mfma_f32_16x16x32_bf16 v[24:27], v[136:139], v[202:205], v[24:27]
	v_mfma_f32_16x16x32_bf16 v[16:19], v[128:131], v[210:213], v[16:19]
	v_mfma_f32_16x16x32_bf16 v[8:11], v[136:139], v[210:213], v[8:11]
	v_mfma_f32_16x16x32_bf16 v[60:63], v[132:135], v[190:193], v[60:63]
	v_mfma_f32_16x16x32_bf16 v[56:59], v[140:143], v[190:193], v[56:59]
	v_mfma_f32_16x16x32_bf16 v[48:51], v[132:135], v[198:201], v[48:51]
	v_mfma_f32_16x16x32_bf16 v[40:43], v[140:143], v[198:201], v[40:43]
	v_mfma_f32_16x16x32_bf16 v[32:35], v[132:135], v[206:209], v[32:35]
	v_mfma_f32_16x16x32_bf16 v[24:27], v[140:143], v[206:209], v[24:27]
	v_mfma_f32_16x16x32_bf16 v[16:19], v[132:135], v[228:231], v[16:19]
	v_mfma_f32_16x16x32_bf16 v[8:11], v[140:143], v[228:231], v[8:11]
	v_mfma_f32_16x16x32_bf16 v[52:55], v[144:147], v[186:189], v[52:55]
	v_mfma_f32_16x16x32_bf16 v[44:47], v[166:169], v[186:189], v[44:47]
	v_mfma_f32_16x16x32_bf16 v[36:39], v[144:147], v[194:197], v[36:39]
	v_mfma_f32_16x16x32_bf16 v[28:31], v[166:169], v[194:197], v[28:31]
	v_mfma_f32_16x16x32_bf16 v[20:23], v[144:147], v[202:205], v[20:23]
	v_mfma_f32_16x16x32_bf16 v[12:15], v[166:169], v[202:205], v[12:15]
	v_mfma_f32_16x16x32_bf16 v[4:7], v[144:147], v[210:213], v[4:7]
	v_mfma_f32_16x16x32_bf16 v[0:3], v[166:169], v[210:213], v[0:3]
	v_mfma_f32_16x16x32_bf16 v[52:55], v[162:165], v[190:193], v[52:55]
	v_mfma_f32_16x16x32_bf16 v[44:47], v[170:173], v[190:193], v[44:47]
	v_mfma_f32_16x16x32_bf16 v[36:39], v[162:165], v[198:201], v[36:39]
	v_mfma_f32_16x16x32_bf16 v[28:31], v[170:173], v[198:201], v[28:31]
	s_setprio 2
	s_barrier
	v_mfma_f32_16x16x32_bf16 v[20:23], v[162:165], v[206:209], v[20:23]
	v_mfma_f32_16x16x32_bf16 v[12:15], v[170:173], v[206:209], v[12:15]
	v_mfma_f32_16x16x32_bf16 v[4:7], v[162:165], v[228:231], v[4:7]
	v_mfma_f32_16x16x32_bf16 v[0:3], v[170:173], v[228:231], v[0:3]
	s_setprio 0
	s_add_i32 s64, 0, 0x18000
	s_add_i32 s65, 0, 0x1c000
	v_add_u32_e32 v140, s64, v175
	v_add_u32_e32 v170, s65, v175
	ds_read_b128 v[128:131], v140
	ds_read_b128 v[132:135], v140 offset:1024
	ds_read_b128 v[136:139], v140 offset:2048
	ds_read_b128 v[140:143], v140 offset:3072
	ds_read_b128 v[144:147], v170
	ds_read_b128 v[162:165], v170 offset:1024
	ds_read_b128 v[166:169], v170 offset:2048
	ds_read_b128 v[170:173], v170 offset:3072
	s_add_u32 s24, s24, 0x40000
	s_addc_u32 s25, s25, 0
	s_mov_b32 m0, s52
	v_lshl_add_u64 v[234:235], s[24:25], 0, v[154:155]
	ds_read_b128 v[186:189], v185 offset:32768
	ds_read_b128 v[190:193], v185 offset:33792
	ds_read_b128 v[194:197], v185 offset:34816
	ds_read_b128 v[198:201], v185 offset:35840
	ds_read_b128 v[202:205], v185 offset:36864
	ds_read_b128 v[206:209], v185 offset:37888
	ds_read_b128 v[210:213], v185 offset:38912
	ds_read_b128 v[228:231], v185 offset:39936
	global_load_lds_dwordx4 v[234:235], off
	v_lshl_add_u64 v[234:235], s[24:25], 0, v[150:151]
	s_mov_b32 m0, s53
	s_nop 0
	global_load_lds_dwordx4 v[234:235], off
	s_waitcnt vmcnt(8)
	s_waitcnt lgkmcnt(0)
	s_barrier
	s_setprio 1
	v_mfma_f32_16x16x32_bf16 v[124:127], v[128:131], v[186:189], v[124:127]
	v_mfma_f32_16x16x32_bf16 v[120:123], v[136:139], v[186:189], v[120:123]
	v_mfma_f32_16x16x32_bf16 v[108:111], v[128:131], v[194:197], v[108:111]
	v_mfma_f32_16x16x32_bf16 v[104:107], v[136:139], v[194:197], v[104:107]
	v_mfma_f32_16x16x32_bf16 v[92:95], v[128:131], v[202:205], v[92:95]
	v_mfma_f32_16x16x32_bf16 v[88:91], v[136:139], v[202:205], v[88:91]
	v_mfma_f32_16x16x32_bf16 v[76:79], v[128:131], v[210:213], v[76:79]
	v_mfma_f32_16x16x32_bf16 v[72:75], v[136:139], v[210:213], v[72:75]
	v_mfma_f32_16x16x32_bf16 v[124:127], v[132:135], v[190:193], v[124:127]
	v_mfma_f32_16x16x32_bf16 v[120:123], v[140:143], v[190:193], v[120:123]
	v_mfma_f32_16x16x32_bf16 v[108:111], v[132:135], v[198:201], v[108:111]
	v_mfma_f32_16x16x32_bf16 v[104:107], v[140:143], v[198:201], v[104:107]
	v_mfma_f32_16x16x32_bf16 v[92:95], v[132:135], v[206:209], v[92:95]
	v_mfma_f32_16x16x32_bf16 v[88:91], v[140:143], v[206:209], v[88:91]
	v_mfma_f32_16x16x32_bf16 v[76:79], v[132:135], v[228:231], v[76:79]
	v_mfma_f32_16x16x32_bf16 v[72:75], v[140:143], v[228:231], v[72:75]
	v_mfma_f32_16x16x32_bf16 v[116:119], v[144:147], v[186:189], v[116:119]
	v_mfma_f32_16x16x32_bf16 v[112:115], v[166:169], v[186:189], v[112:115]
	v_mfma_f32_16x16x32_bf16 v[100:103], v[144:147], v[194:197], v[100:103]
	v_mfma_f32_16x16x32_bf16 v[96:99], v[166:169], v[194:197], v[96:99]
	v_mfma_f32_16x16x32_bf16 v[84:87], v[144:147], v[202:205], v[84:87]
	v_mfma_f32_16x16x32_bf16 v[80:83], v[166:169], v[202:205], v[80:83]
	v_mfma_f32_16x16x32_bf16 v[68:71], v[144:147], v[210:213], v[68:71]
	v_mfma_f32_16x16x32_bf16 v[64:67], v[166:169], v[210:213], v[64:67]
	v_mfma_f32_16x16x32_bf16 v[116:119], v[162:165], v[190:193], v[116:119]
	v_mfma_f32_16x16x32_bf16 v[112:115], v[170:173], v[190:193], v[112:115]
	v_mfma_f32_16x16x32_bf16 v[100:103], v[162:165], v[198:201], v[100:103]
	v_mfma_f32_16x16x32_bf16 v[96:99], v[170:173], v[198:201], v[96:99]
	s_setprio 2
	s_barrier
	v_mfma_f32_16x16x32_bf16 v[84:87], v[162:165], v[206:209], v[84:87]
	v_mfma_f32_16x16x32_bf16 v[80:83], v[170:173], v[206:209], v[80:83]
	v_mfma_f32_16x16x32_bf16 v[68:71], v[162:165], v[228:231], v[68:71]
	v_mfma_f32_16x16x32_bf16 v[64:67], v[170:173], v[228:231], v[64:67]
	s_setprio 0
	s_add_i32 s24, s64, s46
	v_lshl_add_u64 v[220:221], v[220:221], 0, s[34:35]
	s_mov_b32 m0, s24
	ds_read_b128 v[186:189], v185 offset:49152
	ds_read_b128 v[190:193], v185 offset:50176
	ds_read_b128 v[194:197], v185 offset:51200
	ds_read_b128 v[198:201], v185 offset:52224
	ds_read_b128 v[202:205], v185 offset:53248
	ds_read_b128 v[206:209], v185 offset:54272
	ds_read_b128 v[210:213], v185 offset:55296
	ds_read_b128 v[228:231], v185 offset:56320
	global_load_lds_dwordx4 v[220:221], off
	s_add_i32 m0, s24, 0x2000
	s_add_u32 s22, s22, 0x40080
	v_lshl_add_u64 v[220:221], v[222:223], 0, s[34:35]
	s_addc_u32 s23, s23, 0
	s_add_i32 s24, s65, s46
	global_load_lds_dwordx4 v[220:221], off
	v_lshl_add_u64 v[220:221], s[22:23], 0, v[152:153]
	s_mov_b32 m0, s24
	s_nop 0
	global_load_lds_dwordx4 v[220:221], off
	v_lshl_add_u64 v[220:221], s[22:23], 0, v[148:149]
	s_add_i32 m0, s24, 0x2000
	s_nop 0
	global_load_lds_dwordx4 v[220:221], off
	v_lshl_add_u64 v[220:221], v[226:227], 0, s[34:35]
	s_mov_b32 m0, s56
	s_nop 0
	global_load_lds_dwordx4 v[220:221], off
	v_lshl_add_u64 v[220:221], v[232:233], 0, s[34:35]
	s_mov_b32 m0, s57
	s_nop 0
	global_load_lds_dwordx4 v[220:221], off
	s_waitcnt vmcnt(8)
	s_waitcnt lgkmcnt(0)
	s_barrier
	s_setprio 1
	v_mfma_f32_16x16x32_bf16 v[60:63], v[128:131], v[186:189], v[60:63]
	v_mfma_f32_16x16x32_bf16 v[56:59], v[136:139], v[186:189], v[56:59]
	v_mfma_f32_16x16x32_bf16 v[48:51], v[128:131], v[194:197], v[48:51]
	v_mfma_f32_16x16x32_bf16 v[40:43], v[136:139], v[194:197], v[40:43]
	v_mfma_f32_16x16x32_bf16 v[32:35], v[128:131], v[202:205], v[32:35]
	v_mfma_f32_16x16x32_bf16 v[24:27], v[136:139], v[202:205], v[24:27]
	v_mfma_f32_16x16x32_bf16 v[16:19], v[128:131], v[210:213], v[16:19]
	v_mfma_f32_16x16x32_bf16 v[8:11], v[136:139], v[210:213], v[8:11]
	v_mfma_f32_16x16x32_bf16 v[60:63], v[132:135], v[190:193], v[60:63]
	v_mfma_f32_16x16x32_bf16 v[56:59], v[140:143], v[190:193], v[56:59]
	v_mfma_f32_16x16x32_bf16 v[48:51], v[132:135], v[198:201], v[48:51]
	v_mfma_f32_16x16x32_bf16 v[40:43], v[140:143], v[198:201], v[40:43]
	v_mfma_f32_16x16x32_bf16 v[32:35], v[132:135], v[206:209], v[32:35]
	v_mfma_f32_16x16x32_bf16 v[24:27], v[140:143], v[206:209], v[24:27]
	v_mfma_f32_16x16x32_bf16 v[16:19], v[132:135], v[228:231], v[16:19]
	v_mfma_f32_16x16x32_bf16 v[8:11], v[140:143], v[228:231], v[8:11]
	v_mfma_f32_16x16x32_bf16 v[52:55], v[144:147], v[186:189], v[52:55]
	v_mfma_f32_16x16x32_bf16 v[44:47], v[166:169], v[186:189], v[44:47]
	v_mfma_f32_16x16x32_bf16 v[36:39], v[144:147], v[194:197], v[36:39]
	v_mfma_f32_16x16x32_bf16 v[28:31], v[166:169], v[194:197], v[28:31]
	v_mfma_f32_16x16x32_bf16 v[20:23], v[144:147], v[202:205], v[20:23]
	v_mfma_f32_16x16x32_bf16 v[12:15], v[166:169], v[202:205], v[12:15]
	v_mfma_f32_16x16x32_bf16 v[4:7], v[144:147], v[210:213], v[4:7]
	v_mfma_f32_16x16x32_bf16 v[0:3], v[166:169], v[210:213], v[0:3]
	v_mfma_f32_16x16x32_bf16 v[52:55], v[162:165], v[190:193], v[52:55]
	v_mfma_f32_16x16x32_bf16 v[44:47], v[170:173], v[190:193], v[44:47]
	v_mfma_f32_16x16x32_bf16 v[36:39], v[162:165], v[198:201], v[36:39]
	v_mfma_f32_16x16x32_bf16 v[28:31], v[170:173], v[198:201], v[28:31]
	s_setprio 2
	s_barrier
	v_mfma_f32_16x16x32_bf16 v[20:23], v[162:165], v[206:209], v[20:23]
	v_mfma_f32_16x16x32_bf16 v[12:15], v[170:173], v[206:209], v[12:15]
	v_mfma_f32_16x16x32_bf16 v[4:7], v[162:165], v[228:231], v[4:7]
	v_mfma_f32_16x16x32_bf16 v[0:3], v[170:173], v[228:231], v[0:3]
	s_setprio 0
	s_add_i32 s63, s63, 2
	s_add_u32 s61, s61, 0x100
	s_addc_u32 s62, s62, 0
	s_add_u32 s20, s20, 0x100
	s_addc_u32 s21, s21, 0
	s_cmp_gt_u32 s63, 13
	s_cbranch_scc0 .LBB0_634
	s_and_b64 vcc, exec, s[8:9]
	s_cbranch_vccz .LBB0_637
	s_barrier

.LBB0_769:
	s_add_u32 s40, s8, 0x100
	s_addc_u32 s41, s9, 0
	s_add_i32 s64, 0, 0x10000
	s_cmp_eq_u32 s92, 40
	s_cselect_b32 s53, s1, s41
	s_cselect_b32 s52, s0, s40
	s_cselect_b32 s51, s39, s55
	s_cselect_b32 s50, s38, s44
	s_add_i32 s65, 0, 0x14000
	v_add_u32_e32 v140, s64, v228
	v_add_u32_e32 v156, s65, v228
	ds_read_b128 v[128:131], v140
	ds_read_b128 v[132:135], v140 offset:1024
	ds_read_b128 v[136:139], v140 offset:2048
	ds_read_b128 v[140:143], v140 offset:3072
	ds_read_b128 v[144:147], v156
	ds_read_b128 v[148:151], v156 offset:1024
	ds_read_b128 v[152:155], v156 offset:2048
	ds_read_b128 v[156:159], v156 offset:3072
	v_lshl_add_u64 v[178:179], s[8:9], 0, v[184:185]
	s_add_i32 m0, s62, 0xc000
	ds_read_b128 v[160:163], v231
	ds_read_b128 v[164:167], v231 offset:1024
	ds_read_b128 v[186:189], v231 offset:2048
	ds_read_b128 v[190:193], v231 offset:3072
	ds_read_b128 v[194:197], v231 offset:4096
	ds_read_b128 v[198:201], v231 offset:5120
	ds_read_b128 v[202:205], v231 offset:6144
	ds_read_b128 v[206:209], v231 offset:7168
	global_load_lds_dwordx4 v[178:179], off
	v_lshl_add_u64 v[178:179], s[8:9], 0, v[182:183]
	s_add_i32 m0, s62, 0xe000
	s_nop 0
	global_load_lds_dwordx4 v[178:179], off
	s_waitcnt vmcnt(8)
	s_waitcnt lgkmcnt(0)
	s_barrier
	s_setprio 1
	v_mfma_f32_16x16x32_bf16 v[124:127], v[128:131], v[160:163], v[124:127]
	v_mfma_f32_16x16x32_bf16 v[120:123], v[136:139], v[160:163], v[120:123]
	v_mfma_f32_16x16x32_bf16 v[108:111], v[128:131], v[186:189], v[108:111]
	v_mfma_f32_16x16x32_bf16 v[104:107], v[136:139], v[186:189], v[104:107]
	v_mfma_f32_16x16x32_bf16 v[92:95], v[128:131], v[194:197], v[92:95]
	v_mfma_f32_16x16x32_bf16 v[88:91], v[136:139], v[194:197], v[88:91]
	v_mfma_f32_16x16x32_bf16 v[76:79], v[128:131], v[202:205], v[76:79]
	v_mfma_f32_16x16x32_bf16 v[72:75], v[136:139], v[202:205], v[72:75]
	v_mfma_f32_16x16x32_bf16 v[124:127], v[132:135], v[164:167], v[124:127]
	v_mfma_f32_16x16x32_bf16 v[120:123], v[140:143], v[164:167], v[120:123]
	v_mfma_f32_16x16x32_bf16 v[108:111], v[132:135], v[190:193], v[108:111]
	v_mfma_f32_16x16x32_bf16 v[104:107], v[140:143], v[190:193], v[104:107]
	v_mfma_f32_16x16x32_bf16 v[92:95], v[132:135], v[198:201], v[92:95]
	v_mfma_f32_16x16x32_bf16 v[88:91], v[140:143], v[198:201], v[88:91]
	v_mfma_f32_16x16x32_bf16 v[76:79], v[132:135], v[206:209], v[76:79]
	v_mfma_f32_16x16x32_bf16 v[72:75], v[140:143], v[206:209], v[72:75]
	v_mfma_f32_16x16x32_bf16 v[116:119], v[144:147], v[160:163], v[116:119]
	v_mfma_f32_16x16x32_bf16 v[112:115], v[152:155], v[160:163], v[112:115]
	v_mfma_f32_16x16x32_bf16 v[100:103], v[144:147], v[186:189], v[100:103]
	v_mfma_f32_16x16x32_bf16 v[96:99], v[152:155], v[186:189], v[96:99]
	v_mfma_f32_16x16x32_bf16 v[84:87], v[144:147], v[194:197], v[84:87]
	v_mfma_f32_16x16x32_bf16 v[80:83], v[152:155], v[194:197], v[80:83]
	v_mfma_f32_16x16x32_bf16 v[68:71], v[144:147], v[202:205], v[68:71]
	v_mfma_f32_16x16x32_bf16 v[64:67], v[152:155], v[202:205], v[64:67]
	v_mfma_f32_16x16x32_bf16 v[116:119], v[148:151], v[164:167], v[116:119]
	v_mfma_f32_16x16x32_bf16 v[112:115], v[156:159], v[164:167], v[112:115]
	v_mfma_f32_16x16x32_bf16 v[100:103], v[148:151], v[190:193], v[100:103]
	v_mfma_f32_16x16x32_bf16 v[96:99], v[156:159], v[190:193], v[96:99]
	s_setprio 2
	s_barrier
	v_mfma_f32_16x16x32_bf16 v[84:87], v[148:151], v[198:201], v[84:87]
	v_mfma_f32_16x16x32_bf16 v[80:83], v[156:159], v[198:201], v[80:83]
	v_mfma_f32_16x16x32_bf16 v[68:71], v[148:151], v[206:209], v[68:71]
	v_mfma_f32_16x16x32_bf16 v[64:67], v[156:159], v[206:209], v[64:67]
	s_setprio 0
	s_add_i32 s8, s64, s37
	v_lshl_add_u64 v[178:179], s[50:51], 0, v[170:171]
	s_mov_b32 m0, s8
	ds_read_b128 v[160:163], v231 offset:16384
	ds_read_b128 v[164:167], v231 offset:17408
	ds_read_b128 v[186:189], v231 offset:18432
	ds_read_b128 v[190:193], v231 offset:19456
	ds_read_b128 v[194:197], v231 offset:20480
	ds_read_b128 v[198:201], v231 offset:21504
	ds_read_b128 v[202:205], v231 offset:22528
	ds_read_b128 v[206:209], v231 offset:23552
	global_load_lds_dwordx4 v[178:179], off
	s_add_i32 m0, s8, 0x2000
	s_add_u32 s8, s50, 0xb0000
	v_lshl_add_u64 v[210:211], s[50:51], 0, v[174:175]
	s_addc_u32 s9, s51, 0
	s_add_i32 s64, s65, s37
	global_load_lds_dwordx4 v[210:211], off
	v_lshl_add_u64 v[212:213], s[8:9], 0, v[170:171]
	s_mov_b32 m0, s64
	v_lshl_add_u64 v[220:221], s[52:53], 0, v[172:173]
	global_load_lds_dwordx4 v[212:213], off
	v_lshl_add_u64 v[212:213], s[8:9], 0, v[174:175]
	s_add_i32 m0, s64, 0x2000
	s_nop 0
	global_load_lds_dwordx4 v[212:213], off
	v_lshl_add_u64 v[212:213], s[52:53], 0, v[168:169]
	s_mov_b32 m0, s62
	s_nop 0
	global_load_lds_dwordx4 v[212:213], off
	s_mov_b32 m0, s63
	s_nop 0
	global_load_lds_dwordx4 v[220:221], off
	s_waitcnt vmcnt(8)
	s_waitcnt lgkmcnt(0)
	s_barrier
	s_setprio 1
	v_mfma_f32_16x16x32_bf16 v[60:63], v[128:131], v[160:163], v[60:63]
	v_mfma_f32_16x16x32_bf16 v[56:59], v[136:139], v[160:163], v[56:59]
	v_mfma_f32_16x16x32_bf16 v[44:47], v[128:131], v[186:189], v[44:47]
	v_mfma_f32_16x16x32_bf16 v[40:43], v[136:139], v[186:189], v[40:43]
	v_mfma_f32_16x16x32_bf16 v[28:31], v[128:131], v[194:197], v[28:31]
	v_mfma_f32_16x16x32_bf16 v[24:27], v[136:139], v[194:197], v[24:27]
	v_mfma_f32_16x16x32_bf16 v[12:15], v[128:131], v[202:205], v[12:15]
	v_mfma_f32_16x16x32_bf16 v[8:11], v[136:139], v[202:205], v[8:11]
	v_mfma_f32_16x16x32_bf16 v[60:63], v[132:135], v[164:167], v[60:63]
	v_mfma_f32_16x16x32_bf16 v[56:59], v[140:143], v[164:167], v[56:59]
	v_mfma_f32_16x16x32_bf16 v[44:47], v[132:135], v[190:193], v[44:47]
	v_mfma_f32_16x16x32_bf16 v[40:43], v[140:143], v[190:193], v[40:43]
	v_mfma_f32_16x16x32_bf16 v[28:31], v[132:135], v[198:201], v[28:31]
	v_mfma_f32_16x16x32_bf16 v[24:27], v[140:143], v[198:201], v[24:27]
	v_mfma_f32_16x16x32_bf16 v[12:15], v[132:135], v[206:209], v[12:15]
	v_mfma_f32_16x16x32_bf16 v[8:11], v[140:143], v[206:209], v[8:11]
	v_mfma_f32_16x16x32_bf16 v[52:55], v[144:147], v[160:163], v[52:55]
	v_mfma_f32_16x16x32_bf16 v[48:51], v[152:155], v[160:163], v[48:51]
	v_mfma_f32_16x16x32_bf16 v[36:39], v[144:147], v[186:189], v[36:39]
	v_mfma_f32_16x16x32_bf16 v[32:35], v[152:155], v[186:189], v[32:35]
	v_mfma_f32_16x16x32_bf16 v[20:23], v[144:147], v[194:197], v[20:23]
	v_mfma_f32_16x16x32_bf16 v[16:19], v[152:155], v[194:197], v[16:19]
	v_mfma_f32_16x16x32_bf16 v[4:7], v[144:147], v[202:205], v[4:7]
	v_mfma_f32_16x16x32_bf16 v[0:3], v[152:155], v[202:205], v[0:3]
	v_mfma_f32_16x16x32_bf16 v[52:55], v[148:151], v[164:167], v[52:55]
	v_mfma_f32_16x16x32_bf16 v[48:51], v[156:159], v[164:167], v[48:51]
	v_mfma_f32_16x16x32_bf16 v[36:39], v[148:151], v[190:193], v[36:39]
	v_mfma_f32_16x16x32_bf16 v[32:35], v[156:159], v[190:193], v[32:35]
	s_setprio 2
	s_barrier
	v_mfma_f32_16x16x32_bf16 v[20:23], v[148:151], v[198:201], v[20:23]
	v_mfma_f32_16x16x32_bf16 v[16:19], v[156:159], v[198:201], v[16:19]
	v_mfma_f32_16x16x32_bf16 v[4:7], v[148:151], v[206:209], v[4:7]
	v_mfma_f32_16x16x32_bf16 v[0:3], v[156:159], v[206:209], v[0:3]
	s_setprio 0
	s_add_i32 s64, 0, 0x18000
	s_add_i32 s65, 0, 0x1c000
	v_add_u32_e32 v140, s64, v228
	v_add_u32_e32 v156, s65, v228
	ds_read_b128 v[128:131], v140
	ds_read_b128 v[132:135], v140 offset:1024
	ds_read_b128 v[136:139], v140 offset:2048
	ds_read_b128 v[140:143], v140 offset:3072
	ds_read_b128 v[144:147], v156
	ds_read_b128 v[148:151], v156 offset:1024
	ds_read_b128 v[152:155], v156 offset:2048
	ds_read_b128 v[156:159], v156 offset:3072
	s_add_u32 s8, s52, 0xb0000
	s_addc_u32 s9, s53, 0
	s_mov_b32 m0, s68
	v_lshl_add_u64 v[222:223], s[8:9], 0, v[168:169]
	ds_read_b128 v[160:163], v231 offset:32768
	ds_read_b128 v[164:167], v231 offset:33792
	ds_read_b128 v[186:189], v231 offset:34816
	ds_read_b128 v[190:193], v231 offset:35840
	ds_read_b128 v[194:197], v231 offset:36864
	ds_read_b128 v[198:201], v231 offset:37888
	ds_read_b128 v[202:205], v231 offset:38912
	ds_read_b128 v[206:209], v231 offset:39936
	global_load_lds_dwordx4 v[222:223], off
	v_lshl_add_u64 v[222:223], s[8:9], 0, v[172:173]
	s_mov_b32 m0, s69
	s_nop 0
	global_load_lds_dwordx4 v[222:223], off
	s_waitcnt vmcnt(8)
	s_waitcnt lgkmcnt(0)
	s_barrier
	s_setprio 1
	v_mfma_f32_16x16x32_bf16 v[124:127], v[128:131], v[160:163], v[124:127]
	v_mfma_f32_16x16x32_bf16 v[120:123], v[136:139], v[160:163], v[120:123]
	v_mfma_f32_16x16x32_bf16 v[108:111], v[128:131], v[186:189], v[108:111]
	v_mfma_f32_16x16x32_bf16 v[104:107], v[136:139], v[186:189], v[104:107]
	v_mfma_f32_16x16x32_bf16 v[92:95], v[128:131], v[194:197], v[92:95]
	v_mfma_f32_16x16x32_bf16 v[88:91], v[136:139], v[194:197], v[88:91]
	v_mfma_f32_16x16x32_bf16 v[76:79], v[128:131], v[202:205], v[76:79]
	v_mfma_f32_16x16x32_bf16 v[72:75], v[136:139], v[202:205], v[72:75]
	v_mfma_f32_16x16x32_bf16 v[124:127], v[132:135], v[164:167], v[124:127]
	v_mfma_f32_16x16x32_bf16 v[120:123], v[140:143], v[164:167], v[120:123]
	v_mfma_f32_16x16x32_bf16 v[108:111], v[132:135], v[190:193], v[108:111]
	v_mfma_f32_16x16x32_bf16 v[104:107], v[140:143], v[190:193], v[104:107]
	v_mfma_f32_16x16x32_bf16 v[92:95], v[132:135], v[198:201], v[92:95]
	v_mfma_f32_16x16x32_bf16 v[88:91], v[140:143], v[198:201], v[88:91]
	v_mfma_f32_16x16x32_bf16 v[76:79], v[132:135], v[206:209], v[76:79]
	v_mfma_f32_16x16x32_bf16 v[72:75], v[140:143], v[206:209], v[72:75]
	v_mfma_f32_16x16x32_bf16 v[116:119], v[144:147], v[160:163], v[116:119]
	v_mfma_f32_16x16x32_bf16 v[112:115], v[152:155], v[160:163], v[112:115]
	v_mfma_f32_16x16x32_bf16 v[100:103], v[144:147], v[186:189], v[100:103]
	v_mfma_f32_16x16x32_bf16 v[96:99], v[152:155], v[186:189], v[96:99]
	v_mfma_f32_16x16x32_bf16 v[84:87], v[144:147], v[194:197], v[84:87]
	v_mfma_f32_16x16x32_bf16 v[80:83], v[152:155], v[194:197], v[80:83]
	v_mfma_f32_16x16x32_bf16 v[68:71], v[144:147], v[202:205], v[68:71]
	v_mfma_f32_16x16x32_bf16 v[64:67], v[152:155], v[202:205], v[64:67]
	v_mfma_f32_16x16x32_bf16 v[116:119], v[148:151], v[164:167], v[116:119]
	v_mfma_f32_16x16x32_bf16 v[112:115], v[156:159], v[164:167], v[112:115]
	v_mfma_f32_16x16x32_bf16 v[100:103], v[148:151], v[190:193], v[100:103]
	v_mfma_f32_16x16x32_bf16 v[96:99], v[156:159], v[190:193], v[96:99]
	s_setprio 2
	s_barrier
	v_mfma_f32_16x16x32_bf16 v[84:87], v[148:151], v[198:201], v[84:87]
	v_mfma_f32_16x16x32_bf16 v[80:83], v[156:159], v[198:201], v[80:83]
	v_mfma_f32_16x16x32_bf16 v[68:71], v[148:151], v[206:209], v[68:71]
	v_mfma_f32_16x16x32_bf16 v[64:67], v[156:159], v[206:209], v[64:67]
	s_setprio 0
	s_add_i32 s8, s64, s37
	v_lshl_add_u64 v[178:179], v[178:179], 0, s[34:35]
	s_mov_b32 m0, s8
	ds_read_b128 v[160:163], v231 offset:49152
	ds_read_b128 v[164:167], v231 offset:50176
	ds_read_b128 v[186:189], v231 offset:51200
	ds_read_b128 v[190:193], v231 offset:52224
	ds_read_b128 v[194:197], v231 offset:53248
	ds_read_b128 v[198:201], v231 offset:54272
	ds_read_b128 v[202:205], v231 offset:55296
	ds_read_b128 v[206:209], v231 offset:56320
	global_load_lds_dwordx4 v[178:179], off
	s_add_i32 m0, s8, 0x2000
	s_add_u32 s8, s50, 0xb0080
	v_lshl_add_u64 v[178:179], v[210:211], 0, s[34:35]
	s_addc_u32 s9, s51, 0
	s_add_i32 s50, s65, s37
	global_load_lds_dwordx4 v[178:179], off
	v_lshl_add_u64 v[178:179], s[8:9], 0, v[170:171]
	s_mov_b32 m0, s50
	s_nop 0
	global_load_lds_dwordx4 v[178:179], off
	v_lshl_add_u64 v[178:179], s[8:9], 0, v[174:175]
	s_add_i32 m0, s50, 0x2000
	s_nop 0
	global_load_lds_dwordx4 v[178:179], off
	v_lshl_add_u64 v[178:179], v[212:213], 0, s[34:35]
	s_mov_b32 m0, s73
	s_nop 0
	global_load_lds_dwordx4 v[178:179], off
	v_lshl_add_u64 v[178:179], v[220:221], 0, s[34:35]
	s_mov_b32 m0, s74
	s_nop 0
	global_load_lds_dwordx4 v[178:179], off
	s_waitcnt vmcnt(8)
	s_waitcnt lgkmcnt(0)
	s_barrier
	s_setprio 1
	v_mfma_f32_16x16x32_bf16 v[60:63], v[128:131], v[160:163], v[60:63]
	v_mfma_f32_16x16x32_bf16 v[56:59], v[136:139], v[160:163], v[56:59]
	v_mfma_f32_16x16x32_bf16 v[44:47], v[128:131], v[186:189], v[44:47]
	v_mfma_f32_16x16x32_bf16 v[40:43], v[136:139], v[186:189], v[40:43]
	v_mfma_f32_16x16x32_bf16 v[28:31], v[128:131], v[194:197], v[28:31]
	v_mfma_f32_16x16x32_bf16 v[24:27], v[136:139], v[194:197], v[24:27]
	v_mfma_f32_16x16x32_bf16 v[12:15], v[128:131], v[202:205], v[12:15]
	v_mfma_f32_16x16x32_bf16 v[8:11], v[136:139], v[202:205], v[8:11]
	v_mfma_f32_16x16x32_bf16 v[60:63], v[132:135], v[164:167], v[60:63]
	v_mfma_f32_16x16x32_bf16 v[56:59], v[140:143], v[164:167], v[56:59]
	v_mfma_f32_16x16x32_bf16 v[44:47], v[132:135], v[190:193], v[44:47]
	v_mfma_f32_16x16x32_bf16 v[40:43], v[140:143], v[190:193], v[40:43]
	v_mfma_f32_16x16x32_bf16 v[28:31], v[132:135], v[198:201], v[28:31]
	v_mfma_f32_16x16x32_bf16 v[24:27], v[140:143], v[198:201], v[24:27]
	v_mfma_f32_16x16x32_bf16 v[12:15], v[132:135], v[206:209], v[12:15]
	v_mfma_f32_16x16x32_bf16 v[8:11], v[140:143], v[206:209], v[8:11]
	v_mfma_f32_16x16x32_bf16 v[52:55], v[144:147], v[160:163], v[52:55]
	v_mfma_f32_16x16x32_bf16 v[48:51], v[152:155], v[160:163], v[48:51]
	v_mfma_f32_16x16x32_bf16 v[36:39], v[144:147], v[186:189], v[36:39]
	v_mfma_f32_16x16x32_bf16 v[32:35], v[152:155], v[186:189], v[32:35]
	v_mfma_f32_16x16x32_bf16 v[20:23], v[144:147], v[194:197], v[20:23]
	v_mfma_f32_16x16x32_bf16 v[16:19], v[152:155], v[194:197], v[16:19]
	v_mfma_f32_16x16x32_bf16 v[4:7], v[144:147], v[202:205], v[4:7]
	v_mfma_f32_16x16x32_bf16 v[0:3], v[152:155], v[202:205], v[0:3]
	v_mfma_f32_16x16x32_bf16 v[52:55], v[148:151], v[164:167], v[52:55]
	v_mfma_f32_16x16x32_bf16 v[48:51], v[156:159], v[164:167], v[48:51]
	v_mfma_f32_16x16x32_bf16 v[36:39], v[148:151], v[190:193], v[36:39]
	v_mfma_f32_16x16x32_bf16 v[32:35], v[156:159], v[190:193], v[32:35]
	s_setprio 2
	s_barrier
	v_mfma_f32_16x16x32_bf16 v[20:23], v[148:151], v[198:201], v[20:23]
	v_mfma_f32_16x16x32_bf16 v[16:19], v[156:159], v[198:201], v[16:19]
	v_mfma_f32_16x16x32_bf16 v[4:7], v[148:151], v[206:209], v[4:7]
	v_mfma_f32_16x16x32_bf16 v[0:3], v[156:159], v[206:209], v[0:3]
	s_setprio 0
	s_add_i32 s92, s92, 2
	s_add_u32 s44, s44, 0x100
	s_addc_u32 s55, s55, 0
	s_cmp_gt_u32 s92, 41
	s_mov_b64 s[8:9], s[40:41]
	s_cbranch_scc0 .LBB0_769
	s_and_b64 vcc, exec, s[26:27]
	s_cbranch_vccz .LBB0_772
	s_barrier

.LBB0_863:
	s_add_i32 s64, s50, 2
	s_add_u32 s40, s8, 0x100
	s_addc_u32 s41, s9, 0
	s_add_i32 s65, 0, 0x10000
	s_cmp_eq_u32 s27, s50
	s_cselect_b32 s53, s29, s41
	s_cselect_b32 s52, s28, s40
	s_cselect_b32 s51, s39, vcc_hi
	s_cselect_b32 s50, s38, vcc_lo
	s_add_i32 s66, 0, 0x14000
	v_add_u32_e32 v140, s65, v228
	v_add_u32_e32 v156, s66, v228
	ds_read_b128 v[128:131], v140
	ds_read_b128 v[132:135], v140 offset:1024
	ds_read_b128 v[136:139], v140 offset:2048
	ds_read_b128 v[140:143], v140 offset:3072
	ds_read_b128 v[144:147], v156
	ds_read_b128 v[148:151], v156 offset:1024
	ds_read_b128 v[152:155], v156 offset:2048
	ds_read_b128 v[156:159], v156 offset:3072
	v_lshl_add_u64 v[178:179], s[8:9], 0, v[184:185]
	s_add_i32 m0, s74, 0xc000
	ds_read_b128 v[160:163], v232
	ds_read_b128 v[164:167], v232 offset:1024
	ds_read_b128 v[186:189], v232 offset:2048
	ds_read_b128 v[190:193], v232 offset:3072
	ds_read_b128 v[194:197], v232 offset:4096
	ds_read_b128 v[198:201], v232 offset:5120
	ds_read_b128 v[202:205], v232 offset:6144
	ds_read_b128 v[206:209], v232 offset:7168
	global_load_lds_dwordx4 v[178:179], off
	v_lshl_add_u64 v[178:179], s[8:9], 0, v[182:183]
	s_add_i32 m0, s74, 0xe000
	s_nop 0
	global_load_lds_dwordx4 v[178:179], off
	s_waitcnt vmcnt(8)
	s_waitcnt lgkmcnt(0)
	s_barrier
	s_setprio 1
	v_mfma_f32_16x16x32_bf16 v[124:127], v[128:131], v[160:163], v[124:127]
	v_mfma_f32_16x16x32_bf16 v[120:123], v[136:139], v[160:163], v[120:123]
	v_mfma_f32_16x16x32_bf16 v[108:111], v[128:131], v[186:189], v[108:111]
	v_mfma_f32_16x16x32_bf16 v[104:107], v[136:139], v[186:189], v[104:107]
	v_mfma_f32_16x16x32_bf16 v[92:95], v[128:131], v[194:197], v[92:95]
	v_mfma_f32_16x16x32_bf16 v[88:91], v[136:139], v[194:197], v[88:91]
	v_mfma_f32_16x16x32_bf16 v[76:79], v[128:131], v[202:205], v[76:79]
	v_mfma_f32_16x16x32_bf16 v[72:75], v[136:139], v[202:205], v[72:75]
	v_mfma_f32_16x16x32_bf16 v[124:127], v[132:135], v[164:167], v[124:127]
	v_mfma_f32_16x16x32_bf16 v[120:123], v[140:143], v[164:167], v[120:123]
	v_mfma_f32_16x16x32_bf16 v[108:111], v[132:135], v[190:193], v[108:111]
	v_mfma_f32_16x16x32_bf16 v[104:107], v[140:143], v[190:193], v[104:107]
	v_mfma_f32_16x16x32_bf16 v[92:95], v[132:135], v[198:201], v[92:95]
	v_mfma_f32_16x16x32_bf16 v[88:91], v[140:143], v[198:201], v[88:91]
	v_mfma_f32_16x16x32_bf16 v[76:79], v[132:135], v[206:209], v[76:79]
	v_mfma_f32_16x16x32_bf16 v[72:75], v[140:143], v[206:209], v[72:75]
	v_mfma_f32_16x16x32_bf16 v[116:119], v[144:147], v[160:163], v[116:119]
	v_mfma_f32_16x16x32_bf16 v[112:115], v[152:155], v[160:163], v[112:115]
	v_mfma_f32_16x16x32_bf16 v[100:103], v[144:147], v[186:189], v[100:103]
	v_mfma_f32_16x16x32_bf16 v[96:99], v[152:155], v[186:189], v[96:99]
	v_mfma_f32_16x16x32_bf16 v[84:87], v[144:147], v[194:197], v[84:87]
	v_mfma_f32_16x16x32_bf16 v[80:83], v[152:155], v[194:197], v[80:83]
	v_mfma_f32_16x16x32_bf16 v[68:71], v[144:147], v[202:205], v[68:71]
	v_mfma_f32_16x16x32_bf16 v[64:67], v[152:155], v[202:205], v[64:67]
	v_mfma_f32_16x16x32_bf16 v[116:119], v[148:151], v[164:167], v[116:119]
	v_mfma_f32_16x16x32_bf16 v[112:115], v[156:159], v[164:167], v[112:115]
	v_mfma_f32_16x16x32_bf16 v[100:103], v[148:151], v[190:193], v[100:103]
	v_mfma_f32_16x16x32_bf16 v[96:99], v[156:159], v[190:193], v[96:99]
	s_setprio 2
	s_barrier
	v_mfma_f32_16x16x32_bf16 v[84:87], v[148:151], v[198:201], v[84:87]
	v_mfma_f32_16x16x32_bf16 v[80:83], v[156:159], v[198:201], v[80:83]
	v_mfma_f32_16x16x32_bf16 v[68:71], v[148:151], v[206:209], v[68:71]
	v_mfma_f32_16x16x32_bf16 v[64:67], v[156:159], v[206:209], v[64:67]
	s_setprio 0
	s_add_i32 s8, s65, s72
	v_lshl_add_u64 v[178:179], s[50:51], 0, v[170:171]
	s_mov_b32 m0, s8
	ds_read_b128 v[160:163], v232 offset:16384
	ds_read_b128 v[164:167], v232 offset:17408
	ds_read_b128 v[186:189], v232 offset:18432
	ds_read_b128 v[190:193], v232 offset:19456
	ds_read_b128 v[194:197], v232 offset:20480
	ds_read_b128 v[198:201], v232 offset:21504
	ds_read_b128 v[202:205], v232 offset:22528
	ds_read_b128 v[206:209], v232 offset:23552
	global_load_lds_dwordx4 v[178:179], off
	s_add_i32 m0, s8, 0x2000
	s_add_u32 s8, s50, 0xb0000
	v_lshl_add_u64 v[210:211], s[50:51], 0, v[174:175]
	s_addc_u32 s9, s51, 0
	s_add_i32 s65, s66, s72
	global_load_lds_dwordx4 v[210:211], off
	v_lshl_add_u64 v[212:213], s[8:9], 0, v[170:171]
	s_mov_b32 m0, s65
	v_lshl_add_u64 v[220:221], s[52:53], 0, v[172:173]
	global_load_lds_dwordx4 v[212:213], off
	v_lshl_add_u64 v[212:213], s[8:9], 0, v[174:175]
	s_add_i32 m0, s65, 0x2000
	s_nop 0
	global_load_lds_dwordx4 v[212:213], off
	v_lshl_add_u64 v[212:213], s[52:53], 0, v[168:169]
	s_mov_b32 m0, s74
	s_nop 0
	global_load_lds_dwordx4 v[212:213], off
	s_mov_b32 m0, s75
	s_nop 0
	global_load_lds_dwordx4 v[220:221], off
	s_waitcnt vmcnt(8)
	s_waitcnt lgkmcnt(0)
	s_barrier
	s_setprio 1
	v_mfma_f32_16x16x32_bf16 v[60:63], v[128:131], v[160:163], v[60:63]
	v_mfma_f32_16x16x32_bf16 v[56:59], v[136:139], v[160:163], v[56:59]
	v_mfma_f32_16x16x32_bf16 v[44:47], v[128:131], v[186:189], v[44:47]
	v_mfma_f32_16x16x32_bf16 v[40:43], v[136:139], v[186:189], v[40:43]
	v_mfma_f32_16x16x32_bf16 v[28:31], v[128:131], v[194:197], v[28:31]
	v_mfma_f32_16x16x32_bf16 v[24:27], v[136:139], v[194:197], v[24:27]
	v_mfma_f32_16x16x32_bf16 v[12:15], v[128:131], v[202:205], v[12:15]
	v_mfma_f32_16x16x32_bf16 v[8:11], v[136:139], v[202:205], v[8:11]
	v_mfma_f32_16x16x32_bf16 v[60:63], v[132:135], v[164:167], v[60:63]
	v_mfma_f32_16x16x32_bf16 v[56:59], v[140:143], v[164:167], v[56:59]
	v_mfma_f32_16x16x32_bf16 v[44:47], v[132:135], v[190:193], v[44:47]
	v_mfma_f32_16x16x32_bf16 v[40:43], v[140:143], v[190:193], v[40:43]
	v_mfma_f32_16x16x32_bf16 v[28:31], v[132:135], v[198:201], v[28:31]
	v_mfma_f32_16x16x32_bf16 v[24:27], v[140:143], v[198:201], v[24:27]
	v_mfma_f32_16x16x32_bf16 v[12:15], v[132:135], v[206:209], v[12:15]
	v_mfma_f32_16x16x32_bf16 v[8:11], v[140:143], v[206:209], v[8:11]
	v_mfma_f32_16x16x32_bf16 v[52:55], v[144:147], v[160:163], v[52:55]
	v_mfma_f32_16x16x32_bf16 v[48:51], v[152:155], v[160:163], v[48:51]
	v_mfma_f32_16x16x32_bf16 v[36:39], v[144:147], v[186:189], v[36:39]
	v_mfma_f32_16x16x32_bf16 v[32:35], v[152:155], v[186:189], v[32:35]
	v_mfma_f32_16x16x32_bf16 v[20:23], v[144:147], v[194:197], v[20:23]
	v_mfma_f32_16x16x32_bf16 v[16:19], v[152:155], v[194:197], v[16:19]
	v_mfma_f32_16x16x32_bf16 v[4:7], v[144:147], v[202:205], v[4:7]
	v_mfma_f32_16x16x32_bf16 v[0:3], v[152:155], v[202:205], v[0:3]
	v_mfma_f32_16x16x32_bf16 v[52:55], v[148:151], v[164:167], v[52:55]
	v_mfma_f32_16x16x32_bf16 v[48:51], v[156:159], v[164:167], v[48:51]
	v_mfma_f32_16x16x32_bf16 v[36:39], v[148:151], v[190:193], v[36:39]
	v_mfma_f32_16x16x32_bf16 v[32:35], v[156:159], v[190:193], v[32:35]
	s_setprio 2
	s_barrier
	v_mfma_f32_16x16x32_bf16 v[20:23], v[148:151], v[198:201], v[20:23]
	v_mfma_f32_16x16x32_bf16 v[16:19], v[156:159], v[198:201], v[16:19]
	v_mfma_f32_16x16x32_bf16 v[4:7], v[148:151], v[206:209], v[4:7]
	v_mfma_f32_16x16x32_bf16 v[0:3], v[156:159], v[206:209], v[0:3]
	s_setprio 0
	s_add_i32 s65, 0, 0x18000
	s_add_i32 s66, 0, 0x1c000
	v_add_u32_e32 v140, s65, v228
	v_add_u32_e32 v156, s66, v228
	ds_read_b128 v[128:131], v140
	ds_read_b128 v[132:135], v140 offset:1024
	ds_read_b128 v[136:139], v140 offset:2048
	ds_read_b128 v[140:143], v140 offset:3072
	ds_read_b128 v[144:147], v156
	ds_read_b128 v[148:151], v156 offset:1024
	ds_read_b128 v[152:155], v156 offset:2048
	ds_read_b128 v[156:159], v156 offset:3072
	s_add_u32 s8, s52, 0xb0000
	s_addc_u32 s9, s53, 0
	s_mov_b32 m0, s80
	v_lshl_add_u64 v[222:223], s[8:9], 0, v[168:169]
	ds_read_b128 v[160:163], v232 offset:32768
	ds_read_b128 v[164:167], v232 offset:33792
	ds_read_b128 v[186:189], v232 offset:34816
	ds_read_b128 v[190:193], v232 offset:35840
	ds_read_b128 v[194:197], v232 offset:36864
	ds_read_b128 v[198:201], v232 offset:37888
	ds_read_b128 v[202:205], v232 offset:38912
	ds_read_b128 v[206:209], v232 offset:39936
	global_load_lds_dwordx4 v[222:223], off
	v_lshl_add_u64 v[222:223], s[8:9], 0, v[172:173]
	s_mov_b32 m0, s81
	s_nop 0
	global_load_lds_dwordx4 v[222:223], off
	s_waitcnt vmcnt(8)
	s_waitcnt lgkmcnt(0)
	s_barrier
	s_setprio 1
	v_mfma_f32_16x16x32_bf16 v[124:127], v[128:131], v[160:163], v[124:127]
	v_mfma_f32_16x16x32_bf16 v[120:123], v[136:139], v[160:163], v[120:123]
	v_mfma_f32_16x16x32_bf16 v[108:111], v[128:131], v[186:189], v[108:111]
	v_mfma_f32_16x16x32_bf16 v[104:107], v[136:139], v[186:189], v[104:107]
	v_mfma_f32_16x16x32_bf16 v[92:95], v[128:131], v[194:197], v[92:95]
	v_mfma_f32_16x16x32_bf16 v[88:91], v[136:139], v[194:197], v[88:91]
	v_mfma_f32_16x16x32_bf16 v[76:79], v[128:131], v[202:205], v[76:79]
	v_mfma_f32_16x16x32_bf16 v[72:75], v[136:139], v[202:205], v[72:75]
	v_mfma_f32_16x16x32_bf16 v[124:127], v[132:135], v[164:167], v[124:127]
	v_mfma_f32_16x16x32_bf16 v[120:123], v[140:143], v[164:167], v[120:123]
	v_mfma_f32_16x16x32_bf16 v[108:111], v[132:135], v[190:193], v[108:111]
	v_mfma_f32_16x16x32_bf16 v[104:107], v[140:143], v[190:193], v[104:107]
	v_mfma_f32_16x16x32_bf16 v[92:95], v[132:135], v[198:201], v[92:95]
	v_mfma_f32_16x16x32_bf16 v[88:91], v[140:143], v[198:201], v[88:91]
	v_mfma_f32_16x16x32_bf16 v[76:79], v[132:135], v[206:209], v[76:79]
	v_mfma_f32_16x16x32_bf16 v[72:75], v[140:143], v[206:209], v[72:75]
	v_mfma_f32_16x16x32_bf16 v[116:119], v[144:147], v[160:163], v[116:119]
	v_mfma_f32_16x16x32_bf16 v[112:115], v[152:155], v[160:163], v[112:115]
	v_mfma_f32_16x16x32_bf16 v[100:103], v[144:147], v[186:189], v[100:103]
	v_mfma_f32_16x16x32_bf16 v[96:99], v[152:155], v[186:189], v[96:99]
	v_mfma_f32_16x16x32_bf16 v[84:87], v[144:147], v[194:197], v[84:87]
	v_mfma_f32_16x16x32_bf16 v[80:83], v[152:155], v[194:197], v[80:83]
	v_mfma_f32_16x16x32_bf16 v[68:71], v[144:147], v[202:205], v[68:71]
	v_mfma_f32_16x16x32_bf16 v[64:67], v[152:155], v[202:205], v[64:67]
	v_mfma_f32_16x16x32_bf16 v[116:119], v[148:151], v[164:167], v[116:119]
	v_mfma_f32_16x16x32_bf16 v[112:115], v[156:159], v[164:167], v[112:115]
	v_mfma_f32_16x16x32_bf16 v[100:103], v[148:151], v[190:193], v[100:103]
	v_mfma_f32_16x16x32_bf16 v[96:99], v[156:159], v[190:193], v[96:99]
	s_setprio 2
	s_barrier
	v_mfma_f32_16x16x32_bf16 v[84:87], v[148:151], v[198:201], v[84:87]
	v_mfma_f32_16x16x32_bf16 v[80:83], v[156:159], v[198:201], v[80:83]
	v_mfma_f32_16x16x32_bf16 v[68:71], v[148:151], v[206:209], v[68:71]
	v_mfma_f32_16x16x32_bf16 v[64:67], v[156:159], v[206:209], v[64:67]
	s_setprio 0
	s_add_i32 s8, s65, s72
	v_lshl_add_u64 v[178:179], v[178:179], 0, s[34:35]
	s_mov_b32 m0, s8
	ds_read_b128 v[160:163], v232 offset:49152
	ds_read_b128 v[164:167], v232 offset:50176
	ds_read_b128 v[186:189], v232 offset:51200
	ds_read_b128 v[190:193], v232 offset:52224
	ds_read_b128 v[194:197], v232 offset:53248
	ds_read_b128 v[198:201], v232 offset:54272
	ds_read_b128 v[202:205], v232 offset:55296
	ds_read_b128 v[206:209], v232 offset:56320
	global_load_lds_dwordx4 v[178:179], off
	s_add_i32 m0, s8, 0x2000
	s_add_u32 s8, s50, 0xb0080
	v_lshl_add_u64 v[178:179], v[210:211], 0, s[34:35]
	s_addc_u32 s9, s51, 0
	s_add_i32 s50, s66, s72
	global_load_lds_dwordx4 v[178:179], off
	v_lshl_add_u64 v[178:179], s[8:9], 0, v[170:171]
	s_mov_b32 m0, s50
	s_nop 0
	global_load_lds_dwordx4 v[178:179], off
	v_lshl_add_u64 v[178:179], s[8:9], 0, v[174:175]
	s_add_i32 m0, s50, 0x2000
	s_nop 0
	global_load_lds_dwordx4 v[178:179], off
	v_lshl_add_u64 v[178:179], v[212:213], 0, s[34:35]
	s_mov_b32 m0, s83
	s_nop 0
	global_load_lds_dwordx4 v[178:179], off
	v_lshl_add_u64 v[178:179], v[220:221], 0, s[34:35]
	s_mov_b32 m0, s91
	s_nop 0
	global_load_lds_dwordx4 v[178:179], off
	s_waitcnt vmcnt(8)
	s_waitcnt lgkmcnt(0)
	s_barrier
	s_setprio 1
	v_mfma_f32_16x16x32_bf16 v[60:63], v[128:131], v[160:163], v[60:63]
	v_mfma_f32_16x16x32_bf16 v[56:59], v[136:139], v[160:163], v[56:59]
	v_mfma_f32_16x16x32_bf16 v[44:47], v[128:131], v[186:189], v[44:47]
	v_mfma_f32_16x16x32_bf16 v[40:43], v[136:139], v[186:189], v[40:43]
	v_mfma_f32_16x16x32_bf16 v[28:31], v[128:131], v[194:197], v[28:31]
	v_mfma_f32_16x16x32_bf16 v[24:27], v[136:139], v[194:197], v[24:27]
	v_mfma_f32_16x16x32_bf16 v[12:15], v[128:131], v[202:205], v[12:15]
	v_mfma_f32_16x16x32_bf16 v[8:11], v[136:139], v[202:205], v[8:11]
	v_mfma_f32_16x16x32_bf16 v[60:63], v[132:135], v[164:167], v[60:63]
	v_mfma_f32_16x16x32_bf16 v[56:59], v[140:143], v[164:167], v[56:59]
	v_mfma_f32_16x16x32_bf16 v[44:47], v[132:135], v[190:193], v[44:47]
	v_mfma_f32_16x16x32_bf16 v[40:43], v[140:143], v[190:193], v[40:43]
	v_mfma_f32_16x16x32_bf16 v[28:31], v[132:135], v[198:201], v[28:31]
	v_mfma_f32_16x16x32_bf16 v[24:27], v[140:143], v[198:201], v[24:27]
	v_mfma_f32_16x16x32_bf16 v[12:15], v[132:135], v[206:209], v[12:15]
	v_mfma_f32_16x16x32_bf16 v[8:11], v[140:143], v[206:209], v[8:11]
	v_mfma_f32_16x16x32_bf16 v[52:55], v[144:147], v[160:163], v[52:55]
	v_mfma_f32_16x16x32_bf16 v[48:51], v[152:155], v[160:163], v[48:51]
	v_mfma_f32_16x16x32_bf16 v[36:39], v[144:147], v[186:189], v[36:39]
	v_mfma_f32_16x16x32_bf16 v[32:35], v[152:155], v[186:189], v[32:35]
	v_mfma_f32_16x16x32_bf16 v[20:23], v[144:147], v[194:197], v[20:23]
	v_mfma_f32_16x16x32_bf16 v[16:19], v[152:155], v[194:197], v[16:19]
	v_mfma_f32_16x16x32_bf16 v[4:7], v[144:147], v[202:205], v[4:7]
	v_mfma_f32_16x16x32_bf16 v[0:3], v[152:155], v[202:205], v[0:3]
	v_mfma_f32_16x16x32_bf16 v[52:55], v[148:151], v[164:167], v[52:55]
	v_mfma_f32_16x16x32_bf16 v[48:51], v[156:159], v[164:167], v[48:51]
	v_mfma_f32_16x16x32_bf16 v[36:39], v[148:151], v[190:193], v[36:39]
	v_mfma_f32_16x16x32_bf16 v[32:35], v[156:159], v[190:193], v[32:35]
	s_setprio 2
	s_barrier
	v_mfma_f32_16x16x32_bf16 v[20:23], v[148:151], v[198:201], v[20:23]
	v_mfma_f32_16x16x32_bf16 v[16:19], v[156:159], v[198:201], v[16:19]
	v_mfma_f32_16x16x32_bf16 v[4:7], v[148:151], v[206:209], v[4:7]
	v_mfma_f32_16x16x32_bf16 v[0:3], v[156:159], v[206:209], v[0:3]
	s_setprio 0
	s_add_u32 vcc_lo, vcc_lo, 0x100
	s_addc_u32 vcc_hi, vcc_hi, 0
	s_cmp_ge_i32 s64, s63
	s_mov_b64 s[8:9], s[40:41]
	s_mov_b32 s50, s64
	s_cbranch_scc0 .LBB0_863
	s_and_b64 vcc, exec, s[22:23]
	s_cbranch_vccz .LBB0_866

.LBB0_952:
	s_add_u32 s44, s38, 0x180
	v_mov_b32_e32 v0, 0
	s_addc_u32 s53, s39, 0
	s_mov_b32 s83, -2
	v_mov_b32_e32 v1, v0
	v_mov_b32_e32 v2, v0
	v_mov_b32_e32 v3, v0
	v_mov_b32_e32 v4, v0
	v_mov_b32_e32 v5, v0
	v_mov_b32_e32 v6, v0
	v_mov_b32_e32 v7, v0
	v_mov_b32_e32 v16, v0
	v_mov_b32_e32 v17, v0
	v_mov_b32_e32 v18, v0
	v_mov_b32_e32 v19, v0
	s_waitcnt vmcnt(0)
	v_mov_b32_e32 v20, v0
	v_mov_b32_e32 v21, v0
	v_mov_b32_e32 v22, v0
	v_mov_b32_e32 v23, v0
	v_mov_b32_e32 v32, v0
	v_mov_b32_e32 v33, v0
	v_mov_b32_e32 v34, v0
	v_mov_b32_e32 v35, v0
	v_mov_b32_e32 v36, v0
	v_mov_b32_e32 v37, v0
	v_mov_b32_e32 v38, v0
	v_mov_b32_e32 v39, v0
	v_mov_b32_e32 v48, v0
	v_mov_b32_e32 v49, v0
	v_mov_b32_e32 v50, v0
	v_mov_b32_e32 v51, v0
	v_mov_b32_e32 v52, v0
	v_mov_b32_e32 v53, v0
	v_mov_b32_e32 v54, v0
	v_mov_b32_e32 v55, v0
	v_mov_b32_e32 v8, v0
	v_mov_b32_e32 v9, v0
	v_mov_b32_e32 v10, v0
	v_mov_b32_e32 v11, v0
	v_mov_b32_e32 v12, v0
	v_mov_b32_e32 v13, v0
	v_mov_b32_e32 v14, v0
	v_mov_b32_e32 v15, v0
	v_mov_b32_e32 v24, v0
	v_mov_b32_e32 v25, v0
	v_mov_b32_e32 v26, v0
	v_mov_b32_e32 v27, v0
	v_mov_b32_e32 v28, v0
	v_mov_b32_e32 v29, v0
	v_mov_b32_e32 v30, v0
	v_mov_b32_e32 v31, v0
	v_mov_b32_e32 v40, v0
	v_mov_b32_e32 v41, v0
	v_mov_b32_e32 v42, v0
	v_mov_b32_e32 v43, v0
	v_mov_b32_e32 v44, v0
	v_mov_b32_e32 v45, v0
	v_mov_b32_e32 v46, v0
	v_mov_b32_e32 v47, v0
	v_mov_b32_e32 v72, v0
	v_mov_b32_e32 v73, v0
	v_mov_b32_e32 v74, v0
	v_mov_b32_e32 v75, v0
	v_mov_b32_e32 v76, v0
	v_mov_b32_e32 v77, v0
	v_mov_b32_e32 v78, v0
	v_mov_b32_e32 v79, v0
	v_mov_b32_e32 v80, v0
	v_mov_b32_e32 v81, v0
	v_mov_b32_e32 v82, v0
	v_mov_b32_e32 v83, v0
	v_mov_b32_e32 v84, v0
	v_mov_b32_e32 v85, v0
	v_mov_b32_e32 v86, v0
	v_mov_b32_e32 v87, v0
	v_mov_b32_e32 v96, v0
	v_mov_b32_e32 v97, v0
	v_mov_b32_e32 v98, v0
	v_mov_b32_e32 v99, v0
	v_mov_b32_e32 v100, v0
	v_mov_b32_e32 v101, v0
	v_mov_b32_e32 v102, v0
	v_mov_b32_e32 v103, v0
	v_mov_b32_e32 v112, v0
	v_mov_b32_e32 v113, v0
	v_mov_b32_e32 v114, v0
	v_mov_b32_e32 v115, v0
	v_mov_b32_e32 v116, v0
	v_mov_b32_e32 v117, v0
	v_mov_b32_e32 v118, v0
	v_mov_b32_e32 v119, v0
	v_mov_b32_e32 v124, v0
	v_mov_b32_e32 v125, v0
	v_mov_b32_e32 v126, v0
	v_mov_b32_e32 v127, v0
	v_mov_b32_e32 v132, v0
	v_mov_b32_e32 v133, v0
	v_mov_b32_e32 v134, v0
	v_mov_b32_e32 v135, v0
	v_mov_b32_e32 v88, v0
	v_mov_b32_e32 v89, v0
	v_mov_b32_e32 v90, v0
	v_mov_b32_e32 v91, v0
	v_mov_b32_e32 v92, v0
	v_mov_b32_e32 v93, v0
	v_mov_b32_e32 v94, v0
	v_mov_b32_e32 v95, v0
	v_mov_b32_e32 v104, v0
	v_mov_b32_e32 v105, v0
	v_mov_b32_e32 v106, v0
	v_mov_b32_e32 v107, v0
	v_mov_b32_e32 v108, v0
	v_mov_b32_e32 v109, v0
	v_mov_b32_e32 v110, v0
	v_mov_b32_e32 v111, v0
	v_mov_b32_e32 v120, v0
	v_mov_b32_e32 v121, v0
	v_mov_b32_e32 v122, v0
	v_mov_b32_e32 v123, v0
	v_mov_b32_e32 v128, v0
	v_mov_b32_e32 v129, v0
	v_mov_b32_e32 v130, v0
	v_mov_b32_e32 v131, v0
	v_mov_b32_e32 v136, v0
	v_mov_b32_e32 v137, v0
	v_mov_b32_e32 v138, v0
	v_mov_b32_e32 v139, v0
	v_mov_b32_e32 v140, v0
	v_mov_b32_e32 v141, v0
	v_mov_b32_e32 v142, v0
	v_mov_b32_e32 v143, v0
.LBB0_953:
	s_add_u32 s38, s8, 0x180
	s_addc_u32 s39, s9, 0
	s_add_i32 s64, 0, 0x10000
	s_cmp_eq_u32 s83, 12
	s_cselect_b32 s51, s1, s39
	s_cselect_b32 s50, s0, s38
	s_cselect_b32 s41, s29, s53
	s_cselect_b32 s40, s28, s44
	s_add_i32 s65, 0, 0x14000
	v_add_u32_e32 v68, s64, v228
	v_add_u32_e32 v156, s65, v228
	ds_read_b128 v[56:59], v68
	ds_read_b128 v[60:63], v68 offset:1024
	ds_read_b128 v[64:67], v68 offset:2048
	ds_read_b128 v[68:71], v68 offset:3072
	ds_read_b128 v[144:147], v156
	ds_read_b128 v[148:151], v156 offset:1024
	ds_read_b128 v[152:155], v156 offset:2048
	ds_read_b128 v[156:159], v156 offset:3072
	v_lshl_add_u64 v[178:179], s[8:9], 0, v[192:193]
	s_add_i32 m0, s60, 0xc000
	ds_read_b128 v[160:163], v231
	ds_read_b128 v[164:167], v231 offset:1024
	ds_read_b128 v[168:171], v231 offset:2048
	ds_read_b128 v[172:175], v231 offset:3072
	ds_read_b128 v[194:197], v231 offset:4096
	ds_read_b128 v[198:201], v231 offset:5120
	ds_read_b128 v[202:205], v231 offset:6144
	ds_read_b128 v[206:209], v231 offset:7168
	global_load_lds_dwordx4 v[178:179], off
	v_lshl_add_u64 v[178:179], s[8:9], 0, v[190:191]
	s_add_i32 m0, s60, 0xe000
	s_nop 0
	global_load_lds_dwordx4 v[178:179], off
	s_waitcnt vmcnt(8)
	s_waitcnt lgkmcnt(0)
	s_barrier
	s_setprio 1
	v_mfma_f32_16x16x32_bf16 v[140:143], v[56:59], v[160:163], v[140:143]
	v_mfma_f32_16x16x32_bf16 v[136:139], v[64:67], v[160:163], v[136:139]
	v_mfma_f32_16x16x32_bf16 v[128:131], v[56:59], v[168:171], v[128:131]
	v_mfma_f32_16x16x32_bf16 v[120:123], v[64:67], v[168:171], v[120:123]
	v_mfma_f32_16x16x32_bf16 v[108:111], v[56:59], v[194:197], v[108:111]
	v_mfma_f32_16x16x32_bf16 v[104:107], v[64:67], v[194:197], v[104:107]
	v_mfma_f32_16x16x32_bf16 v[92:95], v[56:59], v[202:205], v[92:95]
	v_mfma_f32_16x16x32_bf16 v[88:91], v[64:67], v[202:205], v[88:91]
	v_mfma_f32_16x16x32_bf16 v[140:143], v[60:63], v[164:167], v[140:143]
	v_mfma_f32_16x16x32_bf16 v[136:139], v[68:71], v[164:167], v[136:139]
	v_mfma_f32_16x16x32_bf16 v[128:131], v[60:63], v[172:175], v[128:131]
	v_mfma_f32_16x16x32_bf16 v[120:123], v[68:71], v[172:175], v[120:123]
	v_mfma_f32_16x16x32_bf16 v[108:111], v[60:63], v[198:201], v[108:111]
	v_mfma_f32_16x16x32_bf16 v[104:107], v[68:71], v[198:201], v[104:107]
	v_mfma_f32_16x16x32_bf16 v[92:95], v[60:63], v[206:209], v[92:95]
	v_mfma_f32_16x16x32_bf16 v[88:91], v[68:71], v[206:209], v[88:91]
	v_mfma_f32_16x16x32_bf16 v[132:135], v[144:147], v[160:163], v[132:135]
	v_mfma_f32_16x16x32_bf16 v[124:127], v[152:155], v[160:163], v[124:127]
	v_mfma_f32_16x16x32_bf16 v[116:119], v[144:147], v[168:171], v[116:119]
	v_mfma_f32_16x16x32_bf16 v[112:115], v[152:155], v[168:171], v[112:115]
	v_mfma_f32_16x16x32_bf16 v[100:103], v[144:147], v[194:197], v[100:103]
	v_mfma_f32_16x16x32_bf16 v[96:99], v[152:155], v[194:197], v[96:99]
	v_mfma_f32_16x16x32_bf16 v[84:87], v[144:147], v[202:205], v[84:87]
	v_mfma_f32_16x16x32_bf16 v[80:83], v[152:155], v[202:205], v[80:83]
	v_mfma_f32_16x16x32_bf16 v[132:135], v[148:151], v[164:167], v[132:135]
	v_mfma_f32_16x16x32_bf16 v[124:127], v[156:159], v[164:167], v[124:127]
	v_mfma_f32_16x16x32_bf16 v[116:119], v[148:151], v[172:175], v[116:119]
	v_mfma_f32_16x16x32_bf16 v[112:115], v[156:159], v[172:175], v[112:115]
	s_setprio 2
	s_barrier
	v_mfma_f32_16x16x32_bf16 v[100:103], v[148:151], v[198:201], v[100:103]
	v_mfma_f32_16x16x32_bf16 v[96:99], v[156:159], v[198:201], v[96:99]
	v_mfma_f32_16x16x32_bf16 v[84:87], v[148:151], v[206:209], v[84:87]
	v_mfma_f32_16x16x32_bf16 v[80:83], v[156:159], v[206:209], v[80:83]
	s_setprio 0
	s_add_i32 s8, s64, s37
	v_lshl_add_u64 v[178:179], s[40:41], 0, v[184:185]
	s_mov_b32 m0, s8
	ds_read_b128 v[160:163], v231 offset:16384
	ds_read_b128 v[164:167], v231 offset:17408
	ds_read_b128 v[168:171], v231 offset:18432
	ds_read_b128 v[172:175], v231 offset:19456
	ds_read_b128 v[194:197], v231 offset:20480
	ds_read_b128 v[198:201], v231 offset:21504
	ds_read_b128 v[202:205], v231 offset:22528
	ds_read_b128 v[206:209], v231 offset:23552
	global_load_lds_dwordx4 v[178:179], off
	s_add_i32 m0, s8, 0x2000
	s_add_u32 s8, s40, 0x60000
	v_lshl_add_u64 v[210:211], s[40:41], 0, v[188:189]
	s_addc_u32 s9, s41, 0
	s_add_i32 s64, s65, s37
	global_load_lds_dwordx4 v[210:211], off
	v_lshl_add_u64 v[212:213], s[8:9], 0, v[184:185]
	s_mov_b32 m0, s64
	v_lshl_add_u64 v[220:221], s[50:51], 0, v[186:187]
	global_load_lds_dwordx4 v[212:213], off
	v_lshl_add_u64 v[212:213], s[8:9], 0, v[188:189]
	s_add_i32 m0, s64, 0x2000
	s_nop 0
	global_load_lds_dwordx4 v[212:213], off
	v_lshl_add_u64 v[212:213], s[50:51], 0, v[182:183]
	s_mov_b32 m0, s60
	s_nop 0
	global_load_lds_dwordx4 v[212:213], off
	s_mov_b32 m0, s61
	s_nop 0
	global_load_lds_dwordx4 v[220:221], off
	s_waitcnt vmcnt(8)
	s_waitcnt lgkmcnt(0)
	s_barrier
	s_setprio 1
	v_mfma_f32_16x16x32_bf16 v[76:79], v[56:59], v[160:163], v[76:79]
	v_mfma_f32_16x16x32_bf16 v[72:75], v[64:67], v[160:163], v[72:75]
	v_mfma_f32_16x16x32_bf16 v[44:47], v[56:59], v[168:171], v[44:47]
	v_mfma_f32_16x16x32_bf16 v[40:43], v[64:67], v[168:171], v[40:43]
	v_mfma_f32_16x16x32_bf16 v[28:31], v[56:59], v[194:197], v[28:31]
	v_mfma_f32_16x16x32_bf16 v[24:27], v[64:67], v[194:197], v[24:27]
	v_mfma_f32_16x16x32_bf16 v[12:15], v[56:59], v[202:205], v[12:15]
	v_mfma_f32_16x16x32_bf16 v[8:11], v[64:67], v[202:205], v[8:11]
	v_mfma_f32_16x16x32_bf16 v[76:79], v[60:63], v[164:167], v[76:79]
	v_mfma_f32_16x16x32_bf16 v[72:75], v[68:71], v[164:167], v[72:75]
	v_mfma_f32_16x16x32_bf16 v[44:47], v[60:63], v[172:175], v[44:47]
	v_mfma_f32_16x16x32_bf16 v[40:43], v[68:71], v[172:175], v[40:43]
	v_mfma_f32_16x16x32_bf16 v[28:31], v[60:63], v[198:201], v[28:31]
	v_mfma_f32_16x16x32_bf16 v[24:27], v[68:71], v[198:201], v[24:27]
	v_mfma_f32_16x16x32_bf16 v[12:15], v[60:63], v[206:209], v[12:15]
	v_mfma_f32_16x16x32_bf16 v[8:11], v[68:71], v[206:209], v[8:11]
	v_mfma_f32_16x16x32_bf16 v[52:55], v[144:147], v[160:163], v[52:55]
	v_mfma_f32_16x16x32_bf16 v[48:51], v[152:155], v[160:163], v[48:51]
	v_mfma_f32_16x16x32_bf16 v[36:39], v[144:147], v[168:171], v[36:39]
	v_mfma_f32_16x16x32_bf16 v[32:35], v[152:155], v[168:171], v[32:35]
	v_mfma_f32_16x16x32_bf16 v[20:23], v[144:147], v[194:197], v[20:23]
	v_mfma_f32_16x16x32_bf16 v[16:19], v[152:155], v[194:197], v[16:19]
	v_mfma_f32_16x16x32_bf16 v[4:7], v[144:147], v[202:205], v[4:7]
	v_mfma_f32_16x16x32_bf16 v[0:3], v[152:155], v[202:205], v[0:3]
	v_mfma_f32_16x16x32_bf16 v[52:55], v[148:151], v[164:167], v[52:55]
	v_mfma_f32_16x16x32_bf16 v[48:51], v[156:159], v[164:167], v[48:51]
	v_mfma_f32_16x16x32_bf16 v[36:39], v[148:151], v[172:175], v[36:39]
	v_mfma_f32_16x16x32_bf16 v[32:35], v[156:159], v[172:175], v[32:35]
	s_setprio 2
	s_barrier
	v_mfma_f32_16x16x32_bf16 v[20:23], v[148:151], v[198:201], v[20:23]
	v_mfma_f32_16x16x32_bf16 v[16:19], v[156:159], v[198:201], v[16:19]
	v_mfma_f32_16x16x32_bf16 v[4:7], v[148:151], v[206:209], v[4:7]
	v_mfma_f32_16x16x32_bf16 v[0:3], v[156:159], v[206:209], v[0:3]
	s_setprio 0
	s_add_i32 s64, 0, 0x18000
	s_add_i32 s65, 0, 0x1c000
	v_add_u32_e32 v68, s64, v228
	v_add_u32_e32 v156, s65, v228
	ds_read_b128 v[56:59], v68
	ds_read_b128 v[60:63], v68 offset:1024
	ds_read_b128 v[64:67], v68 offset:2048
	ds_read_b128 v[68:71], v68 offset:3072
	ds_read_b128 v[144:147], v156
	ds_read_b128 v[148:151], v156 offset:1024
	ds_read_b128 v[152:155], v156 offset:2048
	ds_read_b128 v[156:159], v156 offset:3072
	s_add_u32 s8, s50, 0x60000
	s_addc_u32 s9, s51, 0
	s_mov_b32 m0, s62
	v_lshl_add_u64 v[222:223], s[8:9], 0, v[182:183]
	ds_read_b128 v[160:163], v231 offset:32768
	ds_read_b128 v[164:167], v231 offset:33792
	ds_read_b128 v[168:171], v231 offset:34816
	ds_read_b128 v[172:175], v231 offset:35840
	ds_read_b128 v[194:197], v231 offset:36864
	ds_read_b128 v[198:201], v231 offset:37888
	ds_read_b128 v[202:205], v231 offset:38912
	ds_read_b128 v[206:209], v231 offset:39936
	global_load_lds_dwordx4 v[222:223], off
	v_lshl_add_u64 v[222:223], s[8:9], 0, v[186:187]
	s_mov_b32 m0, s63
	s_nop 0
	global_load_lds_dwordx4 v[222:223], off
	s_waitcnt vmcnt(8)
	s_waitcnt lgkmcnt(0)
	s_barrier
	s_setprio 1
	v_mfma_f32_16x16x32_bf16 v[140:143], v[56:59], v[160:163], v[140:143]
	v_mfma_f32_16x16x32_bf16 v[136:139], v[64:67], v[160:163], v[136:139]
	v_mfma_f32_16x16x32_bf16 v[128:131], v[56:59], v[168:171], v[128:131]
	v_mfma_f32_16x16x32_bf16 v[120:123], v[64:67], v[168:171], v[120:123]
	v_mfma_f32_16x16x32_bf16 v[108:111], v[56:59], v[194:197], v[108:111]
	v_mfma_f32_16x16x32_bf16 v[104:107], v[64:67], v[194:197], v[104:107]
	v_mfma_f32_16x16x32_bf16 v[92:95], v[56:59], v[202:205], v[92:95]
	v_mfma_f32_16x16x32_bf16 v[88:91], v[64:67], v[202:205], v[88:91]
	v_mfma_f32_16x16x32_bf16 v[140:143], v[60:63], v[164:167], v[140:143]
	v_mfma_f32_16x16x32_bf16 v[136:139], v[68:71], v[164:167], v[136:139]
	v_mfma_f32_16x16x32_bf16 v[128:131], v[60:63], v[172:175], v[128:131]
	v_mfma_f32_16x16x32_bf16 v[120:123], v[68:71], v[172:175], v[120:123]
	v_mfma_f32_16x16x32_bf16 v[108:111], v[60:63], v[198:201], v[108:111]
	v_mfma_f32_16x16x32_bf16 v[104:107], v[68:71], v[198:201], v[104:107]
	v_mfma_f32_16x16x32_bf16 v[92:95], v[60:63], v[206:209], v[92:95]
	v_mfma_f32_16x16x32_bf16 v[88:91], v[68:71], v[206:209], v[88:91]
	v_mfma_f32_16x16x32_bf16 v[132:135], v[144:147], v[160:163], v[132:135]
	v_mfma_f32_16x16x32_bf16 v[124:127], v[152:155], v[160:163], v[124:127]
	v_mfma_f32_16x16x32_bf16 v[116:119], v[144:147], v[168:171], v[116:119]
	v_mfma_f32_16x16x32_bf16 v[112:115], v[152:155], v[168:171], v[112:115]
	v_mfma_f32_16x16x32_bf16 v[100:103], v[144:147], v[194:197], v[100:103]
	v_mfma_f32_16x16x32_bf16 v[96:99], v[152:155], v[194:197], v[96:99]
	v_mfma_f32_16x16x32_bf16 v[84:87], v[144:147], v[202:205], v[84:87]
	v_mfma_f32_16x16x32_bf16 v[80:83], v[152:155], v[202:205], v[80:83]
	v_mfma_f32_16x16x32_bf16 v[132:135], v[148:151], v[164:167], v[132:135]
	v_mfma_f32_16x16x32_bf16 v[124:127], v[156:159], v[164:167], v[124:127]
	v_mfma_f32_16x16x32_bf16 v[116:119], v[148:151], v[172:175], v[116:119]
	v_mfma_f32_16x16x32_bf16 v[112:115], v[156:159], v[172:175], v[112:115]
	s_setprio 2
	s_barrier
	v_mfma_f32_16x16x32_bf16 v[100:103], v[148:151], v[198:201], v[100:103]
	v_mfma_f32_16x16x32_bf16 v[96:99], v[156:159], v[198:201], v[96:99]
	v_mfma_f32_16x16x32_bf16 v[84:87], v[148:151], v[206:209], v[84:87]
	v_mfma_f32_16x16x32_bf16 v[80:83], v[156:159], v[206:209], v[80:83]
	s_setprio 0
	s_add_i32 s8, s64, s37
	v_lshl_add_u64 v[178:179], v[178:179], 0, s[34:35]
	s_mov_b32 m0, s8
	ds_read_b128 v[160:163], v231 offset:49152
	ds_read_b128 v[164:167], v231 offset:50176
	ds_read_b128 v[168:171], v231 offset:51200
	ds_read_b128 v[172:175], v231 offset:52224
	ds_read_b128 v[194:197], v231 offset:53248
	ds_read_b128 v[198:201], v231 offset:54272
	ds_read_b128 v[202:205], v231 offset:55296
	ds_read_b128 v[206:209], v231 offset:56320
	global_load_lds_dwordx4 v[178:179], off
	s_add_i32 m0, s8, 0x2000
	s_add_u32 s8, s40, 0x60080
	v_lshl_add_u64 v[178:179], v[210:211], 0, s[34:35]
	s_addc_u32 s9, s41, 0
	s_add_i32 s40, s65, s37
	global_load_lds_dwordx4 v[178:179], off
	v_lshl_add_u64 v[178:179], s[8:9], 0, v[184:185]
	s_mov_b32 m0, s40
	s_nop 0
	global_load_lds_dwordx4 v[178:179], off
	v_lshl_add_u64 v[178:179], s[8:9], 0, v[188:189]
	s_add_i32 m0, s40, 0x2000
	s_nop 0
	global_load_lds_dwordx4 v[178:179], off
	v_lshl_add_u64 v[178:179], v[212:213], 0, s[34:35]
	s_mov_b32 m0, s69
	s_nop 0
	global_load_lds_dwordx4 v[178:179], off
	v_lshl_add_u64 v[178:179], v[220:221], 0, s[34:35]
	s_mov_b32 m0, s72
	s_nop 0
	global_load_lds_dwordx4 v[178:179], off
	s_waitcnt vmcnt(8)
	s_waitcnt lgkmcnt(0)
	s_barrier
	s_setprio 1
	v_mfma_f32_16x16x32_bf16 v[76:79], v[56:59], v[160:163], v[76:79]
	v_mfma_f32_16x16x32_bf16 v[72:75], v[64:67], v[160:163], v[72:75]
	v_mfma_f32_16x16x32_bf16 v[44:47], v[56:59], v[168:171], v[44:47]
	v_mfma_f32_16x16x32_bf16 v[40:43], v[64:67], v[168:171], v[40:43]
	v_mfma_f32_16x16x32_bf16 v[28:31], v[56:59], v[194:197], v[28:31]
	v_mfma_f32_16x16x32_bf16 v[24:27], v[64:67], v[194:197], v[24:27]
	v_mfma_f32_16x16x32_bf16 v[12:15], v[56:59], v[202:205], v[12:15]
	v_mfma_f32_16x16x32_bf16 v[8:11], v[64:67], v[202:205], v[8:11]
	v_mfma_f32_16x16x32_bf16 v[76:79], v[60:63], v[164:167], v[76:79]
	v_mfma_f32_16x16x32_bf16 v[72:75], v[68:71], v[164:167], v[72:75]
	v_mfma_f32_16x16x32_bf16 v[44:47], v[60:63], v[172:175], v[44:47]
	v_mfma_f32_16x16x32_bf16 v[40:43], v[68:71], v[172:175], v[40:43]
	v_mfma_f32_16x16x32_bf16 v[28:31], v[60:63], v[198:201], v[28:31]
	v_mfma_f32_16x16x32_bf16 v[24:27], v[68:71], v[198:201], v[24:27]
	v_mfma_f32_16x16x32_bf16 v[12:15], v[60:63], v[206:209], v[12:15]
	v_mfma_f32_16x16x32_bf16 v[8:11], v[68:71], v[206:209], v[8:11]
	v_mfma_f32_16x16x32_bf16 v[52:55], v[144:147], v[160:163], v[52:55]
	v_mfma_f32_16x16x32_bf16 v[48:51], v[152:155], v[160:163], v[48:51]
	v_mfma_f32_16x16x32_bf16 v[36:39], v[144:147], v[168:171], v[36:39]
	v_mfma_f32_16x16x32_bf16 v[32:35], v[152:155], v[168:171], v[32:35]
	v_mfma_f32_16x16x32_bf16 v[20:23], v[144:147], v[194:197], v[20:23]
	v_mfma_f32_16x16x32_bf16 v[16:19], v[152:155], v[194:197], v[16:19]
	v_mfma_f32_16x16x32_bf16 v[4:7], v[144:147], v[202:205], v[4:7]
	v_mfma_f32_16x16x32_bf16 v[0:3], v[152:155], v[202:205], v[0:3]
	v_mfma_f32_16x16x32_bf16 v[52:55], v[148:151], v[164:167], v[52:55]
	v_mfma_f32_16x16x32_bf16 v[48:51], v[156:159], v[164:167], v[48:51]
	v_mfma_f32_16x16x32_bf16 v[36:39], v[148:151], v[172:175], v[36:39]
	v_mfma_f32_16x16x32_bf16 v[32:35], v[156:159], v[172:175], v[32:35]
	s_setprio 2
	s_barrier
	v_mfma_f32_16x16x32_bf16 v[20:23], v[148:151], v[198:201], v[20:23]
	v_mfma_f32_16x16x32_bf16 v[16:19], v[156:159], v[198:201], v[16:19]
	v_mfma_f32_16x16x32_bf16 v[4:7], v[148:151], v[206:209], v[4:7]
	v_mfma_f32_16x16x32_bf16 v[0:3], v[156:159], v[206:209], v[0:3]
	s_setprio 0
	s_add_i32 s83, s83, 2
	s_add_u32 s44, s44, 0x180
	s_addc_u32 s53, s53, 0
	s_cmp_gt_u32 s83, 13
	s_mov_b64 s[8:9], s[38:39]
	s_cbranch_scc0 .LBB0_953
	s_and_b64 vcc, exec, s[24:25]
	s_cbranch_vccz .LBB0_956
	s_barrier

.LBB0_1027:
	s_and_b32 s80, s3, 3
	s_add_i32 m0, s72, 0x18000
	v_lshl_add_u64 v[6:7], v[6:7], 0, s[34:35]
	s_lshl_b32 s3, s4, 13
	s_lshl_b32 s5, s80, 5
	s_lshl_b32 s16, s80, 12
	s_waitcnt vmcnt(2)
	s_barrier
	global_load_lds_dwordx4 v[6:7], off
	v_lshl_add_u64 v[4:5], v[4:5], 0, s[34:35]
	s_add_i32 m0, s72, 0x1a000
	s_add_i32 s81, s72, 0x8000
	s_add_i32 s82, s72, 0xa000
	global_load_lds_dwordx4 v[4:5], off
	v_lshl_add_u64 v[0:1], v[0:1], 0, s[34:35]
	s_mov_b32 m0, s81
	s_add_u32 s6, s38, 0x60080
	global_load_lds_dwordx4 v[0:1], off
	v_lshl_add_u64 v[0:1], v[2:3], 0, s[34:35]
	s_mov_b32 m0, s82
	s_addc_u32 s7, s39, 0
	global_load_lds_dwordx4 v[0:1], off
	s_add_i32 m0, s72, 0x1c000
	v_lshl_add_u64 v[0:1], s[6:7], 0, v[184:185]
	global_load_lds_dwordx4 v[0:1], off
	v_lshl_add_u64 v[0:1], s[6:7], 0, v[188:189]
	s_add_i32 m0, s72, 0x1e000
	v_lshlrev_b32_e32 v3, 2, v8
	global_load_lds_dwordx4 v[0:1], off
	v_and_b32_e32 v0, 15, v8
	v_bfe_u32 v1, v8, 4, 2
	v_lshlrev_b32_e32 v2, 6, v0
	v_lshlrev_b32_e32 v0, 10, v0
	s_movk_i32 s7, 0x600
	v_lshl_or_b32 v2, v1, 4, v2
	v_and_b32_e32 v3, 32, v3
	v_lshl_or_b32 v229, v1, 3, s5
	v_lshl_or_b32 v230, s4, 16, v0
	v_cmp_eq_u32_e64 s[4:5], 0, v1
	v_lshrrev_b32_e32 v1, 1, v13
	v_mul_lo_u32 v0, v15, s7
	s_movk_i32 s6, 0x6000
	v_bitop3_b32 v4, v2, s3, v3 bitop3:0xde
	s_cmpk_lt_u32 s2, 0x100
	v_mad_u64_u32 v[0:1], s[2:3], v1, s6, v[0:1]
	v_or_b32_e32 v0, v0, v14
	v_add_lshl_u32 v176, v0, v16, 1
	v_lshrrev_b32_e32 v1, 1, v9
	v_mul_lo_u32 v0, v11, s7
	v_bitop3_b32 v228, v2, s16, v3 bitop3:0xde
	s_cselect_b64 s[20:21], -1, 0
	s_ashr_i32 s16, s61, 4
	v_mad_u64_u32 v[0:1], s[2:3], v1, s6, v[0:1]
	s_waitcnt vmcnt(6)
	s_and_b32 s37, s61, 3
	s_addk_i32 s16, 0x80
	s_bfe_u32 s17, s61, 0x20002
	s_ashr_i32 s83, s60, 31
	s_ashr_i32 s91, s61, 31
	s_mov_b64 s[24:25], 0x60080
	v_or_b32_e32 v0, v0, v10
	s_cmp_lg_u64 s[48:49], 0
	v_lshl_add_u64 v[190:191], v[176:177], 0, s[24:25]
	v_add_lshl_u32 v176, v0, v12, 1
	v_or_b32_e32 v231, v229, v230
	s_mov_b32 s44, 0
	s_mul_i32 s37, s37, 6
	s_cselect_b64 s[22:23], -1, 0
	v_lshl_add_u64 v[192:193], v[176:177], 0, s[24:25]
	s_mov_b32 s63, 16
	v_add_u32_e32 v232, 0, v4
	s_mov_b32 s53, 0
	s_mov_b32 s92, 0
	s_barrier
	s_branch .LBB0_1030

.LBB0_1030:
	s_mov_b32 s2, s92
	s_add_i32 s92, s92, 1
	s_cmp_lg_u32 s2, 0
	s_cbranch_scc0 .LBB0_1034
	s_mov_b64 s[6:7], 0
	s_cmp_lg_u32 s92, 2
	s_mov_b64 s[26:27], 0
	s_mov_b32 s2, s41
	s_mov_b32 s62, s40
	s_mov_b32 s24, s25
	s_mov_b32 s3, s50
	s_cbranch_scc1 .LBB0_1033
	s_mov_b32 s3, 4
	s_mov_b64 s[26:27], -1
	s_mov_b32 s2, s16
	s_mov_b32 s62, s17
	s_mov_b32 s24, s37

.LBB0_1045:
	s_add_i32 s25, s63, -2
	s_add_u32 s93, s38, 0x180
	v_mov_b32_e32 v0, 0
	s_addc_u32 s94, s39, 0
	s_mov_b32 s40, 0
	v_mov_b32_e32 v1, v0
	v_mov_b32_e32 v2, v0
	v_mov_b32_e32 v3, v0
	v_mov_b32_e32 v4, v0
	v_mov_b32_e32 v5, v0
	v_mov_b32_e32 v6, v0
	v_mov_b32_e32 v7, v0
	v_mov_b32_e32 v16, v0
	v_mov_b32_e32 v17, v0
	v_mov_b32_e32 v18, v0
	v_mov_b32_e32 v19, v0
	s_waitcnt vmcnt(0)
	v_mov_b32_e32 v20, v0
	v_mov_b32_e32 v21, v0
	v_mov_b32_e32 v22, v0
	v_mov_b32_e32 v23, v0
	v_mov_b32_e32 v32, v0
	v_mov_b32_e32 v33, v0
	v_mov_b32_e32 v34, v0
	v_mov_b32_e32 v35, v0
	v_mov_b32_e32 v36, v0
	v_mov_b32_e32 v37, v0
	v_mov_b32_e32 v38, v0
	v_mov_b32_e32 v39, v0
	v_mov_b32_e32 v48, v0
	v_mov_b32_e32 v49, v0
	v_mov_b32_e32 v50, v0
	v_mov_b32_e32 v51, v0
	v_mov_b32_e32 v52, v0
	v_mov_b32_e32 v53, v0
	v_mov_b32_e32 v54, v0
	v_mov_b32_e32 v55, v0
	v_mov_b32_e32 v8, v0
	v_mov_b32_e32 v9, v0
	v_mov_b32_e32 v10, v0
	v_mov_b32_e32 v11, v0
	v_mov_b32_e32 v12, v0
	v_mov_b32_e32 v13, v0
	v_mov_b32_e32 v14, v0
	v_mov_b32_e32 v15, v0
	v_mov_b32_e32 v24, v0
	v_mov_b32_e32 v25, v0
	v_mov_b32_e32 v26, v0
	v_mov_b32_e32 v27, v0
	v_mov_b32_e32 v28, v0
	v_mov_b32_e32 v29, v0
	v_mov_b32_e32 v30, v0
	v_mov_b32_e32 v31, v0
	v_mov_b32_e32 v40, v0
	v_mov_b32_e32 v41, v0
	v_mov_b32_e32 v42, v0
	v_mov_b32_e32 v43, v0
	v_mov_b32_e32 v44, v0
	v_mov_b32_e32 v45, v0
	v_mov_b32_e32 v46, v0
	v_mov_b32_e32 v47, v0
	v_mov_b32_e32 v56, v0
	v_mov_b32_e32 v57, v0
	v_mov_b32_e32 v58, v0
	v_mov_b32_e32 v59, v0
	v_mov_b32_e32 v60, v0
	v_mov_b32_e32 v61, v0
	v_mov_b32_e32 v62, v0
	v_mov_b32_e32 v63, v0
	v_mov_b32_e32 v64, v0
	v_mov_b32_e32 v65, v0
	v_mov_b32_e32 v66, v0
	v_mov_b32_e32 v67, v0
	v_mov_b32_e32 v68, v0
	v_mov_b32_e32 v69, v0
	v_mov_b32_e32 v70, v0
	v_mov_b32_e32 v71, v0
	v_mov_b32_e32 v80, v0
	v_mov_b32_e32 v81, v0
	v_mov_b32_e32 v82, v0
	v_mov_b32_e32 v83, v0
	v_mov_b32_e32 v84, v0
	v_mov_b32_e32 v85, v0
	v_mov_b32_e32 v86, v0
	v_mov_b32_e32 v87, v0
	v_mov_b32_e32 v112, v0
	v_mov_b32_e32 v113, v0
	v_mov_b32_e32 v114, v0
	v_mov_b32_e32 v115, v0
	v_mov_b32_e32 v116, v0
	v_mov_b32_e32 v117, v0
	v_mov_b32_e32 v118, v0
	v_mov_b32_e32 v119, v0
	v_mov_b32_e32 v128, v0
	v_mov_b32_e32 v129, v0
	v_mov_b32_e32 v130, v0
	v_mov_b32_e32 v131, v0
	v_mov_b32_e32 v132, v0
	v_mov_b32_e32 v133, v0
	v_mov_b32_e32 v134, v0
	v_mov_b32_e32 v135, v0
	v_mov_b32_e32 v72, v0
	v_mov_b32_e32 v73, v0
	v_mov_b32_e32 v74, v0
	v_mov_b32_e32 v75, v0
	v_mov_b32_e32 v76, v0
	v_mov_b32_e32 v77, v0
	v_mov_b32_e32 v78, v0
	v_mov_b32_e32 v79, v0
	v_mov_b32_e32 v96, v0
	v_mov_b32_e32 v97, v0
	v_mov_b32_e32 v98, v0
	v_mov_b32_e32 v99, v0
	v_mov_b32_e32 v100, v0
	v_mov_b32_e32 v101, v0
	v_mov_b32_e32 v102, v0
	v_mov_b32_e32 v103, v0
	v_mov_b32_e32 v120, v0
	v_mov_b32_e32 v121, v0
	v_mov_b32_e32 v122, v0
	v_mov_b32_e32 v123, v0
	v_mov_b32_e32 v124, v0
	v_mov_b32_e32 v125, v0
	v_mov_b32_e32 v126, v0
	v_mov_b32_e32 v127, v0
	v_mov_b32_e32 v136, v0
	v_mov_b32_e32 v137, v0
	v_mov_b32_e32 v138, v0
	v_mov_b32_e32 v139, v0
	v_mov_b32_e32 v140, v0
	v_mov_b32_e32 v141, v0
	v_mov_b32_e32 v142, v0
	v_mov_b32_e32 v143, v0
.LBB0_1046:
	s_add_i32 s64, s40, 2
	s_add_u32 s38, s8, 0x180
	s_addc_u32 s39, s9, 0
	s_add_i32 s65, 0, 0x10000
	s_cmp_eq_u32 s25, s40
	s_cselect_b32 s51, s27, s39
	s_cselect_b32 s50, s26, s38
	s_cselect_b32 s41, s29, s94
	s_cselect_b32 s40, s28, s93
	s_add_i32 s66, 0, 0x14000
	v_add_u32_e32 v108, s65, v228
	v_add_u32_e32 v156, s66, v228
	ds_read_b128 v[88:91], v108
	ds_read_b128 v[92:95], v108 offset:1024
	ds_read_b128 v[104:107], v108 offset:2048
	ds_read_b128 v[108:111], v108 offset:3072
	ds_read_b128 v[144:147], v156
	ds_read_b128 v[148:151], v156 offset:1024
	ds_read_b128 v[152:155], v156 offset:2048
	ds_read_b128 v[156:159], v156 offset:3072
	v_lshl_add_u64 v[178:179], s[8:9], 0, v[192:193]
	s_add_i32 m0, s72, 0xc000
	ds_read_b128 v[160:163], v232
	ds_read_b128 v[164:167], v232 offset:1024
	ds_read_b128 v[168:171], v232 offset:2048
	ds_read_b128 v[172:175], v232 offset:3072
	ds_read_b128 v[194:197], v232 offset:4096
	ds_read_b128 v[198:201], v232 offset:5120
	ds_read_b128 v[202:205], v232 offset:6144
	ds_read_b128 v[206:209], v232 offset:7168
	global_load_lds_dwordx4 v[178:179], off
	v_lshl_add_u64 v[178:179], s[8:9], 0, v[190:191]
	s_add_i32 m0, s72, 0xe000
	s_nop 0
	global_load_lds_dwordx4 v[178:179], off
	s_waitcnt vmcnt(8)
	s_waitcnt lgkmcnt(0)
	s_barrier
	s_setprio 1
	v_mfma_f32_16x16x32_bf16 v[140:143], v[88:91], v[160:163], v[140:143]
	v_mfma_f32_16x16x32_bf16 v[136:139], v[104:107], v[160:163], v[136:139]
	v_mfma_f32_16x16x32_bf16 v[124:127], v[88:91], v[168:171], v[124:127]
	v_mfma_f32_16x16x32_bf16 v[120:123], v[104:107], v[168:171], v[120:123]
	v_mfma_f32_16x16x32_bf16 v[100:103], v[88:91], v[194:197], v[100:103]
	v_mfma_f32_16x16x32_bf16 v[96:99], v[104:107], v[194:197], v[96:99]
	v_mfma_f32_16x16x32_bf16 v[76:79], v[88:91], v[202:205], v[76:79]
	v_mfma_f32_16x16x32_bf16 v[72:75], v[104:107], v[202:205], v[72:75]
	v_mfma_f32_16x16x32_bf16 v[140:143], v[92:95], v[164:167], v[140:143]
	v_mfma_f32_16x16x32_bf16 v[136:139], v[108:111], v[164:167], v[136:139]
	v_mfma_f32_16x16x32_bf16 v[124:127], v[92:95], v[172:175], v[124:127]
	v_mfma_f32_16x16x32_bf16 v[120:123], v[108:111], v[172:175], v[120:123]
	v_mfma_f32_16x16x32_bf16 v[100:103], v[92:95], v[198:201], v[100:103]
	v_mfma_f32_16x16x32_bf16 v[96:99], v[108:111], v[198:201], v[96:99]
	v_mfma_f32_16x16x32_bf16 v[76:79], v[92:95], v[206:209], v[76:79]
	v_mfma_f32_16x16x32_bf16 v[72:75], v[108:111], v[206:209], v[72:75]
	v_mfma_f32_16x16x32_bf16 v[132:135], v[144:147], v[160:163], v[132:135]
	v_mfma_f32_16x16x32_bf16 v[128:131], v[152:155], v[160:163], v[128:131]
	v_mfma_f32_16x16x32_bf16 v[116:119], v[144:147], v[168:171], v[116:119]
	v_mfma_f32_16x16x32_bf16 v[112:115], v[152:155], v[168:171], v[112:115]
	v_mfma_f32_16x16x32_bf16 v[84:87], v[144:147], v[194:197], v[84:87]
	v_mfma_f32_16x16x32_bf16 v[80:83], v[152:155], v[194:197], v[80:83]
	v_mfma_f32_16x16x32_bf16 v[68:71], v[144:147], v[202:205], v[68:71]
	v_mfma_f32_16x16x32_bf16 v[64:67], v[152:155], v[202:205], v[64:67]
	v_mfma_f32_16x16x32_bf16 v[132:135], v[148:151], v[164:167], v[132:135]
	v_mfma_f32_16x16x32_bf16 v[128:131], v[156:159], v[164:167], v[128:131]
	v_mfma_f32_16x16x32_bf16 v[116:119], v[148:151], v[172:175], v[116:119]
	v_mfma_f32_16x16x32_bf16 v[112:115], v[156:159], v[172:175], v[112:115]
	s_setprio 2
	s_barrier
	v_mfma_f32_16x16x32_bf16 v[84:87], v[148:151], v[198:201], v[84:87]
	v_mfma_f32_16x16x32_bf16 v[80:83], v[156:159], v[198:201], v[80:83]
	v_mfma_f32_16x16x32_bf16 v[68:71], v[148:151], v[206:209], v[68:71]
	v_mfma_f32_16x16x32_bf16 v[64:67], v[156:159], v[206:209], v[64:67]
	s_setprio 0
	s_add_i32 s8, s65, s68
	v_lshl_add_u64 v[178:179], s[40:41], 0, v[184:185]
	s_mov_b32 m0, s8
	ds_read_b128 v[160:163], v232 offset:16384
	ds_read_b128 v[164:167], v232 offset:17408
	ds_read_b128 v[168:171], v232 offset:18432
	ds_read_b128 v[172:175], v232 offset:19456
	ds_read_b128 v[194:197], v232 offset:20480
	ds_read_b128 v[198:201], v232 offset:21504
	ds_read_b128 v[202:205], v232 offset:22528
	ds_read_b128 v[206:209], v232 offset:23552
	global_load_lds_dwordx4 v[178:179], off
	s_add_i32 m0, s8, 0x2000
	s_add_u32 s8, s40, 0x60000
	v_lshl_add_u64 v[210:211], s[40:41], 0, v[188:189]
	s_addc_u32 s9, s41, 0
	s_add_i32 s65, s66, s68
	global_load_lds_dwordx4 v[210:211], off
	v_lshl_add_u64 v[212:213], s[8:9], 0, v[184:185]
	s_mov_b32 m0, s65
	v_lshl_add_u64 v[220:221], s[50:51], 0, v[186:187]
	global_load_lds_dwordx4 v[212:213], off
	v_lshl_add_u64 v[212:213], s[8:9], 0, v[188:189]
	s_add_i32 m0, s65, 0x2000
	s_nop 0
	global_load_lds_dwordx4 v[212:213], off
	v_lshl_add_u64 v[212:213], s[50:51], 0, v[182:183]
	s_mov_b32 m0, s72
	s_nop 0
	global_load_lds_dwordx4 v[212:213], off
	s_mov_b32 m0, s73
	s_nop 0
	global_load_lds_dwordx4 v[220:221], off
	s_waitcnt vmcnt(8)
	s_waitcnt lgkmcnt(0)
	s_barrier
	s_setprio 1
	v_mfma_f32_16x16x32_bf16 v[60:63], v[88:91], v[160:163], v[60:63]
	v_mfma_f32_16x16x32_bf16 v[56:59], v[104:107], v[160:163], v[56:59]
	v_mfma_f32_16x16x32_bf16 v[44:47], v[88:91], v[168:171], v[44:47]
	v_mfma_f32_16x16x32_bf16 v[40:43], v[104:107], v[168:171], v[40:43]
	v_mfma_f32_16x16x32_bf16 v[28:31], v[88:91], v[194:197], v[28:31]
	v_mfma_f32_16x16x32_bf16 v[24:27], v[104:107], v[194:197], v[24:27]
	v_mfma_f32_16x16x32_bf16 v[12:15], v[88:91], v[202:205], v[12:15]
	v_mfma_f32_16x16x32_bf16 v[8:11], v[104:107], v[202:205], v[8:11]
	v_mfma_f32_16x16x32_bf16 v[60:63], v[92:95], v[164:167], v[60:63]
	v_mfma_f32_16x16x32_bf16 v[56:59], v[108:111], v[164:167], v[56:59]
	v_mfma_f32_16x16x32_bf16 v[44:47], v[92:95], v[172:175], v[44:47]
	v_mfma_f32_16x16x32_bf16 v[40:43], v[108:111], v[172:175], v[40:43]
	v_mfma_f32_16x16x32_bf16 v[28:31], v[92:95], v[198:201], v[28:31]
	v_mfma_f32_16x16x32_bf16 v[24:27], v[108:111], v[198:201], v[24:27]
	v_mfma_f32_16x16x32_bf16 v[12:15], v[92:95], v[206:209], v[12:15]
	v_mfma_f32_16x16x32_bf16 v[8:11], v[108:111], v[206:209], v[8:11]
	v_mfma_f32_16x16x32_bf16 v[52:55], v[144:147], v[160:163], v[52:55]
	v_mfma_f32_16x16x32_bf16 v[48:51], v[152:155], v[160:163], v[48:51]
	v_mfma_f32_16x16x32_bf16 v[36:39], v[144:147], v[168:171], v[36:39]
	v_mfma_f32_16x16x32_bf16 v[32:35], v[152:155], v[168:171], v[32:35]
	v_mfma_f32_16x16x32_bf16 v[20:23], v[144:147], v[194:197], v[20:23]
	v_mfma_f32_16x16x32_bf16 v[16:19], v[152:155], v[194:197], v[16:19]
	v_mfma_f32_16x16x32_bf16 v[4:7], v[144:147], v[202:205], v[4:7]
	v_mfma_f32_16x16x32_bf16 v[0:3], v[152:155], v[202:205], v[0:3]
	v_mfma_f32_16x16x32_bf16 v[52:55], v[148:151], v[164:167], v[52:55]
	v_mfma_f32_16x16x32_bf16 v[48:51], v[156:159], v[164:167], v[48:51]
	v_mfma_f32_16x16x32_bf16 v[36:39], v[148:151], v[172:175], v[36:39]
	v_mfma_f32_16x16x32_bf16 v[32:35], v[156:159], v[172:175], v[32:35]
	s_setprio 2
	s_barrier
	v_mfma_f32_16x16x32_bf16 v[20:23], v[148:151], v[198:201], v[20:23]
	v_mfma_f32_16x16x32_bf16 v[16:19], v[156:159], v[198:201], v[16:19]
	v_mfma_f32_16x16x32_bf16 v[4:7], v[148:151], v[206:209], v[4:7]
	v_mfma_f32_16x16x32_bf16 v[0:3], v[156:159], v[206:209], v[0:3]
	s_setprio 0
	s_add_i32 s65, 0, 0x18000
	s_add_i32 s66, 0, 0x1c000
	v_add_u32_e32 v108, s65, v228
	v_add_u32_e32 v156, s66, v228
	ds_read_b128 v[88:91], v108
	ds_read_b128 v[92:95], v108 offset:1024
	ds_read_b128 v[104:107], v108 offset:2048
	ds_read_b128 v[108:111], v108 offset:3072
	ds_read_b128 v[144:147], v156
	ds_read_b128 v[148:151], v156 offset:1024
	ds_read_b128 v[152:155], v156 offset:2048
	ds_read_b128 v[156:159], v156 offset:3072
	s_add_u32 s8, s50, 0x60000
	s_addc_u32 s9, s51, 0
	s_mov_b32 m0, s74
	v_lshl_add_u64 v[222:223], s[8:9], 0, v[182:183]
	ds_read_b128 v[160:163], v232 offset:32768
	ds_read_b128 v[164:167], v232 offset:33792
	ds_read_b128 v[168:171], v232 offset:34816
	ds_read_b128 v[172:175], v232 offset:35840
	ds_read_b128 v[194:197], v232 offset:36864
	ds_read_b128 v[198:201], v232 offset:37888
	ds_read_b128 v[202:205], v232 offset:38912
	ds_read_b128 v[206:209], v232 offset:39936
	global_load_lds_dwordx4 v[222:223], off
	v_lshl_add_u64 v[222:223], s[8:9], 0, v[186:187]
	s_mov_b32 m0, s75
	s_nop 0
	global_load_lds_dwordx4 v[222:223], off
	s_waitcnt vmcnt(8)
	s_waitcnt lgkmcnt(0)
	s_barrier
	s_setprio 1
	v_mfma_f32_16x16x32_bf16 v[140:143], v[88:91], v[160:163], v[140:143]
	v_mfma_f32_16x16x32_bf16 v[136:139], v[104:107], v[160:163], v[136:139]
	v_mfma_f32_16x16x32_bf16 v[124:127], v[88:91], v[168:171], v[124:127]
	v_mfma_f32_16x16x32_bf16 v[120:123], v[104:107], v[168:171], v[120:123]
	v_mfma_f32_16x16x32_bf16 v[100:103], v[88:91], v[194:197], v[100:103]
	v_mfma_f32_16x16x32_bf16 v[96:99], v[104:107], v[194:197], v[96:99]
	v_mfma_f32_16x16x32_bf16 v[76:79], v[88:91], v[202:205], v[76:79]
	v_mfma_f32_16x16x32_bf16 v[72:75], v[104:107], v[202:205], v[72:75]
	v_mfma_f32_16x16x32_bf16 v[140:143], v[92:95], v[164:167], v[140:143]
	v_mfma_f32_16x16x32_bf16 v[136:139], v[108:111], v[164:167], v[136:139]
	v_mfma_f32_16x16x32_bf16 v[124:127], v[92:95], v[172:175], v[124:127]
	v_mfma_f32_16x16x32_bf16 v[120:123], v[108:111], v[172:175], v[120:123]
	v_mfma_f32_16x16x32_bf16 v[100:103], v[92:95], v[198:201], v[100:103]
	v_mfma_f32_16x16x32_bf16 v[96:99], v[108:111], v[198:201], v[96:99]
	v_mfma_f32_16x16x32_bf16 v[76:79], v[92:95], v[206:209], v[76:79]
	v_mfma_f32_16x16x32_bf16 v[72:75], v[108:111], v[206:209], v[72:75]
	v_mfma_f32_16x16x32_bf16 v[132:135], v[144:147], v[160:163], v[132:135]
	v_mfma_f32_16x16x32_bf16 v[128:131], v[152:155], v[160:163], v[128:131]
	v_mfma_f32_16x16x32_bf16 v[116:119], v[144:147], v[168:171], v[116:119]
	v_mfma_f32_16x16x32_bf16 v[112:115], v[152:155], v[168:171], v[112:115]
	v_mfma_f32_16x16x32_bf16 v[84:87], v[144:147], v[194:197], v[84:87]
	v_mfma_f32_16x16x32_bf16 v[80:83], v[152:155], v[194:197], v[80:83]
	v_mfma_f32_16x16x32_bf16 v[68:71], v[144:147], v[202:205], v[68:71]
	v_mfma_f32_16x16x32_bf16 v[64:67], v[152:155], v[202:205], v[64:67]
	v_mfma_f32_16x16x32_bf16 v[132:135], v[148:151], v[164:167], v[132:135]
	v_mfma_f32_16x16x32_bf16 v[128:131], v[156:159], v[164:167], v[128:131]
	v_mfma_f32_16x16x32_bf16 v[116:119], v[148:151], v[172:175], v[116:119]
	v_mfma_f32_16x16x32_bf16 v[112:115], v[156:159], v[172:175], v[112:115]
	s_setprio 2
	s_barrier
	v_mfma_f32_16x16x32_bf16 v[84:87], v[148:151], v[198:201], v[84:87]
	v_mfma_f32_16x16x32_bf16 v[80:83], v[156:159], v[198:201], v[80:83]
	v_mfma_f32_16x16x32_bf16 v[68:71], v[148:151], v[206:209], v[68:71]
	v_mfma_f32_16x16x32_bf16 v[64:67], v[156:159], v[206:209], v[64:67]
	s_setprio 0
	s_add_i32 s8, s65, s68
	v_lshl_add_u64 v[178:179], v[178:179], 0, s[34:35]
	s_mov_b32 m0, s8
	ds_read_b128 v[160:163], v232 offset:49152
	ds_read_b128 v[164:167], v232 offset:50176
	ds_read_b128 v[168:171], v232 offset:51200
	ds_read_b128 v[172:175], v232 offset:52224
	ds_read_b128 v[194:197], v232 offset:53248
	ds_read_b128 v[198:201], v232 offset:54272
	ds_read_b128 v[202:205], v232 offset:55296
	ds_read_b128 v[206:209], v232 offset:56320
	global_load_lds_dwordx4 v[178:179], off
	s_add_i32 m0, s8, 0x2000
	s_add_u32 s8, s40, 0x60080
	v_lshl_add_u64 v[178:179], v[210:211], 0, s[34:35]
	s_addc_u32 s9, s41, 0
	s_add_i32 s40, s66, s68
	global_load_lds_dwordx4 v[178:179], off
	v_lshl_add_u64 v[178:179], s[8:9], 0, v[184:185]
	s_mov_b32 m0, s40
	s_nop 0
	global_load_lds_dwordx4 v[178:179], off
	v_lshl_add_u64 v[178:179], s[8:9], 0, v[188:189]
	s_add_i32 m0, s40, 0x2000
	s_nop 0
	global_load_lds_dwordx4 v[178:179], off
	v_lshl_add_u64 v[178:179], v[212:213], 0, s[34:35]
	s_mov_b32 m0, s81
	s_nop 0
	global_load_lds_dwordx4 v[178:179], off
	v_lshl_add_u64 v[178:179], v[220:221], 0, s[34:35]
	s_mov_b32 m0, s82
	s_nop 0
	global_load_lds_dwordx4 v[178:179], off
	s_waitcnt vmcnt(8)
	s_waitcnt lgkmcnt(0)
	s_barrier
	s_setprio 1
	v_mfma_f32_16x16x32_bf16 v[60:63], v[88:91], v[160:163], v[60:63]
	v_mfma_f32_16x16x32_bf16 v[56:59], v[104:107], v[160:163], v[56:59]
	v_mfma_f32_16x16x32_bf16 v[44:47], v[88:91], v[168:171], v[44:47]
	v_mfma_f32_16x16x32_bf16 v[40:43], v[104:107], v[168:171], v[40:43]
	v_mfma_f32_16x16x32_bf16 v[28:31], v[88:91], v[194:197], v[28:31]
	v_mfma_f32_16x16x32_bf16 v[24:27], v[104:107], v[194:197], v[24:27]
	v_mfma_f32_16x16x32_bf16 v[12:15], v[88:91], v[202:205], v[12:15]
	v_mfma_f32_16x16x32_bf16 v[8:11], v[104:107], v[202:205], v[8:11]
	v_mfma_f32_16x16x32_bf16 v[60:63], v[92:95], v[164:167], v[60:63]
	v_mfma_f32_16x16x32_bf16 v[56:59], v[108:111], v[164:167], v[56:59]
	v_mfma_f32_16x16x32_bf16 v[44:47], v[92:95], v[172:175], v[44:47]
	v_mfma_f32_16x16x32_bf16 v[40:43], v[108:111], v[172:175], v[40:43]
	v_mfma_f32_16x16x32_bf16 v[28:31], v[92:95], v[198:201], v[28:31]
	v_mfma_f32_16x16x32_bf16 v[24:27], v[108:111], v[198:201], v[24:27]
	v_mfma_f32_16x16x32_bf16 v[12:15], v[92:95], v[206:209], v[12:15]
	v_mfma_f32_16x16x32_bf16 v[8:11], v[108:111], v[206:209], v[8:11]
	v_mfma_f32_16x16x32_bf16 v[52:55], v[144:147], v[160:163], v[52:55]
	v_mfma_f32_16x16x32_bf16 v[48:51], v[152:155], v[160:163], v[48:51]
	v_mfma_f32_16x16x32_bf16 v[36:39], v[144:147], v[168:171], v[36:39]
	v_mfma_f32_16x16x32_bf16 v[32:35], v[152:155], v[168:171], v[32:35]
	v_mfma_f32_16x16x32_bf16 v[20:23], v[144:147], v[194:197], v[20:23]
	v_mfma_f32_16x16x32_bf16 v[16:19], v[152:155], v[194:197], v[16:19]
	v_mfma_f32_16x16x32_bf16 v[4:7], v[144:147], v[202:205], v[4:7]
	v_mfma_f32_16x16x32_bf16 v[0:3], v[152:155], v[202:205], v[0:3]
	v_mfma_f32_16x16x32_bf16 v[52:55], v[148:151], v[164:167], v[52:55]
	v_mfma_f32_16x16x32_bf16 v[48:51], v[156:159], v[164:167], v[48:51]
	v_mfma_f32_16x16x32_bf16 v[36:39], v[148:151], v[172:175], v[36:39]
	v_mfma_f32_16x16x32_bf16 v[32:35], v[156:159], v[172:175], v[32:35]
	s_setprio 2
	s_barrier
	v_mfma_f32_16x16x32_bf16 v[20:23], v[148:151], v[198:201], v[20:23]
	v_mfma_f32_16x16x32_bf16 v[16:19], v[156:159], v[198:201], v[16:19]
	v_mfma_f32_16x16x32_bf16 v[4:7], v[148:151], v[206:209], v[4:7]
	v_mfma_f32_16x16x32_bf16 v[0:3], v[156:159], v[206:209], v[0:3]
	s_setprio 0
	s_add_u32 s93, s93, 0x180
	s_addc_u32 s94, s94, 0
	s_cmp_ge_i32 s64, s63
	s_mov_b64 s[8:9], s[38:39]
	s_mov_b32 s40, s64
	s_cbranch_scc0 .LBB0_1046
	s_and_b64 vcc, exec, s[20:21]
	s_cbranch_vccz .LBB0_1049

.LBB0_1103:
	s_and_b64 vcc, exec, s[6:7]
	s_mov_b64 s[6:7], -1
	s_cbranch_vccnz .LBB0_1029
	s_cmp_lg_u32 s3, 0
	s_cselect_b32 s63, s3, 16
	s_andn2_b64 vcc, exec, s[0:1]
	s_cbranch_vccnz .LBB0_1028
	s_barrier
	s_branch .LBB0_1028

.LBB0_1131:
	s_add_u32 s42, s6, 0xfffc0080
	s_addc_u32 s43, s7, -1
	s_add_i32 s64, 0, 0x10000
	s_cmp_eq_u32 s92, 12
	s_cselect_b32 s51, s27, s43
	s_cselect_b32 s50, s41, s42
	s_cselect_b32 s43, s25, s53
	s_cselect_b32 s42, s44, s52
	s_add_i32 s66, 0, 0x14000
	v_add_u32_e32 v68, s64, v228
	v_add_u32_e32 v156, s66, v228
	ds_read_b128 v[56:59], v68
	ds_read_b128 v[60:63], v68 offset:1024
	ds_read_b128 v[64:67], v68 offset:2048
	ds_read_b128 v[68:71], v68 offset:3072
	ds_read_b128 v[144:147], v156
	ds_read_b128 v[148:151], v156 offset:1024
	ds_read_b128 v[152:155], v156 offset:2048
	ds_read_b128 v[156:159], v156 offset:3072
	v_lshl_add_u64 v[178:179], s[6:7], 0, v[192:193]
	s_add_i32 m0, s17, 0xc000
	ds_read_b128 v[160:163], v231
	ds_read_b128 v[164:167], v231 offset:1024
	ds_read_b128 v[168:171], v231 offset:2048
	ds_read_b128 v[172:175], v231 offset:3072
	ds_read_b128 v[194:197], v231 offset:4096
	ds_read_b128 v[198:201], v231 offset:5120
	ds_read_b128 v[202:205], v231 offset:6144
	ds_read_b128 v[206:209], v231 offset:7168
	global_load_lds_dwordx4 v[178:179], off
	v_lshl_add_u64 v[178:179], s[6:7], 0, v[190:191]
	s_add_i32 m0, s17, 0xe000
	s_nop 0
	global_load_lds_dwordx4 v[178:179], off
	s_waitcnt vmcnt(8)
	s_waitcnt lgkmcnt(0)
	s_barrier
	s_setprio 1
	v_mfma_f32_16x16x32_bf16 v[140:143], v[56:59], v[160:163], v[140:143]
	v_mfma_f32_16x16x32_bf16 v[136:139], v[64:67], v[160:163], v[136:139]
	v_mfma_f32_16x16x32_bf16 v[128:131], v[56:59], v[168:171], v[128:131]
	v_mfma_f32_16x16x32_bf16 v[120:123], v[64:67], v[168:171], v[120:123]
	v_mfma_f32_16x16x32_bf16 v[108:111], v[56:59], v[194:197], v[108:111]
	v_mfma_f32_16x16x32_bf16 v[104:107], v[64:67], v[194:197], v[104:107]
	v_mfma_f32_16x16x32_bf16 v[92:95], v[56:59], v[202:205], v[92:95]
	v_mfma_f32_16x16x32_bf16 v[88:91], v[64:67], v[202:205], v[88:91]
	v_mfma_f32_16x16x32_bf16 v[140:143], v[60:63], v[164:167], v[140:143]
	v_mfma_f32_16x16x32_bf16 v[136:139], v[68:71], v[164:167], v[136:139]
	v_mfma_f32_16x16x32_bf16 v[128:131], v[60:63], v[172:175], v[128:131]
	v_mfma_f32_16x16x32_bf16 v[120:123], v[68:71], v[172:175], v[120:123]
	v_mfma_f32_16x16x32_bf16 v[108:111], v[60:63], v[198:201], v[108:111]
	v_mfma_f32_16x16x32_bf16 v[104:107], v[68:71], v[198:201], v[104:107]
	v_mfma_f32_16x16x32_bf16 v[92:95], v[60:63], v[206:209], v[92:95]
	v_mfma_f32_16x16x32_bf16 v[88:91], v[68:71], v[206:209], v[88:91]
	v_mfma_f32_16x16x32_bf16 v[132:135], v[144:147], v[160:163], v[132:135]
	v_mfma_f32_16x16x32_bf16 v[124:127], v[152:155], v[160:163], v[124:127]
	v_mfma_f32_16x16x32_bf16 v[116:119], v[144:147], v[168:171], v[116:119]
	v_mfma_f32_16x16x32_bf16 v[112:115], v[152:155], v[168:171], v[112:115]
	v_mfma_f32_16x16x32_bf16 v[100:103], v[144:147], v[194:197], v[100:103]
	v_mfma_f32_16x16x32_bf16 v[96:99], v[152:155], v[194:197], v[96:99]
	v_mfma_f32_16x16x32_bf16 v[84:87], v[144:147], v[202:205], v[84:87]
	v_mfma_f32_16x16x32_bf16 v[80:83], v[152:155], v[202:205], v[80:83]
	v_mfma_f32_16x16x32_bf16 v[132:135], v[148:151], v[164:167], v[132:135]
	v_mfma_f32_16x16x32_bf16 v[124:127], v[156:159], v[164:167], v[124:127]
	v_mfma_f32_16x16x32_bf16 v[116:119], v[148:151], v[172:175], v[116:119]
	v_mfma_f32_16x16x32_bf16 v[112:115], v[156:159], v[172:175], v[112:115]
	s_setprio 2
	s_barrier
	v_mfma_f32_16x16x32_bf16 v[100:103], v[148:151], v[198:201], v[100:103]
	v_mfma_f32_16x16x32_bf16 v[96:99], v[156:159], v[198:201], v[96:99]
	v_mfma_f32_16x16x32_bf16 v[84:87], v[148:151], v[206:209], v[84:87]
	v_mfma_f32_16x16x32_bf16 v[80:83], v[156:159], v[206:209], v[80:83]
	s_setprio 0
	s_add_i32 s64, s64, s68
	v_lshl_add_u64 v[178:179], s[42:43], 0, v[184:185]
	s_mov_b32 m0, s64
	ds_read_b128 v[160:163], v231 offset:16384
	ds_read_b128 v[164:167], v231 offset:17408
	ds_read_b128 v[168:171], v231 offset:18432
	ds_read_b128 v[172:175], v231 offset:19456
	ds_read_b128 v[194:197], v231 offset:20480
	ds_read_b128 v[198:201], v231 offset:21504
	ds_read_b128 v[202:205], v231 offset:22528
	ds_read_b128 v[206:209], v231 offset:23552
	global_load_lds_dwordx4 v[178:179], off
	s_add_i32 m0, s64, 0x2000
	s_add_u32 s64, s42, 0x40000
	v_lshl_add_u64 v[210:211], s[42:43], 0, v[188:189]
	s_addc_u32 s65, s43, 0
	s_add_i32 s66, s66, s68
	global_load_lds_dwordx4 v[210:211], off
	v_lshl_add_u64 v[212:213], s[64:65], 0, v[184:185]
	s_mov_b32 m0, s66
	v_lshl_add_u64 v[220:221], s[50:51], 0, v[186:187]
	global_load_lds_dwordx4 v[212:213], off
	v_lshl_add_u64 v[212:213], s[64:65], 0, v[188:189]
	s_add_i32 m0, s66, 0x2000
	s_nop 0
	global_load_lds_dwordx4 v[212:213], off
	v_lshl_add_u64 v[212:213], s[50:51], 0, v[182:183]
	s_mov_b32 m0, s17
	s_nop 0
	global_load_lds_dwordx4 v[212:213], off
	s_mov_b32 m0, s69
	s_nop 0
	global_load_lds_dwordx4 v[220:221], off
	s_waitcnt vmcnt(8)
	s_waitcnt lgkmcnt(0)
	s_barrier
	s_setprio 1
	v_mfma_f32_16x16x32_bf16 v[76:79], v[56:59], v[160:163], v[76:79]
	v_mfma_f32_16x16x32_bf16 v[72:75], v[64:67], v[160:163], v[72:75]
	v_mfma_f32_16x16x32_bf16 v[44:47], v[56:59], v[168:171], v[44:47]
	v_mfma_f32_16x16x32_bf16 v[40:43], v[64:67], v[168:171], v[40:43]
	v_mfma_f32_16x16x32_bf16 v[28:31], v[56:59], v[194:197], v[28:31]
	v_mfma_f32_16x16x32_bf16 v[24:27], v[64:67], v[194:197], v[24:27]
	v_mfma_f32_16x16x32_bf16 v[12:15], v[56:59], v[202:205], v[12:15]
	v_mfma_f32_16x16x32_bf16 v[8:11], v[64:67], v[202:205], v[8:11]
	v_mfma_f32_16x16x32_bf16 v[76:79], v[60:63], v[164:167], v[76:79]
	v_mfma_f32_16x16x32_bf16 v[72:75], v[68:71], v[164:167], v[72:75]
	v_mfma_f32_16x16x32_bf16 v[44:47], v[60:63], v[172:175], v[44:47]
	v_mfma_f32_16x16x32_bf16 v[40:43], v[68:71], v[172:175], v[40:43]
	v_mfma_f32_16x16x32_bf16 v[28:31], v[60:63], v[198:201], v[28:31]
	v_mfma_f32_16x16x32_bf16 v[24:27], v[68:71], v[198:201], v[24:27]
	v_mfma_f32_16x16x32_bf16 v[12:15], v[60:63], v[206:209], v[12:15]
	v_mfma_f32_16x16x32_bf16 v[8:11], v[68:71], v[206:209], v[8:11]
	v_mfma_f32_16x16x32_bf16 v[52:55], v[144:147], v[160:163], v[52:55]
	v_mfma_f32_16x16x32_bf16 v[48:51], v[152:155], v[160:163], v[48:51]
	v_mfma_f32_16x16x32_bf16 v[36:39], v[144:147], v[168:171], v[36:39]
	v_mfma_f32_16x16x32_bf16 v[32:35], v[152:155], v[168:171], v[32:35]
	v_mfma_f32_16x16x32_bf16 v[20:23], v[144:147], v[194:197], v[20:23]
	v_mfma_f32_16x16x32_bf16 v[16:19], v[152:155], v[194:197], v[16:19]
	v_mfma_f32_16x16x32_bf16 v[4:7], v[144:147], v[202:205], v[4:7]
	v_mfma_f32_16x16x32_bf16 v[0:3], v[152:155], v[202:205], v[0:3]
	v_mfma_f32_16x16x32_bf16 v[52:55], v[148:151], v[164:167], v[52:55]
	v_mfma_f32_16x16x32_bf16 v[48:51], v[156:159], v[164:167], v[48:51]
	v_mfma_f32_16x16x32_bf16 v[36:39], v[148:151], v[172:175], v[36:39]
	v_mfma_f32_16x16x32_bf16 v[32:35], v[156:159], v[172:175], v[32:35]
	s_setprio 2
	s_barrier
	v_mfma_f32_16x16x32_bf16 v[20:23], v[148:151], v[198:201], v[20:23]
	v_mfma_f32_16x16x32_bf16 v[16:19], v[156:159], v[198:201], v[16:19]
	v_mfma_f32_16x16x32_bf16 v[4:7], v[148:151], v[206:209], v[4:7]
	v_mfma_f32_16x16x32_bf16 v[0:3], v[156:159], v[206:209], v[0:3]
	s_setprio 0
	s_add_i32 s64, 0, 0x18000
	s_add_i32 s65, 0, 0x1c000
	v_add_u32_e32 v68, s64, v228
	v_add_u32_e32 v156, s65, v228
	ds_read_b128 v[56:59], v68
	ds_read_b128 v[60:63], v68 offset:1024
	ds_read_b128 v[64:67], v68 offset:2048
	ds_read_b128 v[68:71], v68 offset:3072
	ds_read_b128 v[144:147], v156
	ds_read_b128 v[148:151], v156 offset:1024
	ds_read_b128 v[152:155], v156 offset:2048
	ds_read_b128 v[156:159], v156 offset:3072
	s_add_u32 s50, s50, 0x40000
	s_addc_u32 s51, s51, 0
	s_mov_b32 m0, s72
	v_lshl_add_u64 v[222:223], s[50:51], 0, v[182:183]
	ds_read_b128 v[160:163], v231 offset:32768
	ds_read_b128 v[164:167], v231 offset:33792
	ds_read_b128 v[168:171], v231 offset:34816
	ds_read_b128 v[172:175], v231 offset:35840
	ds_read_b128 v[194:197], v231 offset:36864
	ds_read_b128 v[198:201], v231 offset:37888
	ds_read_b128 v[202:205], v231 offset:38912
	ds_read_b128 v[206:209], v231 offset:39936
	global_load_lds_dwordx4 v[222:223], off
	v_lshl_add_u64 v[222:223], s[50:51], 0, v[186:187]
	s_mov_b32 m0, s73
	s_nop 0
	global_load_lds_dwordx4 v[222:223], off
	s_waitcnt vmcnt(8)
	s_waitcnt lgkmcnt(0)
	s_barrier
	s_setprio 1
	v_mfma_f32_16x16x32_bf16 v[140:143], v[56:59], v[160:163], v[140:143]
	v_mfma_f32_16x16x32_bf16 v[136:139], v[64:67], v[160:163], v[136:139]
	v_mfma_f32_16x16x32_bf16 v[128:131], v[56:59], v[168:171], v[128:131]
	v_mfma_f32_16x16x32_bf16 v[120:123], v[64:67], v[168:171], v[120:123]
	v_mfma_f32_16x16x32_bf16 v[108:111], v[56:59], v[194:197], v[108:111]
	v_mfma_f32_16x16x32_bf16 v[104:107], v[64:67], v[194:197], v[104:107]
	v_mfma_f32_16x16x32_bf16 v[92:95], v[56:59], v[202:205], v[92:95]
	v_mfma_f32_16x16x32_bf16 v[88:91], v[64:67], v[202:205], v[88:91]
	v_mfma_f32_16x16x32_bf16 v[140:143], v[60:63], v[164:167], v[140:143]
	v_mfma_f32_16x16x32_bf16 v[136:139], v[68:71], v[164:167], v[136:139]
	v_mfma_f32_16x16x32_bf16 v[128:131], v[60:63], v[172:175], v[128:131]
	v_mfma_f32_16x16x32_bf16 v[120:123], v[68:71], v[172:175], v[120:123]
	v_mfma_f32_16x16x32_bf16 v[108:111], v[60:63], v[198:201], v[108:111]
	v_mfma_f32_16x16x32_bf16 v[104:107], v[68:71], v[198:201], v[104:107]
	v_mfma_f32_16x16x32_bf16 v[92:95], v[60:63], v[206:209], v[92:95]
	v_mfma_f32_16x16x32_bf16 v[88:91], v[68:71], v[206:209], v[88:91]
	v_mfma_f32_16x16x32_bf16 v[132:135], v[144:147], v[160:163], v[132:135]
	v_mfma_f32_16x16x32_bf16 v[124:127], v[152:155], v[160:163], v[124:127]
	v_mfma_f32_16x16x32_bf16 v[116:119], v[144:147], v[168:171], v[116:119]
	v_mfma_f32_16x16x32_bf16 v[112:115], v[152:155], v[168:171], v[112:115]
	v_mfma_f32_16x16x32_bf16 v[100:103], v[144:147], v[194:197], v[100:103]
	v_mfma_f32_16x16x32_bf16 v[96:99], v[152:155], v[194:197], v[96:99]
	v_mfma_f32_16x16x32_bf16 v[84:87], v[144:147], v[202:205], v[84:87]
	v_mfma_f32_16x16x32_bf16 v[80:83], v[152:155], v[202:205], v[80:83]
	v_mfma_f32_16x16x32_bf16 v[132:135], v[148:151], v[164:167], v[132:135]
	v_mfma_f32_16x16x32_bf16 v[124:127], v[156:159], v[164:167], v[124:127]
	v_mfma_f32_16x16x32_bf16 v[116:119], v[148:151], v[172:175], v[116:119]
	v_mfma_f32_16x16x32_bf16 v[112:115], v[156:159], v[172:175], v[112:115]
	s_setprio 2
	s_barrier
	v_mfma_f32_16x16x32_bf16 v[100:103], v[148:151], v[198:201], v[100:103]
	v_mfma_f32_16x16x32_bf16 v[96:99], v[156:159], v[198:201], v[96:99]
	v_mfma_f32_16x16x32_bf16 v[84:87], v[148:151], v[206:209], v[84:87]
	v_mfma_f32_16x16x32_bf16 v[80:83], v[156:159], v[206:209], v[80:83]
	s_setprio 0
	s_add_i32 s50, s64, s68
	v_lshl_add_u64 v[178:179], v[178:179], 0, s[34:35]
	s_mov_b32 m0, s50
	ds_read_b128 v[160:163], v231 offset:49152
	ds_read_b128 v[164:167], v231 offset:50176
	ds_read_b128 v[168:171], v231 offset:51200
	ds_read_b128 v[172:175], v231 offset:52224
	ds_read_b128 v[194:197], v231 offset:53248
	ds_read_b128 v[198:201], v231 offset:54272
	ds_read_b128 v[202:205], v231 offset:55296
	ds_read_b128 v[206:209], v231 offset:56320
	global_load_lds_dwordx4 v[178:179], off
	s_add_i32 m0, s50, 0x2000
	s_add_u32 s42, s42, 0x40080
	v_lshl_add_u64 v[178:179], v[210:211], 0, s[34:35]
	s_addc_u32 s43, s43, 0
	s_add_i32 s50, s65, s68
	global_load_lds_dwordx4 v[178:179], off
	v_lshl_add_u64 v[178:179], s[42:43], 0, v[184:185]
	s_mov_b32 m0, s50
	s_nop 0
	global_load_lds_dwordx4 v[178:179], off
	v_lshl_add_u64 v[178:179], s[42:43], 0, v[188:189]
	s_add_i32 m0, s50, 0x2000
	s_nop 0
	global_load_lds_dwordx4 v[178:179], off
	v_lshl_add_u64 v[178:179], v[212:213], 0, s[34:35]
	s_mov_b32 m0, s75
	s_nop 0
	global_load_lds_dwordx4 v[178:179], off
	v_lshl_add_u64 v[178:179], v[220:221], 0, s[34:35]
	s_mov_b32 m0, s80
	s_nop 0
	global_load_lds_dwordx4 v[178:179], off
	s_waitcnt vmcnt(8)
	s_waitcnt lgkmcnt(0)
	s_barrier
	s_setprio 1
	v_mfma_f32_16x16x32_bf16 v[76:79], v[56:59], v[160:163], v[76:79]
	v_mfma_f32_16x16x32_bf16 v[72:75], v[64:67], v[160:163], v[72:75]
	v_mfma_f32_16x16x32_bf16 v[44:47], v[56:59], v[168:171], v[44:47]
	v_mfma_f32_16x16x32_bf16 v[40:43], v[64:67], v[168:171], v[40:43]
	v_mfma_f32_16x16x32_bf16 v[28:31], v[56:59], v[194:197], v[28:31]
	v_mfma_f32_16x16x32_bf16 v[24:27], v[64:67], v[194:197], v[24:27]
	v_mfma_f32_16x16x32_bf16 v[12:15], v[56:59], v[202:205], v[12:15]
	v_mfma_f32_16x16x32_bf16 v[8:11], v[64:67], v[202:205], v[8:11]
	v_mfma_f32_16x16x32_bf16 v[76:79], v[60:63], v[164:167], v[76:79]
	v_mfma_f32_16x16x32_bf16 v[72:75], v[68:71], v[164:167], v[72:75]
	v_mfma_f32_16x16x32_bf16 v[44:47], v[60:63], v[172:175], v[44:47]
	v_mfma_f32_16x16x32_bf16 v[40:43], v[68:71], v[172:175], v[40:43]
	v_mfma_f32_16x16x32_bf16 v[28:31], v[60:63], v[198:201], v[28:31]
	v_mfma_f32_16x16x32_bf16 v[24:27], v[68:71], v[198:201], v[24:27]
	v_mfma_f32_16x16x32_bf16 v[12:15], v[60:63], v[206:209], v[12:15]
	v_mfma_f32_16x16x32_bf16 v[8:11], v[68:71], v[206:209], v[8:11]
	v_mfma_f32_16x16x32_bf16 v[52:55], v[144:147], v[160:163], v[52:55]
	v_mfma_f32_16x16x32_bf16 v[48:51], v[152:155], v[160:163], v[48:51]
	v_mfma_f32_16x16x32_bf16 v[36:39], v[144:147], v[168:171], v[36:39]
	v_mfma_f32_16x16x32_bf16 v[32:35], v[152:155], v[168:171], v[32:35]
	v_mfma_f32_16x16x32_bf16 v[20:23], v[144:147], v[194:197], v[20:23]
	v_mfma_f32_16x16x32_bf16 v[16:19], v[152:155], v[194:197], v[16:19]
	v_mfma_f32_16x16x32_bf16 v[4:7], v[144:147], v[202:205], v[4:7]
	v_mfma_f32_16x16x32_bf16 v[0:3], v[152:155], v[202:205], v[0:3]
	v_mfma_f32_16x16x32_bf16 v[52:55], v[148:151], v[164:167], v[52:55]
	v_mfma_f32_16x16x32_bf16 v[48:51], v[156:159], v[164:167], v[48:51]
	v_mfma_f32_16x16x32_bf16 v[36:39], v[148:151], v[172:175], v[36:39]
	v_mfma_f32_16x16x32_bf16 v[32:35], v[156:159], v[172:175], v[32:35]
	s_setprio 2
	s_barrier
	v_mfma_f32_16x16x32_bf16 v[20:23], v[148:151], v[198:201], v[20:23]
	v_mfma_f32_16x16x32_bf16 v[16:19], v[156:159], v[198:201], v[16:19]
	v_mfma_f32_16x16x32_bf16 v[4:7], v[148:151], v[206:209], v[4:7]
	v_mfma_f32_16x16x32_bf16 v[0:3], v[156:159], v[206:209], v[0:3]
	s_setprio 0
	s_add_i32 s92, s92, 2
	s_add_u32 s52, s52, 0x100
	s_addc_u32 s53, s53, 0
	s_add_u32 s6, s6, 0x100
	s_addc_u32 s7, s7, 0
	s_cmp_gt_u32 s92, 13
	s_cbranch_scc0 .LBB0_1131
	s_and_b64 vcc, exec, s[20:21]
	s_cbranch_vccz .LBB0_1134
	s_barrier

.LBB0_1222:
	s_add_i32 vcc_hi, s42, 2
	s_add_u32 s43, s4, 0xfffc0080
	s_addc_u32 s50, s5, -1
	s_add_i32 s64, 0, 0x10000
	s_cmp_eq_u32 s63, s42
	s_cselect_b32 s51, s21, s50
	s_cselect_b32 s50, s23, s43
	s_cselect_b32 s43, s27, vcc_lo
	s_cselect_b32 s42, s53, s95
	s_add_i32 s66, 0, 0x14000
	v_add_u32_e32 v108, s64, v228
	v_add_u32_e32 v156, s66, v228
	ds_read_b128 v[88:91], v108
	ds_read_b128 v[92:95], v108 offset:1024
	ds_read_b128 v[104:107], v108 offset:2048
	ds_read_b128 v[108:111], v108 offset:3072
	ds_read_b128 v[144:147], v156
	ds_read_b128 v[148:151], v156 offset:1024
	ds_read_b128 v[152:155], v156 offset:2048
	ds_read_b128 v[156:159], v156 offset:3072
	v_lshl_add_u64 v[178:179], s[4:5], 0, v[192:193]
	s_add_i32 m0, s7, 0xc000
	ds_read_b128 v[160:163], v232
	ds_read_b128 v[164:167], v232 offset:1024
	ds_read_b128 v[168:171], v232 offset:2048
	ds_read_b128 v[172:175], v232 offset:3072
	ds_read_b128 v[194:197], v232 offset:4096
	ds_read_b128 v[198:201], v232 offset:5120
	ds_read_b128 v[202:205], v232 offset:6144
	ds_read_b128 v[206:209], v232 offset:7168
	global_load_lds_dwordx4 v[178:179], off
	v_lshl_add_u64 v[178:179], s[4:5], 0, v[190:191]
	s_add_i32 m0, s7, 0xe000
	s_nop 0
	global_load_lds_dwordx4 v[178:179], off
	s_waitcnt vmcnt(8)
	s_waitcnt lgkmcnt(0)
	s_barrier
	s_setprio 1
	v_mfma_f32_16x16x32_bf16 v[140:143], v[88:91], v[160:163], v[140:143]
	v_mfma_f32_16x16x32_bf16 v[136:139], v[104:107], v[160:163], v[136:139]
	v_mfma_f32_16x16x32_bf16 v[124:127], v[88:91], v[168:171], v[124:127]
	v_mfma_f32_16x16x32_bf16 v[120:123], v[104:107], v[168:171], v[120:123]
	v_mfma_f32_16x16x32_bf16 v[100:103], v[88:91], v[194:197], v[100:103]
	v_mfma_f32_16x16x32_bf16 v[96:99], v[104:107], v[194:197], v[96:99]
	v_mfma_f32_16x16x32_bf16 v[76:79], v[88:91], v[202:205], v[76:79]
	v_mfma_f32_16x16x32_bf16 v[72:75], v[104:107], v[202:205], v[72:75]
	v_mfma_f32_16x16x32_bf16 v[140:143], v[92:95], v[164:167], v[140:143]
	v_mfma_f32_16x16x32_bf16 v[136:139], v[108:111], v[164:167], v[136:139]
	v_mfma_f32_16x16x32_bf16 v[124:127], v[92:95], v[172:175], v[124:127]
	v_mfma_f32_16x16x32_bf16 v[120:123], v[108:111], v[172:175], v[120:123]
	v_mfma_f32_16x16x32_bf16 v[100:103], v[92:95], v[198:201], v[100:103]
	v_mfma_f32_16x16x32_bf16 v[96:99], v[108:111], v[198:201], v[96:99]
	v_mfma_f32_16x16x32_bf16 v[76:79], v[92:95], v[206:209], v[76:79]
	v_mfma_f32_16x16x32_bf16 v[72:75], v[108:111], v[206:209], v[72:75]
	v_mfma_f32_16x16x32_bf16 v[132:135], v[144:147], v[160:163], v[132:135]
	v_mfma_f32_16x16x32_bf16 v[128:131], v[152:155], v[160:163], v[128:131]
	v_mfma_f32_16x16x32_bf16 v[116:119], v[144:147], v[168:171], v[116:119]
	v_mfma_f32_16x16x32_bf16 v[112:115], v[152:155], v[168:171], v[112:115]
	v_mfma_f32_16x16x32_bf16 v[84:87], v[144:147], v[194:197], v[84:87]
	v_mfma_f32_16x16x32_bf16 v[80:83], v[152:155], v[194:197], v[80:83]
	v_mfma_f32_16x16x32_bf16 v[68:71], v[144:147], v[202:205], v[68:71]
	v_mfma_f32_16x16x32_bf16 v[64:67], v[152:155], v[202:205], v[64:67]
	v_mfma_f32_16x16x32_bf16 v[132:135], v[148:151], v[164:167], v[132:135]
	v_mfma_f32_16x16x32_bf16 v[128:131], v[156:159], v[164:167], v[128:131]
	v_mfma_f32_16x16x32_bf16 v[116:119], v[148:151], v[172:175], v[116:119]
	v_mfma_f32_16x16x32_bf16 v[112:115], v[156:159], v[172:175], v[112:115]
	s_setprio 2
	s_barrier
	v_mfma_f32_16x16x32_bf16 v[84:87], v[148:151], v[198:201], v[84:87]
	v_mfma_f32_16x16x32_bf16 v[80:83], v[156:159], v[198:201], v[80:83]
	v_mfma_f32_16x16x32_bf16 v[68:71], v[148:151], v[206:209], v[68:71]
	v_mfma_f32_16x16x32_bf16 v[64:67], v[156:159], v[206:209], v[64:67]
	s_setprio 0
	s_add_i32 s64, s64, s72
	v_lshl_add_u64 v[178:179], s[42:43], 0, v[184:185]
	s_mov_b32 m0, s64
	ds_read_b128 v[160:163], v232 offset:16384
	ds_read_b128 v[164:167], v232 offset:17408
	ds_read_b128 v[168:171], v232 offset:18432
	ds_read_b128 v[172:175], v232 offset:19456
	ds_read_b128 v[194:197], v232 offset:20480
	ds_read_b128 v[198:201], v232 offset:21504
	ds_read_b128 v[202:205], v232 offset:22528
	ds_read_b128 v[206:209], v232 offset:23552
	global_load_lds_dwordx4 v[178:179], off
	s_add_i32 m0, s64, 0x2000
	s_add_u32 s64, s42, 0x40000
	v_lshl_add_u64 v[210:211], s[42:43], 0, v[188:189]
	s_addc_u32 s65, s43, 0
	s_add_i32 s66, s66, s72
	global_load_lds_dwordx4 v[210:211], off
	v_lshl_add_u64 v[212:213], s[64:65], 0, v[184:185]
	s_mov_b32 m0, s66
	v_lshl_add_u64 v[220:221], s[50:51], 0, v[186:187]
	global_load_lds_dwordx4 v[212:213], off
	v_lshl_add_u64 v[212:213], s[64:65], 0, v[188:189]
	s_add_i32 m0, s66, 0x2000
	s_nop 0
	global_load_lds_dwordx4 v[212:213], off
	v_lshl_add_u64 v[212:213], s[50:51], 0, v[182:183]
	s_mov_b32 m0, s7
	s_nop 0
	global_load_lds_dwordx4 v[212:213], off
	s_mov_b32 m0, s73
	s_nop 0
	global_load_lds_dwordx4 v[220:221], off
	s_waitcnt vmcnt(8)
	s_waitcnt lgkmcnt(0)
	s_barrier
	s_setprio 1
	v_mfma_f32_16x16x32_bf16 v[60:63], v[88:91], v[160:163], v[60:63]
	v_mfma_f32_16x16x32_bf16 v[56:59], v[104:107], v[160:163], v[56:59]
	v_mfma_f32_16x16x32_bf16 v[44:47], v[88:91], v[168:171], v[44:47]
	v_mfma_f32_16x16x32_bf16 v[40:43], v[104:107], v[168:171], v[40:43]
	v_mfma_f32_16x16x32_bf16 v[28:31], v[88:91], v[194:197], v[28:31]
	v_mfma_f32_16x16x32_bf16 v[24:27], v[104:107], v[194:197], v[24:27]
	v_mfma_f32_16x16x32_bf16 v[12:15], v[88:91], v[202:205], v[12:15]
	v_mfma_f32_16x16x32_bf16 v[8:11], v[104:107], v[202:205], v[8:11]
	v_mfma_f32_16x16x32_bf16 v[60:63], v[92:95], v[164:167], v[60:63]
	v_mfma_f32_16x16x32_bf16 v[56:59], v[108:111], v[164:167], v[56:59]
	v_mfma_f32_16x16x32_bf16 v[44:47], v[92:95], v[172:175], v[44:47]
	v_mfma_f32_16x16x32_bf16 v[40:43], v[108:111], v[172:175], v[40:43]
	v_mfma_f32_16x16x32_bf16 v[28:31], v[92:95], v[198:201], v[28:31]
	v_mfma_f32_16x16x32_bf16 v[24:27], v[108:111], v[198:201], v[24:27]
	v_mfma_f32_16x16x32_bf16 v[12:15], v[92:95], v[206:209], v[12:15]
	v_mfma_f32_16x16x32_bf16 v[8:11], v[108:111], v[206:209], v[8:11]
	v_mfma_f32_16x16x32_bf16 v[52:55], v[144:147], v[160:163], v[52:55]
	v_mfma_f32_16x16x32_bf16 v[48:51], v[152:155], v[160:163], v[48:51]
	v_mfma_f32_16x16x32_bf16 v[36:39], v[144:147], v[168:171], v[36:39]
	v_mfma_f32_16x16x32_bf16 v[32:35], v[152:155], v[168:171], v[32:35]
	v_mfma_f32_16x16x32_bf16 v[20:23], v[144:147], v[194:197], v[20:23]
	v_mfma_f32_16x16x32_bf16 v[16:19], v[152:155], v[194:197], v[16:19]
	v_mfma_f32_16x16x32_bf16 v[4:7], v[144:147], v[202:205], v[4:7]
	v_mfma_f32_16x16x32_bf16 v[0:3], v[152:155], v[202:205], v[0:3]
	v_mfma_f32_16x16x32_bf16 v[52:55], v[148:151], v[164:167], v[52:55]
	v_mfma_f32_16x16x32_bf16 v[48:51], v[156:159], v[164:167], v[48:51]
	v_mfma_f32_16x16x32_bf16 v[36:39], v[148:151], v[172:175], v[36:39]
	v_mfma_f32_16x16x32_bf16 v[32:35], v[156:159], v[172:175], v[32:35]
	s_setprio 2
	s_barrier
	v_mfma_f32_16x16x32_bf16 v[20:23], v[148:151], v[198:201], v[20:23]
	v_mfma_f32_16x16x32_bf16 v[16:19], v[156:159], v[198:201], v[16:19]
	v_mfma_f32_16x16x32_bf16 v[4:7], v[148:151], v[206:209], v[4:7]
	v_mfma_f32_16x16x32_bf16 v[0:3], v[156:159], v[206:209], v[0:3]
	s_setprio 0
	s_add_i32 s64, 0, 0x18000
	s_add_i32 s65, 0, 0x1c000
	v_add_u32_e32 v108, s64, v228
	v_add_u32_e32 v156, s65, v228
	ds_read_b128 v[88:91], v108
	ds_read_b128 v[92:95], v108 offset:1024
	ds_read_b128 v[104:107], v108 offset:2048
	ds_read_b128 v[108:111], v108 offset:3072
	ds_read_b128 v[144:147], v156
	ds_read_b128 v[148:151], v156 offset:1024
	ds_read_b128 v[152:155], v156 offset:2048
	ds_read_b128 v[156:159], v156 offset:3072
	s_add_u32 s50, s50, 0x40000
	s_addc_u32 s51, s51, 0
	s_mov_b32 m0, s74
	v_lshl_add_u64 v[222:223], s[50:51], 0, v[182:183]
	ds_read_b128 v[160:163], v232 offset:32768
	ds_read_b128 v[164:167], v232 offset:33792
	ds_read_b128 v[168:171], v232 offset:34816
	ds_read_b128 v[172:175], v232 offset:35840
	ds_read_b128 v[194:197], v232 offset:36864
	ds_read_b128 v[198:201], v232 offset:37888
	ds_read_b128 v[202:205], v232 offset:38912
	ds_read_b128 v[206:209], v232 offset:39936
	global_load_lds_dwordx4 v[222:223], off
	v_lshl_add_u64 v[222:223], s[50:51], 0, v[186:187]
	s_mov_b32 m0, s75
	s_nop 0
	global_load_lds_dwordx4 v[222:223], off
	s_waitcnt vmcnt(8)
	s_waitcnt lgkmcnt(0)
	s_barrier
	s_setprio 1
	v_mfma_f32_16x16x32_bf16 v[140:143], v[88:91], v[160:163], v[140:143]
	v_mfma_f32_16x16x32_bf16 v[136:139], v[104:107], v[160:163], v[136:139]
	v_mfma_f32_16x16x32_bf16 v[124:127], v[88:91], v[168:171], v[124:127]
	v_mfma_f32_16x16x32_bf16 v[120:123], v[104:107], v[168:171], v[120:123]
	v_mfma_f32_16x16x32_bf16 v[100:103], v[88:91], v[194:197], v[100:103]
	v_mfma_f32_16x16x32_bf16 v[96:99], v[104:107], v[194:197], v[96:99]
	v_mfma_f32_16x16x32_bf16 v[76:79], v[88:91], v[202:205], v[76:79]
	v_mfma_f32_16x16x32_bf16 v[72:75], v[104:107], v[202:205], v[72:75]
	v_mfma_f32_16x16x32_bf16 v[140:143], v[92:95], v[164:167], v[140:143]
	v_mfma_f32_16x16x32_bf16 v[136:139], v[108:111], v[164:167], v[136:139]
	v_mfma_f32_16x16x32_bf16 v[124:127], v[92:95], v[172:175], v[124:127]
	v_mfma_f32_16x16x32_bf16 v[120:123], v[108:111], v[172:175], v[120:123]
	v_mfma_f32_16x16x32_bf16 v[100:103], v[92:95], v[198:201], v[100:103]
	v_mfma_f32_16x16x32_bf16 v[96:99], v[108:111], v[198:201], v[96:99]
	v_mfma_f32_16x16x32_bf16 v[76:79], v[92:95], v[206:209], v[76:79]
	v_mfma_f32_16x16x32_bf16 v[72:75], v[108:111], v[206:209], v[72:75]
	v_mfma_f32_16x16x32_bf16 v[132:135], v[144:147], v[160:163], v[132:135]
	v_mfma_f32_16x16x32_bf16 v[128:131], v[152:155], v[160:163], v[128:131]
	v_mfma_f32_16x16x32_bf16 v[116:119], v[144:147], v[168:171], v[116:119]
	v_mfma_f32_16x16x32_bf16 v[112:115], v[152:155], v[168:171], v[112:115]
	v_mfma_f32_16x16x32_bf16 v[84:87], v[144:147], v[194:197], v[84:87]
	v_mfma_f32_16x16x32_bf16 v[80:83], v[152:155], v[194:197], v[80:83]
	v_mfma_f32_16x16x32_bf16 v[68:71], v[144:147], v[202:205], v[68:71]
	v_mfma_f32_16x16x32_bf16 v[64:67], v[152:155], v[202:205], v[64:67]
	v_mfma_f32_16x16x32_bf16 v[132:135], v[148:151], v[164:167], v[132:135]
	v_mfma_f32_16x16x32_bf16 v[128:131], v[156:159], v[164:167], v[128:131]
	v_mfma_f32_16x16x32_bf16 v[116:119], v[148:151], v[172:175], v[116:119]
	v_mfma_f32_16x16x32_bf16 v[112:115], v[156:159], v[172:175], v[112:115]
	s_setprio 2
	s_barrier
	v_mfma_f32_16x16x32_bf16 v[84:87], v[148:151], v[198:201], v[84:87]
	v_mfma_f32_16x16x32_bf16 v[80:83], v[156:159], v[198:201], v[80:83]
	v_mfma_f32_16x16x32_bf16 v[68:71], v[148:151], v[206:209], v[68:71]
	v_mfma_f32_16x16x32_bf16 v[64:67], v[156:159], v[206:209], v[64:67]
	s_setprio 0
	s_add_i32 s50, s64, s72
	v_lshl_add_u64 v[178:179], v[178:179], 0, s[34:35]
	s_mov_b32 m0, s50
	ds_read_b128 v[160:163], v232 offset:49152
	ds_read_b128 v[164:167], v232 offset:50176
	ds_read_b128 v[168:171], v232 offset:51200
	ds_read_b128 v[172:175], v232 offset:52224
	ds_read_b128 v[194:197], v232 offset:53248
	ds_read_b128 v[198:201], v232 offset:54272
	ds_read_b128 v[202:205], v232 offset:55296
	ds_read_b128 v[206:209], v232 offset:56320
	global_load_lds_dwordx4 v[178:179], off
	s_add_i32 m0, s50, 0x2000
	s_add_u32 s42, s42, 0x40080
	v_lshl_add_u64 v[178:179], v[210:211], 0, s[34:35]
	s_addc_u32 s43, s43, 0
	s_add_i32 s50, s65, s72
	global_load_lds_dwordx4 v[178:179], off
	v_lshl_add_u64 v[178:179], s[42:43], 0, v[184:185]
	s_mov_b32 m0, s50
	s_nop 0
	global_load_lds_dwordx4 v[178:179], off
	v_lshl_add_u64 v[178:179], s[42:43], 0, v[188:189]
	s_add_i32 m0, s50, 0x2000
	s_nop 0
	global_load_lds_dwordx4 v[178:179], off
	v_lshl_add_u64 v[178:179], v[212:213], 0, s[34:35]
	s_mov_b32 m0, s81
	s_nop 0
	global_load_lds_dwordx4 v[178:179], off
	v_lshl_add_u64 v[178:179], v[220:221], 0, s[34:35]
	s_mov_b32 m0, s82
	s_nop 0
	global_load_lds_dwordx4 v[178:179], off
	s_waitcnt vmcnt(8)
	s_waitcnt lgkmcnt(0)
	s_barrier
	s_setprio 1
	v_mfma_f32_16x16x32_bf16 v[60:63], v[88:91], v[160:163], v[60:63]
	v_mfma_f32_16x16x32_bf16 v[56:59], v[104:107], v[160:163], v[56:59]
	v_mfma_f32_16x16x32_bf16 v[44:47], v[88:91], v[168:171], v[44:47]
	v_mfma_f32_16x16x32_bf16 v[40:43], v[104:107], v[168:171], v[40:43]
	v_mfma_f32_16x16x32_bf16 v[28:31], v[88:91], v[194:197], v[28:31]
	v_mfma_f32_16x16x32_bf16 v[24:27], v[104:107], v[194:197], v[24:27]
	v_mfma_f32_16x16x32_bf16 v[12:15], v[88:91], v[202:205], v[12:15]
	v_mfma_f32_16x16x32_bf16 v[8:11], v[104:107], v[202:205], v[8:11]
	v_mfma_f32_16x16x32_bf16 v[60:63], v[92:95], v[164:167], v[60:63]
	v_mfma_f32_16x16x32_bf16 v[56:59], v[108:111], v[164:167], v[56:59]
	v_mfma_f32_16x16x32_bf16 v[44:47], v[92:95], v[172:175], v[44:47]
	v_mfma_f32_16x16x32_bf16 v[40:43], v[108:111], v[172:175], v[40:43]
	v_mfma_f32_16x16x32_bf16 v[28:31], v[92:95], v[198:201], v[28:31]
	v_mfma_f32_16x16x32_bf16 v[24:27], v[108:111], v[198:201], v[24:27]
	v_mfma_f32_16x16x32_bf16 v[12:15], v[92:95], v[206:209], v[12:15]
	v_mfma_f32_16x16x32_bf16 v[8:11], v[108:111], v[206:209], v[8:11]
	v_mfma_f32_16x16x32_bf16 v[52:55], v[144:147], v[160:163], v[52:55]
	v_mfma_f32_16x16x32_bf16 v[48:51], v[152:155], v[160:163], v[48:51]
	v_mfma_f32_16x16x32_bf16 v[36:39], v[144:147], v[168:171], v[36:39]
	v_mfma_f32_16x16x32_bf16 v[32:35], v[152:155], v[168:171], v[32:35]
	v_mfma_f32_16x16x32_bf16 v[20:23], v[144:147], v[194:197], v[20:23]
	v_mfma_f32_16x16x32_bf16 v[16:19], v[152:155], v[194:197], v[16:19]
	v_mfma_f32_16x16x32_bf16 v[4:7], v[144:147], v[202:205], v[4:7]
	v_mfma_f32_16x16x32_bf16 v[0:3], v[152:155], v[202:205], v[0:3]
	v_mfma_f32_16x16x32_bf16 v[52:55], v[148:151], v[164:167], v[52:55]
	v_mfma_f32_16x16x32_bf16 v[48:51], v[156:159], v[164:167], v[48:51]
	v_mfma_f32_16x16x32_bf16 v[36:39], v[148:151], v[172:175], v[36:39]
	v_mfma_f32_16x16x32_bf16 v[32:35], v[156:159], v[172:175], v[32:35]
	s_setprio 2
	s_barrier
	v_mfma_f32_16x16x32_bf16 v[20:23], v[148:151], v[198:201], v[20:23]
	v_mfma_f32_16x16x32_bf16 v[16:19], v[156:159], v[198:201], v[16:19]
	v_mfma_f32_16x16x32_bf16 v[4:7], v[148:151], v[206:209], v[4:7]
	v_mfma_f32_16x16x32_bf16 v[0:3], v[156:159], v[206:209], v[0:3]
	s_setprio 0
	s_add_u32 s95, s95, 0x100
	s_addc_u32 vcc_lo, vcc_lo, 0
	s_add_u32 s4, s4, 0x100
	s_addc_u32 s5, s5, 0
	s_cmp_ge_i32 vcc_hi, s52
	s_mov_b32 s42, vcc_hi
	s_cbranch_scc0 .LBB0_1222
	s_and_b64 vcc, exec, s[16:17]
	s_cbranch_vccz .LBB0_1225
